# v11 + K-loop LDS-DMA loads in saddr form (SGPR base + 32-bit VGPR offset): 49 VALU 64-bit adds removed from the load segments
# speedup vs baseline: 1.0029x; 1.0029x over previous
; #define PG8_STAGE(bufoff, gbase, voff) do { _Pragma("unroll") for (int _i = 0; _i < 2; ++_i) \
;         __builtin_amdgcn_global_load_lds((const GAS unsigned*)((const GAS char*)(gbase) + (voff)[_i]), (LAS unsigned*)(lds + (bufoff) + ldsw + _i * 8192), 16, 0, 0); } while (0)
; #define PG8_LDA(dst, b, h) do { _Pragma("unroll") for (int m = 0; m < 4; ++m) _Pragma("unroll") for (int k = 0; k < 2; ++k) dst[m][k] = *(const LAS bf16x8*)(lds + PG8_SA(b, h) + aoff + m * 2048 + k * 1024); } while (0)
; #define PG8_LDB(dst, b, h) do { _Pragma("unroll") for (int n = 0; n < 2; ++n) _Pragma("unroll") for (int k = 0; k < 2; ++k) dst[n][k] = *(const LAS bf16x8*)(lds + PG8_SB(b, h) + boff + n * 2048 + k * 1024); } while (0)
; #define PG8_MMA(ai, bj, At, Bt) do { __builtin_amdgcn_s_setprio(1); _Pragma("unroll") for (int m = 0; m < 4; ++m) _Pragma("unroll") for (int n = 0; n < 2; ++n) _Pragma("unroll") for (int k = 0; k < 2; ++k) \
;         acc[ai][bj][m][n] = __builtin_amdgcn_mfma_f32_16x16x32_bf16(Bt[n][k], At[m][k], acc[ai][bj][m][n], 0, 0, 0); __builtin_amdgcn_s_setprio(0); } while (0)
; #define PG8_WAIT_V(n) asm volatile("s_waitcnt vmcnt(" #n ")" ::: "memory")
; #define PG8_WAIT_L(n) asm volatile("s_waitcnt lgkmcnt(" #n ")" ::: "memory")
; #define PG8_BAR __builtin_amdgcn_s_barrier()
; #define PG8_SCHED __builtin_amdgcn_sched_barrier(0)
; template <class Epi, class Sched, bool ALIGN_EPI>
; __device__ __forceinline__ void gemm_phase(LAS unsigned char* lds, const Gemm g, const Sched& S, const Epi& E, int wave_id) {
;     ...
;             PG8_LDB(B0, 0, 0); PG8_LDB(B1, 0, 1); PG8_SCHED; PG8_LDA(At, 0, 0); PG8_STAGE(PG8_SA(1, 1), a1 + hsA, voffA);
;             PG8_WAIT_V(8); PG8_WAIT_L(0); PG8_BAR; PG8_MMA(0, 0, At, B0); PG8_MMA(0, 1, At, B1); PG8_BAR; PG8_SCHED;
;             PG8_LDA(At, 0, 1); PG8_STAGE(PG8_SB(0, 0), b2, voffB); PG8_STAGE(PG8_SB(0, 1), b2 + hsB, voffB); PG8_STAGE(PG8_SA(0, 0), a2, voffA);
;             PG8_WAIT_V(8); PG8_WAIT_L(0); PG8_BAR; PG8_MMA(1, 0, At, B0); PG8_MMA(1, 1, At, B1); PG8_BAR; PG8_SCHED;
.LBB0_1117:
	s_add_u32 s58, s0, 0xfff80080
	s_addc_u32 s59, s1, -1
	s_cmp_eq_u32 s76, 28
	s_cselect_b32 s61, s33, s59
	s_cselect_b32 s60, s47, s58
	s_cselect_b32 s59, s49, s74
	s_cselect_b32 s58, s57, s71
	s_mov_b32 m0, s87
	s_nop 0
	global_load_lds_dwordx4 v204, s[0:1]
	s_mov_b32 m0, s88
	s_nop 0
	global_load_lds_dwordx4 v202, s[0:1]
	v_add_u32_e32 v0, 0x10400, v250
	ds_read_b128 v[130:133], v0
	ds_read_b128 v[134:137], v0 offset:1024
	ds_read_b128 v[138:141], v0 offset:2048
	ds_read_b128 v[142:145], v0 offset:3072
	v_add_u32_e32 v0, 0x14400, v250
	ds_read_b128 v[146:149], v0
	ds_read_b128 v[150:153], v0 offset:1024
	ds_read_b128 v[154:157], v0 offset:2048
	ds_read_b128 v[158:161], v0 offset:3072
	ds_read_b128 v[162:165], v253 offset:1024
	ds_read_b128 v[166:169], v253 offset:2048
	ds_read_b128 v[170:173], v253 offset:3072
	ds_read_b128 v[174:177], v253 offset:4096
	ds_read_b128 v[178:181], v253 offset:5120
	ds_read_b128 v[182:185], v253 offset:6144
	ds_read_b128 v[186:189], v253 offset:7168
	ds_read_b128 v[190:193], v253 offset:8192
	s_waitcnt vmcnt(8)
	s_waitcnt lgkmcnt(0)
	s_barrier
	s_setprio 1
	s_waitcnt lgkmcnt(0)
	v_mfma_f32_16x16x32_bf16 v[126:129], v[130:133], v[162:165], v[126:129]
	v_mfma_f32_16x16x32_bf16 v[122:125], v[138:141], v[162:165], v[122:125]
	v_mfma_f32_16x16x32_bf16 v[110:113], v[130:133], v[170:173], v[110:113]
	v_mfma_f32_16x16x32_bf16 v[106:109], v[138:141], v[170:173], v[106:109]
	v_mfma_f32_16x16x32_bf16 v[94:97], v[130:133], v[178:181], v[94:97]
	v_mfma_f32_16x16x32_bf16 v[90:93], v[138:141], v[178:181], v[90:93]
	v_mfma_f32_16x16x32_bf16 v[78:81], v[130:133], v[186:189], v[78:81]
	v_mfma_f32_16x16x32_bf16 v[74:77], v[138:141], v[186:189], v[74:77]
	v_mfma_f32_16x16x32_bf16 v[126:129], v[134:137], v[166:169], v[126:129]
	v_mfma_f32_16x16x32_bf16 v[122:125], v[142:145], v[166:169], v[122:125]
	v_mfma_f32_16x16x32_bf16 v[110:113], v[134:137], v[174:177], v[110:113]
	v_mfma_f32_16x16x32_bf16 v[106:109], v[142:145], v[174:177], v[106:109]
	v_mfma_f32_16x16x32_bf16 v[94:97], v[134:137], v[182:185], v[94:97]
	v_mfma_f32_16x16x32_bf16 v[90:93], v[142:145], v[182:185], v[90:93]
	v_mfma_f32_16x16x32_bf16 v[78:81], v[134:137], v[190:193], v[78:81]
	v_mfma_f32_16x16x32_bf16 v[74:77], v[142:145], v[190:193], v[74:77]
	s_setprio 0
	s_setprio 1
	v_mfma_f32_16x16x32_bf16 v[118:121], v[146:149], v[162:165], v[118:121]
	v_mfma_f32_16x16x32_bf16 v[114:117], v[154:157], v[162:165], v[114:117]
	v_mfma_f32_16x16x32_bf16 v[102:105], v[146:149], v[170:173], v[102:105]
	v_mfma_f32_16x16x32_bf16 v[98:101], v[154:157], v[170:173], v[98:101]
	v_mfma_f32_16x16x32_bf16 v[86:89], v[146:149], v[178:181], v[86:89]
	v_mfma_f32_16x16x32_bf16 v[82:85], v[154:157], v[178:181], v[82:85]
	v_mfma_f32_16x16x32_bf16 v[70:73], v[146:149], v[186:189], v[70:73]
	v_mfma_f32_16x16x32_bf16 v[66:69], v[154:157], v[186:189], v[66:69]
	v_mfma_f32_16x16x32_bf16 v[118:121], v[150:153], v[166:169], v[118:121]
	v_mfma_f32_16x16x32_bf16 v[114:117], v[158:161], v[166:169], v[114:117]
	v_mfma_f32_16x16x32_bf16 v[102:105], v[150:153], v[174:177], v[102:105]
	v_mfma_f32_16x16x32_bf16 v[98:101], v[158:161], v[174:177], v[98:101]
	v_mfma_f32_16x16x32_bf16 v[86:89], v[150:153], v[182:185], v[86:89]
	v_mfma_f32_16x16x32_bf16 v[82:85], v[158:161], v[182:185], v[82:85]
	v_mfma_f32_16x16x32_bf16 v[70:73], v[150:153], v[190:193], v[70:73]
	v_mfma_f32_16x16x32_bf16 v[66:69], v[158:161], v[190:193], v[66:69]
	s_setprio 0
	s_barrier
	s_mov_b32 m0, s15
	v_lshl_add_u64 v[206:207], s[58:59], 0, v[196:197]
	s_add_u32 vcc_lo, s58, 0x80000
	global_load_lds_dwordx4 v196, s[58:59]
	v_lshl_add_u64 v[208:209], s[58:59], 0, v[200:201]
	s_mov_b32 m0, s73
	s_addc_u32 vcc_hi, s59, 0
	global_load_lds_dwordx4 v200, s[58:59]
	s_mov_b32 m0, s75
	v_lshl_add_u64 v[212:213], s[60:61], 0, v[198:199]
	global_load_lds_dwordx4 v196, vcc
	s_mov_b32 m0, s80
	s_nop 0
	global_load_lds_dwordx4 v200, vcc
	v_lshl_add_u64 v[210:211], s[60:61], 0, v[194:195]
	s_mov_b32 m0, s81
	s_nop 0
	global_load_lds_dwordx4 v194, s[60:61]
	s_mov_b32 m0, s82
	s_nop 0
	global_load_lds_dwordx4 v198, s[60:61]
	ds_read_b128 v[162:165], v253 offset:17408
	ds_read_b128 v[166:169], v253 offset:18432
	ds_read_b128 v[170:173], v253 offset:19456
	ds_read_b128 v[174:177], v253 offset:20480
	ds_read_b128 v[178:181], v253 offset:21504
	ds_read_b128 v[182:185], v253 offset:22528
	ds_read_b128 v[186:189], v253 offset:23552
	ds_read_b128 v[190:193], v253 offset:24576
	s_waitcnt vmcnt(8)
	s_waitcnt lgkmcnt(0)
	s_barrier
	s_setprio 1
	s_waitcnt lgkmcnt(0)
	v_mfma_f32_16x16x32_bf16 v[62:65], v[130:133], v[162:165], v[62:65]
	v_mfma_f32_16x16x32_bf16 v[58:61], v[138:141], v[162:165], v[58:61]
	v_mfma_f32_16x16x32_bf16 v[46:49], v[130:133], v[170:173], v[46:49]
	v_mfma_f32_16x16x32_bf16 v[42:45], v[138:141], v[170:173], v[42:45]
	v_mfma_f32_16x16x32_bf16 v[30:33], v[130:133], v[178:181], v[30:33]
	v_mfma_f32_16x16x32_bf16 v[26:29], v[138:141], v[178:181], v[26:29]
	v_mfma_f32_16x16x32_bf16 v[14:17], v[130:133], v[186:189], v[14:17]
	v_mfma_f32_16x16x32_bf16 v[10:13], v[138:141], v[186:189], v[10:13]
	v_mfma_f32_16x16x32_bf16 v[62:65], v[134:137], v[166:169], v[62:65]
	v_mfma_f32_16x16x32_bf16 v[58:61], v[142:145], v[166:169], v[58:61]
	v_mfma_f32_16x16x32_bf16 v[46:49], v[134:137], v[174:177], v[46:49]
	v_mfma_f32_16x16x32_bf16 v[42:45], v[142:145], v[174:177], v[42:45]
	v_mfma_f32_16x16x32_bf16 v[30:33], v[134:137], v[182:185], v[30:33]
	v_mfma_f32_16x16x32_bf16 v[26:29], v[142:145], v[182:185], v[26:29]
	v_mfma_f32_16x16x32_bf16 v[14:17], v[134:137], v[190:193], v[14:17]
	v_mfma_f32_16x16x32_bf16 v[10:13], v[142:145], v[190:193], v[10:13]
	s_setprio 0
	s_setprio 1
	v_mfma_f32_16x16x32_bf16 v[54:57], v[146:149], v[162:165], v[54:57]
	v_mfma_f32_16x16x32_bf16 v[50:53], v[154:157], v[162:165], v[50:53]
	v_mfma_f32_16x16x32_bf16 v[38:41], v[146:149], v[170:173], v[38:41]
	v_mfma_f32_16x16x32_bf16 v[34:37], v[154:157], v[170:173], v[34:37]
	v_mfma_f32_16x16x32_bf16 v[22:25], v[146:149], v[178:181], v[22:25]
	v_mfma_f32_16x16x32_bf16 v[18:21], v[154:157], v[178:181], v[18:21]
	v_mfma_f32_16x16x32_bf16 v[6:9], v[146:149], v[186:189], v[6:9]
	v_mfma_f32_16x16x32_bf16 v[2:5], v[154:157], v[186:189], v[2:5]
	v_mfma_f32_16x16x32_bf16 v[54:57], v[150:153], v[166:169], v[54:57]
	v_mfma_f32_16x16x32_bf16 v[50:53], v[158:161], v[166:169], v[50:53]
	v_mfma_f32_16x16x32_bf16 v[38:41], v[150:153], v[174:177], v[38:41]
	v_mfma_f32_16x16x32_bf16 v[34:37], v[158:161], v[174:177], v[34:37]
	v_mfma_f32_16x16x32_bf16 v[22:25], v[150:153], v[182:185], v[22:25]
	v_mfma_f32_16x16x32_bf16 v[18:21], v[158:161], v[182:185], v[18:21]
	v_mfma_f32_16x16x32_bf16 v[6:9], v[150:153], v[190:193], v[6:9]
	v_mfma_f32_16x16x32_bf16 v[2:5], v[158:161], v[190:193], v[2:5]
	s_setprio 0
	s_barrier
; #define PG8_STAGE(bufoff, gbase, voff) do { _Pragma("unroll") for (int _i = 0; _i < 2; ++_i) \
;         __builtin_amdgcn_global_load_lds((const GAS unsigned*)((const GAS char*)(gbase) + (voff)[_i]), (LAS unsigned*)(lds + (bufoff) + ldsw + _i * 8192), 16, 0, 0); } while (0)
; #define PG8_LDA(dst, b, h) do { _Pragma("unroll") for (int m = 0; m < 4; ++m) _Pragma("unroll") for (int k = 0; k < 2; ++k) dst[m][k] = *(const LAS bf16x8*)(lds + PG8_SA(b, h) + aoff + m * 2048 + k * 1024); } while (0)
; #define PG8_LDB(dst, b, h) do { _Pragma("unroll") for (int n = 0; n < 2; ++n) _Pragma("unroll") for (int k = 0; k < 2; ++k) dst[n][k] = *(const LAS bf16x8*)(lds + PG8_SB(b, h) + boff + n * 2048 + k * 1024); } while (0)
; #define PG8_MMA(ai, bj, At, Bt) do { __builtin_amdgcn_s_setprio(1); _Pragma("unroll") for (int m = 0; m < 4; ++m) _Pragma("unroll") for (int n = 0; n < 2; ++n) _Pragma("unroll") for (int k = 0; k < 2; ++k) \
;         acc[ai][bj][m][n] = __builtin_amdgcn_mfma_f32_16x16x32_bf16(Bt[n][k], At[m][k], acc[ai][bj][m][n], 0, 0, 0); __builtin_amdgcn_s_setprio(0); } while (0)
; #define PG8_WAIT_V(n) asm volatile("s_waitcnt vmcnt(" #n ")" ::: "memory")
; #define PG8_WAIT_L(n) asm volatile("s_waitcnt lgkmcnt(" #n ")" ::: "memory")
; #define PG8_BAR __builtin_amdgcn_s_barrier()
; #define PG8_SCHED __builtin_amdgcn_sched_barrier(0)
; template <class Epi, class Sched, bool ALIGN_EPI>
; __device__ __forceinline__ void gemm_phase(LAS unsigned char* lds, const Gemm g, const Sched& S, const Epi& E, int wave_id) {
;     ...
;             PG8_LDB(B0, 1, 0); PG8_LDB(B1, 1, 1); PG8_SCHED; PG8_LDA(At, 1, 0); PG8_STAGE(PG8_SA(0, 1), a2 + hsA, voffA);
;             PG8_WAIT_V(8); PG8_WAIT_L(0); PG8_BAR; PG8_MMA(0, 0, At, B0); PG8_MMA(0, 1, At, B1); PG8_BAR; PG8_SCHED;
;             PG8_LDA(At, 1, 1); PG8_STAGE(PG8_SB(1, 0), b3, voffB); PG8_STAGE(PG8_SB(1, 1), b3 + hsB, voffB); PG8_STAGE(PG8_SA(1, 0), a3, voffA);
;             PG8_WAIT_V(8); PG8_WAIT_L(0); PG8_BAR; PG8_MMA(1, 0, At, B0); PG8_MMA(1, 1, At, B1); PG8_BAR; PG8_SCHED;
	s_add_u32 s60, s60, 0x80000
	s_addc_u32 s61, s61, 0
	s_mov_b32 m0, s83
	s_nop 0
	global_load_lds_dwordx4 v194, s[60:61]
	s_mov_b32 m0, s84
	s_nop 0
	global_load_lds_dwordx4 v198, s[60:61]
	v_add_u32_e32 v0, 0x18400, v250
	ds_read_b128 v[130:133], v0
	ds_read_b128 v[134:137], v0 offset:1024
	ds_read_b128 v[138:141], v0 offset:2048
	ds_read_b128 v[142:145], v0 offset:3072
	v_add_u32_e32 v0, 0x1c400, v250
	ds_read_b128 v[146:149], v0
	ds_read_b128 v[150:153], v0 offset:1024
	ds_read_b128 v[154:157], v0 offset:2048
	ds_read_b128 v[158:161], v0 offset:3072
	ds_read_b128 v[162:165], v253 offset:33792
	ds_read_b128 v[166:169], v253 offset:34816
	ds_read_b128 v[170:173], v253 offset:35840
	ds_read_b128 v[174:177], v253 offset:36864
	ds_read_b128 v[178:181], v253 offset:37888
	ds_read_b128 v[182:185], v253 offset:38912
	ds_read_b128 v[186:189], v253 offset:39936
	ds_read_b128 v[190:193], v253 offset:40960
	s_waitcnt vmcnt(8)
	s_waitcnt lgkmcnt(0)
	s_barrier
	s_setprio 1
	s_waitcnt lgkmcnt(0)
	v_mfma_f32_16x16x32_bf16 v[126:129], v[130:133], v[162:165], v[126:129]
	v_mfma_f32_16x16x32_bf16 v[122:125], v[138:141], v[162:165], v[122:125]
	v_mfma_f32_16x16x32_bf16 v[110:113], v[130:133], v[170:173], v[110:113]
	v_mfma_f32_16x16x32_bf16 v[106:109], v[138:141], v[170:173], v[106:109]
	v_mfma_f32_16x16x32_bf16 v[94:97], v[130:133], v[178:181], v[94:97]
	v_mfma_f32_16x16x32_bf16 v[90:93], v[138:141], v[178:181], v[90:93]
	v_mfma_f32_16x16x32_bf16 v[78:81], v[130:133], v[186:189], v[78:81]
	v_mfma_f32_16x16x32_bf16 v[74:77], v[138:141], v[186:189], v[74:77]
	v_mfma_f32_16x16x32_bf16 v[126:129], v[134:137], v[166:169], v[126:129]
	v_mfma_f32_16x16x32_bf16 v[122:125], v[142:145], v[166:169], v[122:125]
	v_mfma_f32_16x16x32_bf16 v[110:113], v[134:137], v[174:177], v[110:113]
	v_mfma_f32_16x16x32_bf16 v[106:109], v[142:145], v[174:177], v[106:109]
	v_mfma_f32_16x16x32_bf16 v[94:97], v[134:137], v[182:185], v[94:97]
	v_mfma_f32_16x16x32_bf16 v[90:93], v[142:145], v[182:185], v[90:93]
	v_mfma_f32_16x16x32_bf16 v[78:81], v[134:137], v[190:193], v[78:81]
	v_mfma_f32_16x16x32_bf16 v[74:77], v[142:145], v[190:193], v[74:77]
	s_setprio 0
	s_setprio 1
	v_mfma_f32_16x16x32_bf16 v[118:121], v[146:149], v[162:165], v[118:121]
	v_mfma_f32_16x16x32_bf16 v[114:117], v[154:157], v[162:165], v[114:117]
	v_mfma_f32_16x16x32_bf16 v[102:105], v[146:149], v[170:173], v[102:105]
	v_mfma_f32_16x16x32_bf16 v[98:101], v[154:157], v[170:173], v[98:101]
	v_mfma_f32_16x16x32_bf16 v[86:89], v[146:149], v[178:181], v[86:89]
	v_mfma_f32_16x16x32_bf16 v[82:85], v[154:157], v[178:181], v[82:85]
	v_mfma_f32_16x16x32_bf16 v[70:73], v[146:149], v[186:189], v[70:73]
	v_mfma_f32_16x16x32_bf16 v[66:69], v[154:157], v[186:189], v[66:69]
	v_mfma_f32_16x16x32_bf16 v[118:121], v[150:153], v[166:169], v[118:121]
	v_mfma_f32_16x16x32_bf16 v[114:117], v[158:161], v[166:169], v[114:117]
	v_mfma_f32_16x16x32_bf16 v[102:105], v[150:153], v[174:177], v[102:105]
	v_mfma_f32_16x16x32_bf16 v[98:101], v[158:161], v[174:177], v[98:101]
	v_mfma_f32_16x16x32_bf16 v[86:89], v[150:153], v[182:185], v[86:89]
	v_mfma_f32_16x16x32_bf16 v[82:85], v[158:161], v[182:185], v[82:85]
	v_mfma_f32_16x16x32_bf16 v[70:73], v[150:153], v[190:193], v[70:73]
	v_mfma_f32_16x16x32_bf16 v[66:69], v[158:161], v[190:193], v[66:69]
	s_setprio 0
	s_barrier
	s_mov_b32 m0, s95
	v_lshl_add_u64 v[206:207], v[206:207], 0, s[92:93]
	s_add_u32 s58, s58, 0x80080
	global_load_lds_dwordx4 v[206:207], off
	v_lshl_add_u64 v[206:207], v[208:209], 0, s[92:93]
	s_mov_b32 m0, s96
	s_addc_u32 s59, s59, 0
	global_load_lds_dwordx4 v[206:207], off
	s_mov_b32 m0, s17
	s_nop 0
	global_load_lds_dwordx4 v196, s[58:59]
	s_mov_b32 m0, s18
	s_nop 0
	global_load_lds_dwordx4 v200, s[58:59]
	v_lshl_add_u64 v[206:207], v[210:211], 0, s[92:93]
	s_mov_b32 m0, s97
	s_nop 0
	global_load_lds_dwordx4 v[206:207], off
	v_lshl_add_u64 v[206:207], v[212:213], 0, s[92:93]
	s_mov_b32 m0, s16
	s_nop 0
	global_load_lds_dwordx4 v[206:207], off
	ds_read_b128 v[162:165], v253 offset:50176
	ds_read_b128 v[166:169], v253 offset:51200
	ds_read_b128 v[170:173], v253 offset:52224
	ds_read_b128 v[174:177], v253 offset:53248
	ds_read_b128 v[178:181], v253 offset:54272
	ds_read_b128 v[182:185], v253 offset:55296
	ds_read_b128 v[186:189], v253 offset:56320
	ds_read_b128 v[190:193], v253 offset:57344
	s_waitcnt vmcnt(8)
	s_waitcnt lgkmcnt(0)
	s_barrier
	s_setprio 1
	s_waitcnt lgkmcnt(0)
	v_mfma_f32_16x16x32_bf16 v[62:65], v[130:133], v[162:165], v[62:65]
	v_mfma_f32_16x16x32_bf16 v[58:61], v[138:141], v[162:165], v[58:61]
	v_mfma_f32_16x16x32_bf16 v[46:49], v[130:133], v[170:173], v[46:49]
	v_mfma_f32_16x16x32_bf16 v[42:45], v[138:141], v[170:173], v[42:45]
	v_mfma_f32_16x16x32_bf16 v[30:33], v[130:133], v[178:181], v[30:33]
	v_mfma_f32_16x16x32_bf16 v[26:29], v[138:141], v[178:181], v[26:29]
	v_mfma_f32_16x16x32_bf16 v[14:17], v[130:133], v[186:189], v[14:17]
	v_mfma_f32_16x16x32_bf16 v[10:13], v[138:141], v[186:189], v[10:13]
	v_mfma_f32_16x16x32_bf16 v[62:65], v[134:137], v[166:169], v[62:65]
	v_mfma_f32_16x16x32_bf16 v[58:61], v[142:145], v[166:169], v[58:61]
	v_mfma_f32_16x16x32_bf16 v[46:49], v[134:137], v[174:177], v[46:49]
	v_mfma_f32_16x16x32_bf16 v[42:45], v[142:145], v[174:177], v[42:45]
	v_mfma_f32_16x16x32_bf16 v[30:33], v[134:137], v[182:185], v[30:33]
	v_mfma_f32_16x16x32_bf16 v[26:29], v[142:145], v[182:185], v[26:29]
	v_mfma_f32_16x16x32_bf16 v[14:17], v[134:137], v[190:193], v[14:17]
	v_mfma_f32_16x16x32_bf16 v[10:13], v[142:145], v[190:193], v[10:13]
	s_setprio 0
	s_setprio 1
	v_mfma_f32_16x16x32_bf16 v[54:57], v[146:149], v[162:165], v[54:57]
	v_mfma_f32_16x16x32_bf16 v[50:53], v[154:157], v[162:165], v[50:53]
	v_mfma_f32_16x16x32_bf16 v[38:41], v[146:149], v[170:173], v[38:41]
	v_mfma_f32_16x16x32_bf16 v[34:37], v[154:157], v[170:173], v[34:37]
	v_mfma_f32_16x16x32_bf16 v[22:25], v[146:149], v[178:181], v[22:25]
	v_mfma_f32_16x16x32_bf16 v[18:21], v[154:157], v[178:181], v[18:21]
	v_mfma_f32_16x16x32_bf16 v[6:9], v[146:149], v[186:189], v[6:9]
	v_mfma_f32_16x16x32_bf16 v[2:5], v[154:157], v[186:189], v[2:5]
	v_mfma_f32_16x16x32_bf16 v[54:57], v[150:153], v[166:169], v[54:57]
	v_mfma_f32_16x16x32_bf16 v[50:53], v[158:161], v[166:169], v[50:53]
	v_mfma_f32_16x16x32_bf16 v[38:41], v[150:153], v[174:177], v[38:41]
	v_mfma_f32_16x16x32_bf16 v[34:37], v[158:161], v[174:177], v[34:37]
	v_mfma_f32_16x16x32_bf16 v[22:25], v[150:153], v[182:185], v[22:25]
	v_mfma_f32_16x16x32_bf16 v[18:21], v[158:161], v[182:185], v[18:21]
	v_mfma_f32_16x16x32_bf16 v[6:9], v[150:153], v[190:193], v[6:9]
	v_mfma_f32_16x16x32_bf16 v[2:5], v[158:161], v[190:193], v[2:5]
	s_setprio 0
	s_barrier
	s_add_i32 s76, s76, 2
	s_add_u32 s71, s71, 0x100
	s_addc_u32 s74, s74, 0
	s_add_u32 s0, s0, 0x100
	s_addc_u32 s1, s1, 0
	s_cmp_gt_u32 s76, 29
	s_cbranch_scc0 .LBB0_1117
	s_and_b64 vcc, exec, s[44:45]
	s_cbranch_vccz .LBB0_1120
	s_barrier

; #define PG8_STAGE(bufoff, gbase, voff) do { _Pragma("unroll") for (int _i = 0; _i < 2; ++_i) \
;         __builtin_amdgcn_global_load_lds((const GAS unsigned*)((const GAS char*)(gbase) + (voff)[_i]), (LAS unsigned*)(lds + (bufoff) + ldsw + _i * 8192), 16, 0, 0); } while (0)
; #define PG8_LDA(dst, b, h) do { _Pragma("unroll") for (int m = 0; m < 4; ++m) _Pragma("unroll") for (int k = 0; k < 2; ++k) dst[m][k] = *(const LAS bf16x8*)(lds + PG8_SA(b, h) + aoff + m * 2048 + k * 1024); } while (0)
; #define PG8_LDB(dst, b, h) do { _Pragma("unroll") for (int n = 0; n < 2; ++n) _Pragma("unroll") for (int k = 0; k < 2; ++k) dst[n][k] = *(const LAS bf16x8*)(lds + PG8_SB(b, h) + boff + n * 2048 + k * 1024); } while (0)
; #define PG8_MMA(ai, bj, At, Bt) do { __builtin_amdgcn_s_setprio(1); _Pragma("unroll") for (int m = 0; m < 4; ++m) _Pragma("unroll") for (int n = 0; n < 2; ++n) _Pragma("unroll") for (int k = 0; k < 2; ++k) \
;         acc[ai][bj][m][n] = __builtin_amdgcn_mfma_f32_16x16x32_bf16(Bt[n][k], At[m][k], acc[ai][bj][m][n], 0, 0, 0); __builtin_amdgcn_s_setprio(0); } while (0)
; #define PG8_WAIT_V(n) asm volatile("s_waitcnt vmcnt(" #n ")" ::: "memory")
; #define PG8_WAIT_L(n) asm volatile("s_waitcnt lgkmcnt(" #n ")" ::: "memory")
; #define PG8_BAR __builtin_amdgcn_s_barrier()
; #define PG8_SCHED __builtin_amdgcn_sched_barrier(0)
; template <class Epi, class Sched, bool ALIGN_EPI>
; __device__ __forceinline__ void gemm_phase(LAS unsigned char* lds, const Gemm g, const Sched& S, const Epi& E, int wave_id) {
;     ...
;             PG8_LDB(B0, 0, 0); PG8_LDB(B1, 0, 1); PG8_SCHED; PG8_LDA(At, 0, 0); PG8_STAGE(PG8_SA(1, 1), a1 + hsA, voffA);
;             PG8_WAIT_V(8); PG8_WAIT_L(0); PG8_BAR; PG8_MMA(0, 0, At, B0); PG8_MMA(0, 1, At, B1); PG8_BAR; PG8_SCHED;
;             PG8_LDA(At, 0, 1); PG8_STAGE(PG8_SB(0, 0), b2, voffB); PG8_STAGE(PG8_SB(0, 1), b2 + hsB, voffB); PG8_STAGE(PG8_SA(0, 0), a2, voffA);
;             PG8_WAIT_V(8); PG8_WAIT_L(0); PG8_BAR; PG8_MMA(1, 0, At, B0); PG8_MMA(1, 1, At, B1); PG8_BAR; PG8_SCHED;
.LBB0_1335:
	s_add_u32 s34, s12, s26
	s_addc_u32 s35, s13, s27
	s_add_u32 s30, s34, 0x100
	s_addc_u32 s31, s35, 0
	s_and_b64 s[28:29], s[24:25], exec
	s_cselect_b32 s29, s17, s31
	s_cselect_b32 s28, s16, s30
	s_add_u32 s26, s10, s26
	s_addc_u32 s27, s11, s27
	s_add_u32 s26, s26, 0x100
	s_addc_u32 s27, s27, 0
	s_and_b64 s[24:25], s[24:25], exec
	s_cselect_b32 s31, s60, s27
	s_cselect_b32 s30, s61, s26
	s_add_u32 s36, s34, 0x18080
	s_addc_u32 s37, s35, 0
	s_add_i32 m0, s40, 0xc400
	s_add_i32 s62, s40, 0xe400
	s_add_u32 s34, s30, 0x10000
	s_addc_u32 s35, s31, 0
	s_add_u32 s26, s28, 0x18000
	s_addc_u32 s27, s29, 0
	s_add_u32 s24, s30, 0x10080
	s_addc_u32 s25, s31, 0
	global_load_lds_dwordx4 v70, s[36:37]
	s_mov_b32 m0, s62
	s_nop 0
	global_load_lds_dwordx4 v68, s[36:37]
	v_add_u32_e32 v86, 0x10400, v73
	ds_read_b128 v[74:77], v86
	ds_read_b128 v[78:81], v86 offset:1024
	ds_read_b128 v[82:85], v86 offset:2048
	ds_read_b128 v[86:89], v86 offset:3072
	ds_read_b128 v[90:93], v72 offset:1024
	ds_read_b128 v[94:97], v72 offset:2048
	ds_read_b128 v[98:101], v72 offset:3072
	ds_read_b128 v[102:105], v72 offset:4096
	ds_read_b128 v[106:109], v72 offset:5120
	ds_read_b128 v[110:113], v72 offset:6144
	ds_read_b128 v[114:117], v72 offset:7168
	ds_read_b128 v[118:121], v72 offset:8192
	s_waitcnt vmcnt(8)
	s_waitcnt lgkmcnt(0)
	s_barrier
	s_setprio 1
	s_waitcnt lgkmcnt(0)
	v_mfma_f32_16x16x32_bf16 v[62:65], v[74:77], v[90:93], v[62:65]
	v_mfma_f32_16x16x32_bf16 v[58:61], v[82:85], v[90:93], v[58:61]
	v_mfma_f32_16x16x32_bf16 v[54:57], v[74:77], v[98:101], v[54:57]
	v_mfma_f32_16x16x32_bf16 v[50:53], v[82:85], v[98:101], v[50:53]
	v_mfma_f32_16x16x32_bf16 v[46:49], v[74:77], v[106:109], v[46:49]
	v_mfma_f32_16x16x32_bf16 v[42:45], v[82:85], v[106:109], v[42:45]
	v_mfma_f32_16x16x32_bf16 v[38:41], v[74:77], v[114:117], v[38:41]
	v_mfma_f32_16x16x32_bf16 v[34:37], v[82:85], v[114:117], v[34:37]
	v_mfma_f32_16x16x32_bf16 v[62:65], v[78:81], v[94:97], v[62:65]
	v_mfma_f32_16x16x32_bf16 v[58:61], v[86:89], v[94:97], v[58:61]
	v_mfma_f32_16x16x32_bf16 v[54:57], v[78:81], v[102:105], v[54:57]
	v_mfma_f32_16x16x32_bf16 v[50:53], v[86:89], v[102:105], v[50:53]
	v_mfma_f32_16x16x32_bf16 v[46:49], v[78:81], v[110:113], v[46:49]
	v_mfma_f32_16x16x32_bf16 v[42:45], v[86:89], v[110:113], v[42:45]
	v_mfma_f32_16x16x32_bf16 v[38:41], v[78:81], v[118:121], v[38:41]
	v_mfma_f32_16x16x32_bf16 v[34:37], v[86:89], v[118:121], v[34:37]
	s_setprio 0
	s_setprio 1
	s_setprio 0
	s_barrier
	s_mov_b32 m0, s41
	v_lshl_add_u64 v[122:123], s[30:31], 0, v[0:1]
	global_load_lds_dwordx4 v[122:123], off
	v_lshl_add_u64 v[124:125], s[30:31], 0, v[66:67]
	s_mov_b32 m0, s42
	v_lshl_add_u64 v[126:127], s[34:35], 0, v[0:1]
	global_load_lds_dwordx4 v66, s[30:31]
	s_mov_b32 m0, s43
	v_lshl_add_u64 v[128:129], s[28:29], 0, v[68:69]
	global_load_lds_dwordx4 v[126:127], off
	s_mov_b32 m0, s44
	s_nop 0
	global_load_lds_dwordx4 v66, s[34:35]
	v_lshl_add_u64 v[126:127], s[28:29], 0, v[70:71]
	s_mov_b32 m0, s45
	s_nop 0
	global_load_lds_dwordx4 v70, s[28:29]
	s_mov_b32 m0, s46
	s_nop 0
	global_load_lds_dwordx4 v68, s[28:29]
	ds_read_b128 v[90:93], v72 offset:17408
	ds_read_b128 v[94:97], v72 offset:18432
	ds_read_b128 v[98:101], v72 offset:19456
	ds_read_b128 v[102:105], v72 offset:20480
	ds_read_b128 v[106:109], v72 offset:21504
	ds_read_b128 v[110:113], v72 offset:22528
	ds_read_b128 v[114:117], v72 offset:23552
	ds_read_b128 v[118:121], v72 offset:24576
	s_waitcnt vmcnt(8)
	s_waitcnt lgkmcnt(0)
	s_barrier
	s_setprio 1
	s_waitcnt lgkmcnt(0)
	v_mfma_f32_16x16x32_bf16 v[30:33], v[74:77], v[90:93], v[30:33]
	v_mfma_f32_16x16x32_bf16 v[26:29], v[82:85], v[90:93], v[26:29]
	v_mfma_f32_16x16x32_bf16 v[22:25], v[74:77], v[98:101], v[22:25]
	v_mfma_f32_16x16x32_bf16 v[18:21], v[82:85], v[98:101], v[18:21]
	v_mfma_f32_16x16x32_bf16 v[14:17], v[74:77], v[106:109], v[14:17]
	v_mfma_f32_16x16x32_bf16 v[10:13], v[82:85], v[106:109], v[10:13]
	v_mfma_f32_16x16x32_bf16 v[6:9], v[74:77], v[114:117], v[6:9]
	v_mfma_f32_16x16x32_bf16 v[2:5], v[82:85], v[114:117], v[2:5]
	v_mfma_f32_16x16x32_bf16 v[30:33], v[78:81], v[94:97], v[30:33]
	v_mfma_f32_16x16x32_bf16 v[26:29], v[86:89], v[94:97], v[26:29]
	v_mfma_f32_16x16x32_bf16 v[22:25], v[78:81], v[102:105], v[22:25]
	v_mfma_f32_16x16x32_bf16 v[18:21], v[86:89], v[102:105], v[18:21]
	v_mfma_f32_16x16x32_bf16 v[14:17], v[78:81], v[110:113], v[14:17]
	v_mfma_f32_16x16x32_bf16 v[10:13], v[86:89], v[110:113], v[10:13]
	v_mfma_f32_16x16x32_bf16 v[6:9], v[78:81], v[118:121], v[6:9]
	v_mfma_f32_16x16x32_bf16 v[2:5], v[86:89], v[118:121], v[2:5]
	s_setprio 0
	s_setprio 1
	s_setprio 0
	s_barrier
; #define PG8_STAGE(bufoff, gbase, voff) do { _Pragma("unroll") for (int _i = 0; _i < 2; ++_i) \
;         __builtin_amdgcn_global_load_lds((const GAS unsigned*)((const GAS char*)(gbase) + (voff)[_i]), (LAS unsigned*)(lds + (bufoff) + ldsw + _i * 8192), 16, 0, 0); } while (0)
; #define PG8_LDA(dst, b, h) do { _Pragma("unroll") for (int m = 0; m < 4; ++m) _Pragma("unroll") for (int k = 0; k < 2; ++k) dst[m][k] = *(const LAS bf16x8*)(lds + PG8_SA(b, h) + aoff + m * 2048 + k * 1024); } while (0)
; #define PG8_LDB(dst, b, h) do { _Pragma("unroll") for (int n = 0; n < 2; ++n) _Pragma("unroll") for (int k = 0; k < 2; ++k) dst[n][k] = *(const LAS bf16x8*)(lds + PG8_SB(b, h) + boff + n * 2048 + k * 1024); } while (0)
; #define PG8_MMA(ai, bj, At, Bt) do { __builtin_amdgcn_s_setprio(1); _Pragma("unroll") for (int m = 0; m < 4; ++m) _Pragma("unroll") for (int n = 0; n < 2; ++n) _Pragma("unroll") for (int k = 0; k < 2; ++k) \
;         acc[ai][bj][m][n] = __builtin_amdgcn_mfma_f32_16x16x32_bf16(Bt[n][k], At[m][k], acc[ai][bj][m][n], 0, 0, 0); __builtin_amdgcn_s_setprio(0); } while (0)
; #define PG8_WAIT_V(n) asm volatile("s_waitcnt vmcnt(" #n ")" ::: "memory")
; #define PG8_WAIT_L(n) asm volatile("s_waitcnt lgkmcnt(" #n ")" ::: "memory")
; #define PG8_BAR __builtin_amdgcn_s_barrier()
; #define PG8_SCHED __builtin_amdgcn_sched_barrier(0)
; template <class Epi, class Sched, bool ALIGN_EPI>
; __device__ __forceinline__ void gemm_phase(LAS unsigned char* lds, const Gemm g, const Sched& S, const Epi& E, int wave_id) {
;     ...
;             PG8_LDB(B0, 1, 0); PG8_LDB(B1, 1, 1); PG8_SCHED; PG8_LDA(At, 1, 0); PG8_STAGE(PG8_SA(0, 1), a2 + hsA, voffA);
;             PG8_WAIT_V(8); PG8_WAIT_L(0); PG8_BAR; PG8_MMA(0, 0, At, B0); PG8_MMA(0, 1, At, B1); PG8_BAR; PG8_SCHED;
;             PG8_LDA(At, 1, 1); PG8_STAGE(PG8_SB(1, 0), b3, voffB); PG8_STAGE(PG8_SB(1, 1), b3 + hsB, voffB); PG8_STAGE(PG8_SA(1, 0), a3, voffA);
;             PG8_WAIT_V(8); PG8_WAIT_L(0); PG8_BAR; PG8_MMA(1, 0, At, B0); PG8_MMA(1, 1, At, B1); PG8_BAR; PG8_SCHED;
;         }
	s_mov_b32 m0, s47
	s_nop 0
	global_load_lds_dwordx4 v70, s[26:27]
	s_mov_b32 m0, s48
	s_nop 0
	global_load_lds_dwordx4 v68, s[26:27]
	v_add_u32_e32 v86, 0x18400, v73
	ds_read_b128 v[74:77], v86
	ds_read_b128 v[78:81], v86 offset:1024
	ds_read_b128 v[82:85], v86 offset:2048
	ds_read_b128 v[86:89], v86 offset:3072
	ds_read_b128 v[90:93], v72 offset:33792
	ds_read_b128 v[94:97], v72 offset:34816
	ds_read_b128 v[98:101], v72 offset:35840
	ds_read_b128 v[102:105], v72 offset:36864
	ds_read_b128 v[106:109], v72 offset:37888
	ds_read_b128 v[110:113], v72 offset:38912
	ds_read_b128 v[114:117], v72 offset:39936
	ds_read_b128 v[118:121], v72 offset:40960
	s_waitcnt vmcnt(8)
	s_waitcnt lgkmcnt(0)
	s_barrier
	s_setprio 1
	s_waitcnt lgkmcnt(0)
	v_mfma_f32_16x16x32_bf16 v[62:65], v[74:77], v[90:93], v[62:65]
	v_mfma_f32_16x16x32_bf16 v[58:61], v[82:85], v[90:93], v[58:61]
	v_mfma_f32_16x16x32_bf16 v[54:57], v[74:77], v[98:101], v[54:57]
	v_mfma_f32_16x16x32_bf16 v[50:53], v[82:85], v[98:101], v[50:53]
	v_mfma_f32_16x16x32_bf16 v[46:49], v[74:77], v[106:109], v[46:49]
	v_mfma_f32_16x16x32_bf16 v[42:45], v[82:85], v[106:109], v[42:45]
	v_mfma_f32_16x16x32_bf16 v[38:41], v[74:77], v[114:117], v[38:41]
	v_mfma_f32_16x16x32_bf16 v[34:37], v[82:85], v[114:117], v[34:37]
	v_mfma_f32_16x16x32_bf16 v[62:65], v[78:81], v[94:97], v[62:65]
	v_mfma_f32_16x16x32_bf16 v[58:61], v[86:89], v[94:97], v[58:61]
	v_mfma_f32_16x16x32_bf16 v[54:57], v[78:81], v[102:105], v[54:57]
	v_mfma_f32_16x16x32_bf16 v[50:53], v[86:89], v[102:105], v[50:53]
	v_mfma_f32_16x16x32_bf16 v[46:49], v[78:81], v[110:113], v[46:49]
	v_mfma_f32_16x16x32_bf16 v[42:45], v[86:89], v[110:113], v[42:45]
	v_mfma_f32_16x16x32_bf16 v[38:41], v[78:81], v[118:121], v[38:41]
	v_mfma_f32_16x16x32_bf16 v[34:37], v[86:89], v[118:121], v[34:37]
	s_setprio 0
	s_setprio 1
	s_setprio 0
	s_barrier
	s_mov_b32 m0, s51
	v_lshl_add_u64 v[122:123], v[122:123], 0, s[92:93]
	global_load_lds_dwordx4 v[122:123], off
	v_lshl_add_u64 v[122:123], v[124:125], 0, s[92:93]
	s_mov_b32 m0, s52
	s_nop 0
	global_load_lds_dwordx4 v[122:123], off
	v_lshl_add_u64 v[122:123], s[24:25], 0, v[0:1]
	s_mov_b32 m0, s55
	s_nop 0
	global_load_lds_dwordx4 v[122:123], off
	s_mov_b32 m0, s56
	s_nop 0
	global_load_lds_dwordx4 v66, s[24:25]
	v_lshl_add_u64 v[122:123], v[126:127], 0, s[92:93]
	s_mov_b32 m0, s53
	s_nop 0
	global_load_lds_dwordx4 v[122:123], off
	v_lshl_add_u64 v[122:123], v[128:129], 0, s[92:93]
	s_mov_b32 m0, s54
	s_nop 0
	global_load_lds_dwordx4 v[122:123], off
	ds_read_b128 v[90:93], v72 offset:50176
	ds_read_b128 v[94:97], v72 offset:51200
	ds_read_b128 v[98:101], v72 offset:52224
	ds_read_b128 v[102:105], v72 offset:53248
	ds_read_b128 v[106:109], v72 offset:54272
	ds_read_b128 v[110:113], v72 offset:55296
	ds_read_b128 v[114:117], v72 offset:56320
	ds_read_b128 v[118:121], v72 offset:57344
	s_waitcnt vmcnt(8)
	s_waitcnt lgkmcnt(0)
	s_barrier
	s_setprio 1
	s_waitcnt lgkmcnt(0)
	v_mfma_f32_16x16x32_bf16 v[30:33], v[74:77], v[90:93], v[30:33]
	v_mfma_f32_16x16x32_bf16 v[26:29], v[82:85], v[90:93], v[26:29]
	v_mfma_f32_16x16x32_bf16 v[22:25], v[74:77], v[98:101], v[22:25]
	v_mfma_f32_16x16x32_bf16 v[18:21], v[82:85], v[98:101], v[18:21]
	v_mfma_f32_16x16x32_bf16 v[14:17], v[74:77], v[106:109], v[14:17]
	v_mfma_f32_16x16x32_bf16 v[10:13], v[82:85], v[106:109], v[10:13]
	v_mfma_f32_16x16x32_bf16 v[6:9], v[74:77], v[114:117], v[6:9]
	v_mfma_f32_16x16x32_bf16 v[2:5], v[82:85], v[114:117], v[2:5]
	v_mfma_f32_16x16x32_bf16 v[30:33], v[78:81], v[94:97], v[30:33]
	v_mfma_f32_16x16x32_bf16 v[26:29], v[86:89], v[94:97], v[26:29]
	v_mfma_f32_16x16x32_bf16 v[22:25], v[78:81], v[102:105], v[22:25]
	v_mfma_f32_16x16x32_bf16 v[18:21], v[86:89], v[102:105], v[18:21]
	v_mfma_f32_16x16x32_bf16 v[14:17], v[78:81], v[110:113], v[14:17]
	v_mfma_f32_16x16x32_bf16 v[10:13], v[86:89], v[110:113], v[10:13]
	v_mfma_f32_16x16x32_bf16 v[6:9], v[78:81], v[118:121], v[6:9]
	v_mfma_f32_16x16x32_bf16 v[2:5], v[86:89], v[118:121], v[2:5]
	s_setprio 0
	s_setprio 1
	s_setprio 0
	s_barrier
	s_andn2_b64 vcc, exec, s[22:23]
	s_mov_b64 s[24:25], -1
	s_mov_b64 s[22:23], 0
	s_mov_b64 s[26:27], 0x100
	s_cbranch_vccz .LBB0_1335
	s_and_b64 vcc, exec, s[14:15]
	s_cbranch_vccz .LBB0_1338
	s_barrier

; #define GAS __attribute__((address_space(1)))
; #define PG8_STAGE(bufoff, gbase, voff) do { _Pragma("unroll") for (int _i = 0; _i < 2; ++_i) \
;         __builtin_amdgcn_global_load_lds((const GAS unsigned*)((const GAS char*)(gbase) + (voff)[_i]), (LAS unsigned*)(lds + (bufoff) + ldsw + _i * 8192), 16, 0, 0); } while (0)
; #define PG8_LDA(dst, b, h) do { _Pragma("unroll") for (int m = 0; m < 4; ++m) _Pragma("unroll") for (int k = 0; k < 2; ++k) dst[m][k] = *(const LAS bf16x8*)(lds + PG8_SA(b, h) + aoff + m * 2048 + k * 1024); } while (0)
; #define PG8_LDB(dst, b, h) do { _Pragma("unroll") for (int n = 0; n < 2; ++n) _Pragma("unroll") for (int k = 0; k < 2; ++k) dst[n][k] = *(const LAS bf16x8*)(lds + PG8_SB(b, h) + boff + n * 2048 + k * 1024); } while (0)
; #define PG8_MMA(ai, bj, At, Bt) do { __builtin_amdgcn_s_setprio(1); _Pragma("unroll") for (int m = 0; m < 4; ++m) _Pragma("unroll") for (int n = 0; n < 2; ++n) _Pragma("unroll") for (int k = 0; k < 2; ++k) \
;         acc[ai][bj][m][n] = __builtin_amdgcn_mfma_f32_16x16x32_bf16(Bt[n][k], At[m][k], acc[ai][bj][m][n], 0, 0, 0); __builtin_amdgcn_s_setprio(0); } while (0)
; #define PG8_WAIT_V(n) asm volatile("s_waitcnt vmcnt(" #n ")" ::: "memory")
; #define PG8_WAIT_L(n) asm volatile("s_waitcnt lgkmcnt(" #n ")" ::: "memory")
; template <class Epi, class Sched, bool ALIGN_EPI>
; __device__ __forceinline__ void gemm_phase(LAS unsigned char* lds, const Gemm g, const Sched& S, const Epi& E, int wave_id) {
;     ...
;         for (int t = 0; t < nt; t += 2) {
;             const bool last = (t == nt - 2);
;             const GAS char* a1 = cA + (size_t)(t + 1) * kstep;
;             const GAS char* a2 = last ? nA : cA + (size_t)(t + 2) * kstep; const GAS char* b2 = last ? nB : cB + (size_t)(t + 2) * kstep;
;             const GAS char* a3 = a2 + kstep; const GAS char* b3 = b2 + kstep;
;             PG8_LDB(B0, 0, 0); PG8_LDB(B1, 0, 1); PG8_SCHED; PG8_LDA(At, 0, 0); PG8_STAGE(PG8_SA(1, 1), a1 + hsA, voffA);
;             PG8_WAIT_V(8); PG8_WAIT_L(0); PG8_BAR; PG8_MMA(0, 0, At, B0); PG8_MMA(0, 1, At, B1); PG8_BAR; PG8_SCHED;
;             PG8_LDA(At, 0, 1); PG8_STAGE(PG8_SB(0, 0), b2, voffB); PG8_STAGE(PG8_SB(0, 1), b2 + hsB, voffB); PG8_STAGE(PG8_SA(0, 0), a2, voffA);
;             PG8_WAIT_V(8); PG8_WAIT_L(0); PG8_BAR; PG8_MMA(1, 0, At, B0); PG8_MMA(1, 1, At, B1); PG8_BAR; PG8_SCHED;
.LBB0_1458:
	s_add_u32 s21, s26, s34
	s_addc_u32 s33, s27, s35
	s_add_u32 s38, s21, 0x100
	s_addc_u32 s39, s33, 0
	s_and_b64 s[36:37], s[30:31], exec
	s_cselect_b32 s37, s3, s39
	s_cselect_b32 s36, s5, s38
	s_add_u32 s34, s6, s34
	s_addc_u32 s35, s7, s35
	s_add_u32 s34, s34, 0x100
	s_addc_u32 s35, s35, 0
	s_and_b64 s[30:31], s[30:31], exec
	s_cselect_b32 s39, s9, s35
	s_cselect_b32 s38, s19, s34
	s_add_u32 s42, s21, 0x10080
	s_addc_u32 s43, s33, 0
	s_add_i32 m0, s49, 0xc400
	s_add_i32 s21, s49, 0xe400
	s_add_u32 s40, s38, 0x10000
	s_addc_u32 s41, s39, 0
	s_add_u32 s34, s36, 0x10000
	s_addc_u32 s35, s37, 0
	s_add_u32 s30, s38, 0x10080
	s_addc_u32 s31, s39, 0
	global_load_lds_dwordx4 v140, s[42:43]
	s_mov_b32 m0, s21
	s_nop 0
	global_load_lds_dwordx4 v144, s[42:43]
	v_add_u32_e32 v0, 0x10400, v159
	ds_read_b128 v[100:103], v0
	ds_read_b128 v[108:111], v0 offset:1024
	ds_read_b128 v[148:151], v0 offset:2048
	ds_read_b128 v[152:155], v0 offset:3072
	v_add_u32_e32 v0, 0x14400, v159
	ds_read_b128 v[160:163], v0
	ds_read_b128 v[164:167], v0 offset:1024
	ds_read_b128 v[168:171], v0 offset:2048
	ds_read_b128 v[172:175], v0 offset:3072
	ds_read_b128 v[176:179], v158 offset:1024
	ds_read_b128 v[180:183], v158 offset:2048
	ds_read_b128 v[184:187], v158 offset:3072
	ds_read_b128 v[188:191], v158 offset:4096
	ds_read_b128 v[192:195], v158 offset:5120
	ds_read_b128 v[196:199], v158 offset:6144
	ds_read_b128 v[200:203], v158 offset:7168
	ds_read_b128 v[204:207], v158 offset:8192
	s_waitcnt vmcnt(8)
	s_waitcnt lgkmcnt(0)
	s_barrier
	s_setprio 1
	s_waitcnt lgkmcnt(0)
	v_mfma_f32_16x16x32_bf16 v[136:139], v[100:103], v[176:179], v[136:139]
	v_mfma_f32_16x16x32_bf16 v[132:135], v[148:151], v[176:179], v[132:135]
	v_mfma_f32_16x16x32_bf16 v[128:131], v[100:103], v[184:187], v[128:131]
	v_mfma_f32_16x16x32_bf16 v[124:127], v[148:151], v[184:187], v[124:127]
	v_mfma_f32_16x16x32_bf16 v[120:123], v[100:103], v[192:195], v[120:123]
	v_mfma_f32_16x16x32_bf16 v[116:119], v[148:151], v[192:195], v[116:119]
	v_mfma_f32_16x16x32_bf16 v[112:115], v[100:103], v[200:203], v[112:115]
	v_mfma_f32_16x16x32_bf16 v[104:107], v[148:151], v[200:203], v[104:107]
	v_mfma_f32_16x16x32_bf16 v[136:139], v[108:111], v[180:183], v[136:139]
	v_mfma_f32_16x16x32_bf16 v[132:135], v[152:155], v[180:183], v[132:135]
	v_mfma_f32_16x16x32_bf16 v[128:131], v[108:111], v[188:191], v[128:131]
	v_mfma_f32_16x16x32_bf16 v[124:127], v[152:155], v[188:191], v[124:127]
	v_mfma_f32_16x16x32_bf16 v[120:123], v[108:111], v[196:199], v[120:123]
	v_mfma_f32_16x16x32_bf16 v[116:119], v[152:155], v[196:199], v[116:119]
	v_mfma_f32_16x16x32_bf16 v[112:115], v[108:111], v[204:207], v[112:115]
	v_mfma_f32_16x16x32_bf16 v[104:107], v[152:155], v[204:207], v[104:107]
	s_setprio 0
	s_setprio 1
	v_mfma_f32_16x16x32_bf16 v[64:67], v[160:163], v[176:179], v[64:67]
	v_mfma_f32_16x16x32_bf16 v[60:63], v[168:171], v[176:179], v[60:63]
	v_mfma_f32_16x16x32_bf16 v[56:59], v[160:163], v[184:187], v[56:59]
	v_mfma_f32_16x16x32_bf16 v[52:55], v[168:171], v[184:187], v[52:55]
	v_mfma_f32_16x16x32_bf16 v[48:51], v[160:163], v[192:195], v[48:51]
	v_mfma_f32_16x16x32_bf16 v[44:47], v[168:171], v[192:195], v[44:47]
	v_mfma_f32_16x16x32_bf16 v[40:43], v[160:163], v[200:203], v[40:43]
	v_mfma_f32_16x16x32_bf16 v[36:39], v[168:171], v[200:203], v[36:39]
	v_mfma_f32_16x16x32_bf16 v[64:67], v[164:167], v[180:183], v[64:67]
	v_mfma_f32_16x16x32_bf16 v[60:63], v[172:175], v[180:183], v[60:63]
	v_mfma_f32_16x16x32_bf16 v[56:59], v[164:167], v[188:191], v[56:59]
	v_mfma_f32_16x16x32_bf16 v[52:55], v[172:175], v[188:191], v[52:55]
	v_mfma_f32_16x16x32_bf16 v[48:51], v[164:167], v[196:199], v[48:51]
	v_mfma_f32_16x16x32_bf16 v[44:47], v[172:175], v[196:199], v[44:47]
	v_mfma_f32_16x16x32_bf16 v[40:43], v[164:167], v[204:207], v[40:43]
	v_mfma_f32_16x16x32_bf16 v[36:39], v[172:175], v[204:207], v[36:39]
	s_setprio 0
	s_barrier
	s_mov_b32 m0, s50
	v_lshl_add_u64 v[156:157], s[38:39], 0, v[142:143]
	global_load_lds_dwordx4 v142, s[38:39]
	v_lshl_add_u64 v[208:209], s[38:39], 0, v[146:147]
	s_mov_b32 m0, s51
	s_nop 0
	global_load_lds_dwordx4 v146, s[38:39]
	s_mov_b32 m0, s52
	v_lshl_add_u64 v[210:211], s[36:37], 0, v[140:141]
	global_load_lds_dwordx4 v142, s[40:41]
	v_lshl_add_u64 v[2:3], s[40:41], 0, v[146:147]
	s_mov_b32 m0, s53
	v_lshl_add_u64 v[212:213], s[36:37], 0, v[144:145]
	global_load_lds_dwordx4 v146, s[40:41]
	s_mov_b32 m0, s54
	s_nop 0
	global_load_lds_dwordx4 v140, s[36:37]
	s_mov_b32 m0, s55
	s_nop 0
	global_load_lds_dwordx4 v144, s[36:37]
	ds_read_b128 v[176:179], v158 offset:17408
	ds_read_b128 v[180:183], v158 offset:18432
	ds_read_b128 v[184:187], v158 offset:19456
	ds_read_b128 v[188:191], v158 offset:20480
	ds_read_b128 v[192:195], v158 offset:21504
	ds_read_b128 v[196:199], v158 offset:22528
	ds_read_b128 v[200:203], v158 offset:23552
	ds_read_b128 v[204:207], v158 offset:24576
	s_waitcnt vmcnt(8)
	s_waitcnt lgkmcnt(0)
	s_barrier
; #define PG8_STAGE(bufoff, gbase, voff) do { _Pragma("unroll") for (int _i = 0; _i < 2; ++_i) \
;         __builtin_amdgcn_global_load_lds((const GAS unsigned*)((const GAS char*)(gbase) + (voff)[_i]), (LAS unsigned*)(lds + (bufoff) + ldsw + _i * 8192), 16, 0, 0); } while (0)
; #define PG8_LDA(dst, b, h) do { _Pragma("unroll") for (int m = 0; m < 4; ++m) _Pragma("unroll") for (int k = 0; k < 2; ++k) dst[m][k] = *(const LAS bf16x8*)(lds + PG8_SA(b, h) + aoff + m * 2048 + k * 1024); } while (0)
; #define PG8_LDB(dst, b, h) do { _Pragma("unroll") for (int n = 0; n < 2; ++n) _Pragma("unroll") for (int k = 0; k < 2; ++k) dst[n][k] = *(const LAS bf16x8*)(lds + PG8_SB(b, h) + boff + n * 2048 + k * 1024); } while (0)
; #define PG8_MMA(ai, bj, At, Bt) do { __builtin_amdgcn_s_setprio(1); _Pragma("unroll") for (int m = 0; m < 4; ++m) _Pragma("unroll") for (int n = 0; n < 2; ++n) _Pragma("unroll") for (int k = 0; k < 2; ++k) \
;         acc[ai][bj][m][n] = __builtin_amdgcn_mfma_f32_16x16x32_bf16(Bt[n][k], At[m][k], acc[ai][bj][m][n], 0, 0, 0); __builtin_amdgcn_s_setprio(0); } while (0)
; #define PG8_WAIT_V(n) asm volatile("s_waitcnt vmcnt(" #n ")" ::: "memory")
; #define PG8_WAIT_L(n) asm volatile("s_waitcnt lgkmcnt(" #n ")" ::: "memory")
; #define PG8_BAR __builtin_amdgcn_s_barrier()
; #define PG8_SCHED __builtin_amdgcn_sched_barrier(0)
; template <class Epi, class Sched, bool ALIGN_EPI>
; __device__ __forceinline__ void gemm_phase(LAS unsigned char* lds, const Gemm g, const Sched& S, const Epi& E, int wave_id) {
;     ...
;             PG8_WAIT_V(8); PG8_WAIT_L(0); PG8_BAR; PG8_MMA(1, 0, At, B0); PG8_MMA(1, 1, At, B1); PG8_BAR; PG8_SCHED;
;             PG8_LDB(B0, 1, 0); PG8_LDB(B1, 1, 1); PG8_SCHED; PG8_LDA(At, 1, 0); PG8_STAGE(PG8_SA(0, 1), a2 + hsA, voffA);
;             PG8_WAIT_V(8); PG8_WAIT_L(0); PG8_BAR; PG8_MMA(0, 0, At, B0); PG8_MMA(0, 1, At, B1); PG8_BAR; PG8_SCHED;
	s_setprio 1
	s_waitcnt lgkmcnt(0)
	v_mfma_f32_16x16x32_bf16 v[96:99], v[100:103], v[176:179], v[96:99]
	v_mfma_f32_16x16x32_bf16 v[92:95], v[148:151], v[176:179], v[92:95]
	v_mfma_f32_16x16x32_bf16 v[88:91], v[100:103], v[184:187], v[88:91]
	v_mfma_f32_16x16x32_bf16 v[84:87], v[148:151], v[184:187], v[84:87]
	v_mfma_f32_16x16x32_bf16 v[80:83], v[100:103], v[192:195], v[80:83]
	v_mfma_f32_16x16x32_bf16 v[76:79], v[148:151], v[192:195], v[76:79]
	v_mfma_f32_16x16x32_bf16 v[72:75], v[100:103], v[200:203], v[72:75]
	v_mfma_f32_16x16x32_bf16 v[68:71], v[148:151], v[200:203], v[68:71]
	v_mfma_f32_16x16x32_bf16 v[96:99], v[108:111], v[180:183], v[96:99]
	v_mfma_f32_16x16x32_bf16 v[92:95], v[152:155], v[180:183], v[92:95]
	v_mfma_f32_16x16x32_bf16 v[88:91], v[108:111], v[188:191], v[88:91]
	v_mfma_f32_16x16x32_bf16 v[84:87], v[152:155], v[188:191], v[84:87]
	v_mfma_f32_16x16x32_bf16 v[80:83], v[108:111], v[196:199], v[80:83]
	v_mfma_f32_16x16x32_bf16 v[76:79], v[152:155], v[196:199], v[76:79]
	v_mfma_f32_16x16x32_bf16 v[72:75], v[108:111], v[204:207], v[72:75]
	v_mfma_f32_16x16x32_bf16 v[68:71], v[152:155], v[204:207], v[68:71]
	s_setprio 0
	s_setprio 1
	v_mfma_f32_16x16x32_bf16 v[32:35], v[160:163], v[176:179], v[32:35]
	v_mfma_f32_16x16x32_bf16 v[28:31], v[168:171], v[176:179], v[28:31]
	v_mfma_f32_16x16x32_bf16 v[24:27], v[160:163], v[184:187], v[24:27]
	v_mfma_f32_16x16x32_bf16 v[20:23], v[168:171], v[184:187], v[20:23]
	v_mfma_f32_16x16x32_bf16 v[16:19], v[160:163], v[192:195], v[16:19]
	v_mfma_f32_16x16x32_bf16 v[12:15], v[168:171], v[192:195], v[12:15]
	v_mfma_f32_16x16x32_bf16 v[8:11], v[160:163], v[200:203], v[8:11]
	v_mfma_f32_16x16x32_bf16 v[2:5], v[168:171], v[200:203], v[4:7]
	v_mfma_f32_16x16x32_bf16 v[32:35], v[164:167], v[180:183], v[32:35]
	v_mfma_f32_16x16x32_bf16 v[28:31], v[172:175], v[180:183], v[28:31]
	v_mfma_f32_16x16x32_bf16 v[24:27], v[164:167], v[188:191], v[24:27]
	v_mfma_f32_16x16x32_bf16 v[20:23], v[172:175], v[188:191], v[20:23]
	v_mfma_f32_16x16x32_bf16 v[16:19], v[164:167], v[196:199], v[16:19]
	v_mfma_f32_16x16x32_bf16 v[12:15], v[172:175], v[196:199], v[12:15]
	v_mfma_f32_16x16x32_bf16 v[8:11], v[164:167], v[204:207], v[8:11]
	v_mfma_f32_16x16x32_bf16 v[2:5], v[172:175], v[204:207], v[2:5]
	s_setprio 0
	s_barrier
	s_mov_b32 m0, s56
	s_nop 0
	global_load_lds_dwordx4 v140, s[34:35]
	s_mov_b32 m0, s57
	s_nop 0
	global_load_lds_dwordx4 v144, s[34:35]
	v_add_u32_e32 v0, 0x18400, v159
	ds_read_b128 v[100:103], v0
	ds_read_b128 v[108:111], v0 offset:1024
	ds_read_b128 v[148:151], v0 offset:2048
	ds_read_b128 v[152:155], v0 offset:3072
	v_add_u32_e32 v0, 0x1c400, v159
	ds_read_b128 v[160:163], v0
	ds_read_b128 v[164:167], v0 offset:1024
	ds_read_b128 v[168:171], v0 offset:2048
	ds_read_b128 v[172:175], v0 offset:3072
	ds_read_b128 v[176:179], v158 offset:33792
	ds_read_b128 v[180:183], v158 offset:34816
	ds_read_b128 v[184:187], v158 offset:35840
	ds_read_b128 v[188:191], v158 offset:36864
	ds_read_b128 v[192:195], v158 offset:37888
	ds_read_b128 v[196:199], v158 offset:38912
	ds_read_b128 v[200:203], v158 offset:39936
	ds_read_b128 v[204:207], v158 offset:40960
	s_waitcnt vmcnt(8)
	s_waitcnt lgkmcnt(0)
	s_barrier
	s_setprio 1
	s_waitcnt lgkmcnt(0)
	v_mfma_f32_16x16x32_bf16 v[136:139], v[100:103], v[176:179], v[136:139]
	v_mfma_f32_16x16x32_bf16 v[132:135], v[148:151], v[176:179], v[132:135]
	v_mfma_f32_16x16x32_bf16 v[128:131], v[100:103], v[184:187], v[128:131]
	v_mfma_f32_16x16x32_bf16 v[124:127], v[148:151], v[184:187], v[124:127]
	v_mfma_f32_16x16x32_bf16 v[120:123], v[100:103], v[192:195], v[120:123]
	v_mfma_f32_16x16x32_bf16 v[116:119], v[148:151], v[192:195], v[116:119]
	v_mfma_f32_16x16x32_bf16 v[112:115], v[100:103], v[200:203], v[112:115]
	v_mfma_f32_16x16x32_bf16 v[104:107], v[148:151], v[200:203], v[104:107]
	v_mfma_f32_16x16x32_bf16 v[136:139], v[108:111], v[180:183], v[136:139]
	v_mfma_f32_16x16x32_bf16 v[132:135], v[152:155], v[180:183], v[132:135]
	v_mfma_f32_16x16x32_bf16 v[128:131], v[108:111], v[188:191], v[128:131]
	v_mfma_f32_16x16x32_bf16 v[124:127], v[152:155], v[188:191], v[124:127]
	v_mfma_f32_16x16x32_bf16 v[120:123], v[108:111], v[196:199], v[120:123]
	v_mfma_f32_16x16x32_bf16 v[116:119], v[152:155], v[196:199], v[116:119]
	v_mfma_f32_16x16x32_bf16 v[112:115], v[108:111], v[204:207], v[112:115]
	v_mfma_f32_16x16x32_bf16 v[104:107], v[152:155], v[204:207], v[104:107]
	s_setprio 0
	s_setprio 1
	v_mfma_f32_16x16x32_bf16 v[64:67], v[160:163], v[176:179], v[64:67]
	v_mfma_f32_16x16x32_bf16 v[60:63], v[168:171], v[176:179], v[60:63]
	v_mfma_f32_16x16x32_bf16 v[56:59], v[160:163], v[184:187], v[56:59]
	v_mfma_f32_16x16x32_bf16 v[52:55], v[168:171], v[184:187], v[52:55]
	v_mfma_f32_16x16x32_bf16 v[48:51], v[160:163], v[192:195], v[48:51]
	v_mfma_f32_16x16x32_bf16 v[44:47], v[168:171], v[192:195], v[44:47]
	v_mfma_f32_16x16x32_bf16 v[40:43], v[160:163], v[200:203], v[40:43]
	v_mfma_f32_16x16x32_bf16 v[36:39], v[168:171], v[200:203], v[36:39]
	v_mfma_f32_16x16x32_bf16 v[64:67], v[164:167], v[180:183], v[64:67]
	v_mfma_f32_16x16x32_bf16 v[60:63], v[172:175], v[180:183], v[60:63]
	v_mfma_f32_16x16x32_bf16 v[56:59], v[164:167], v[188:191], v[56:59]
	v_mfma_f32_16x16x32_bf16 v[52:55], v[172:175], v[188:191], v[52:55]
	v_mfma_f32_16x16x32_bf16 v[48:51], v[164:167], v[196:199], v[48:51]
	v_mfma_f32_16x16x32_bf16 v[44:47], v[172:175], v[196:199], v[44:47]
	v_mfma_f32_16x16x32_bf16 v[40:43], v[164:167], v[204:207], v[40:43]
	v_mfma_f32_16x16x32_bf16 v[36:39], v[172:175], v[204:207], v[36:39]
	s_setprio 0
	s_barrier
; #define PG8_STAGE(bufoff, gbase, voff) do { _Pragma("unroll") for (int _i = 0; _i < 2; ++_i) \
;         __builtin_amdgcn_global_load_lds((const GAS unsigned*)((const GAS char*)(gbase) + (voff)[_i]), (LAS unsigned*)(lds + (bufoff) + ldsw + _i * 8192), 16, 0, 0); } while (0)
; #define PG8_LDA(dst, b, h) do { _Pragma("unroll") for (int m = 0; m < 4; ++m) _Pragma("unroll") for (int k = 0; k < 2; ++k) dst[m][k] = *(const LAS bf16x8*)(lds + PG8_SA(b, h) + aoff + m * 2048 + k * 1024); } while (0)
; #define PG8_MMA(ai, bj, At, Bt) do { __builtin_amdgcn_s_setprio(1); _Pragma("unroll") for (int m = 0; m < 4; ++m) _Pragma("unroll") for (int n = 0; n < 2; ++n) _Pragma("unroll") for (int k = 0; k < 2; ++k) \
;         acc[ai][bj][m][n] = __builtin_amdgcn_mfma_f32_16x16x32_bf16(Bt[n][k], At[m][k], acc[ai][bj][m][n], 0, 0, 0); __builtin_amdgcn_s_setprio(0); } while (0)
; #define PG8_WAIT_V(n) asm volatile("s_waitcnt vmcnt(" #n ")" ::: "memory")
; #define PG8_WAIT_L(n) asm volatile("s_waitcnt lgkmcnt(" #n ")" ::: "memory")
; #define PG8_BAR __builtin_amdgcn_s_barrier()
; #define PG8_SCHED __builtin_amdgcn_sched_barrier(0)
; template <class Epi, class Sched, bool ALIGN_EPI>
; __device__ __forceinline__ void gemm_phase(LAS unsigned char* lds, const Gemm g, const Sched& S, const Epi& E, int wave_id) {
;     ...
;             PG8_LDA(At, 1, 1); PG8_STAGE(PG8_SB(1, 0), b3, voffB); PG8_STAGE(PG8_SB(1, 1), b3 + hsB, voffB); PG8_STAGE(PG8_SA(1, 0), a3, voffA);
;             PG8_WAIT_V(8); PG8_WAIT_L(0); PG8_BAR; PG8_MMA(1, 0, At, B0); PG8_MMA(1, 1, At, B1); PG8_BAR; PG8_SCHED;
;         }
	s_mov_b32 m0, s63
	v_lshl_add_u64 v[6:7], v[156:157], 0, s[92:93]
	global_load_lds_dwordx4 v[6:7], off
	v_lshl_add_u64 v[6:7], v[208:209], 0, s[92:93]
	s_mov_b32 m0, s64
	s_nop 0
	global_load_lds_dwordx4 v[6:7], off
	s_mov_b32 m0, s67
	s_nop 0
	global_load_lds_dwordx4 v142, s[30:31]
	s_mov_b32 m0, s72
	s_nop 0
	global_load_lds_dwordx4 v146, s[30:31]
	v_lshl_add_u64 v[6:7], v[210:211], 0, s[92:93]
	s_mov_b32 m0, s65
	s_nop 0
	global_load_lds_dwordx4 v[6:7], off
	v_lshl_add_u64 v[6:7], v[212:213], 0, s[92:93]
	s_mov_b32 m0, s66
	s_nop 0
	global_load_lds_dwordx4 v[6:7], off
	ds_read_b128 v[176:179], v158 offset:50176
	ds_read_b128 v[180:183], v158 offset:51200
	ds_read_b128 v[184:187], v158 offset:52224
	ds_read_b128 v[188:191], v158 offset:53248
	ds_read_b128 v[192:195], v158 offset:54272
	ds_read_b128 v[196:199], v158 offset:55296
	ds_read_b128 v[200:203], v158 offset:56320
	ds_read_b128 v[204:207], v158 offset:57344
	s_waitcnt vmcnt(8)
	s_waitcnt lgkmcnt(0)
	s_barrier
	s_setprio 1
	s_waitcnt lgkmcnt(0)
	v_mfma_f32_16x16x32_bf16 v[96:99], v[100:103], v[176:179], v[96:99]
	v_mfma_f32_16x16x32_bf16 v[92:95], v[148:151], v[176:179], v[92:95]
	v_mfma_f32_16x16x32_bf16 v[88:91], v[100:103], v[184:187], v[88:91]
	v_mfma_f32_16x16x32_bf16 v[84:87], v[148:151], v[184:187], v[84:87]
	v_mfma_f32_16x16x32_bf16 v[80:83], v[100:103], v[192:195], v[80:83]
	v_mfma_f32_16x16x32_bf16 v[76:79], v[148:151], v[192:195], v[76:79]
	v_mfma_f32_16x16x32_bf16 v[72:75], v[100:103], v[200:203], v[72:75]
	v_mfma_f32_16x16x32_bf16 v[68:71], v[148:151], v[200:203], v[68:71]
	v_mfma_f32_16x16x32_bf16 v[96:99], v[108:111], v[180:183], v[96:99]
	v_mfma_f32_16x16x32_bf16 v[92:95], v[152:155], v[180:183], v[92:95]
	v_mfma_f32_16x16x32_bf16 v[88:91], v[108:111], v[188:191], v[88:91]
	v_mfma_f32_16x16x32_bf16 v[84:87], v[152:155], v[188:191], v[84:87]
	v_mfma_f32_16x16x32_bf16 v[80:83], v[108:111], v[196:199], v[80:83]
	v_mfma_f32_16x16x32_bf16 v[76:79], v[152:155], v[196:199], v[76:79]
	v_mfma_f32_16x16x32_bf16 v[72:75], v[108:111], v[204:207], v[72:75]
	v_mfma_f32_16x16x32_bf16 v[68:71], v[152:155], v[204:207], v[68:71]
	s_setprio 0
	s_setprio 1
	v_mfma_f32_16x16x32_bf16 v[32:35], v[160:163], v[176:179], v[32:35]
	v_mfma_f32_16x16x32_bf16 v[28:31], v[168:171], v[176:179], v[28:31]
	v_mfma_f32_16x16x32_bf16 v[24:27], v[160:163], v[184:187], v[24:27]
	v_mfma_f32_16x16x32_bf16 v[20:23], v[168:171], v[184:187], v[20:23]
	v_mfma_f32_16x16x32_bf16 v[16:19], v[160:163], v[192:195], v[16:19]
	v_mfma_f32_16x16x32_bf16 v[12:15], v[168:171], v[192:195], v[12:15]
	v_mfma_f32_16x16x32_bf16 v[6:9], v[160:163], v[200:203], v[8:11]
	v_mfma_f32_16x16x32_bf16 v[2:5], v[168:171], v[200:203], v[2:5]
	v_mfma_f32_16x16x32_bf16 v[32:35], v[164:167], v[180:183], v[32:35]
	v_mfma_f32_16x16x32_bf16 v[28:31], v[172:175], v[180:183], v[28:31]
	v_mfma_f32_16x16x32_bf16 v[24:27], v[164:167], v[188:191], v[24:27]
	v_mfma_f32_16x16x32_bf16 v[20:23], v[172:175], v[188:191], v[20:23]
	v_mfma_f32_16x16x32_bf16 v[16:19], v[164:167], v[196:199], v[16:19]
	v_mfma_f32_16x16x32_bf16 v[12:15], v[172:175], v[196:199], v[12:15]
	v_mfma_f32_16x16x32_bf16 v[8:11], v[164:167], v[204:207], v[6:9]
	v_mfma_f32_16x16x32_bf16 v[4:7], v[172:175], v[204:207], v[2:5]
	s_setprio 0
	s_barrier
	s_andn2_b64 vcc, exec, s[28:29]
	s_mov_b64 s[30:31], -1
	s_mov_b64 s[28:29], 0
	s_mov_b64 s[34:35], 0x100
	s_cbranch_vccz .LBB0_1458
	s_and_b64 vcc, exec, s[16:17]
	s_cbranch_vccz .LBB0_1461
	s_barrier

; #define GAS __attribute__((address_space(1)))
; #define PG8_STAGE(bufoff, gbase, voff) do { _Pragma("unroll") for (int _i = 0; _i < 2; ++_i) \
;         __builtin_amdgcn_global_load_lds((const GAS unsigned*)((const GAS char*)(gbase) + (voff)[_i]), (LAS unsigned*)(lds + (bufoff) + ldsw + _i * 8192), 16, 0, 0); } while (0)
; #define PG8_LDA(dst, b, h) do { _Pragma("unroll") for (int m = 0; m < 4; ++m) _Pragma("unroll") for (int k = 0; k < 2; ++k) dst[m][k] = *(const LAS bf16x8*)(lds + PG8_SA(b, h) + aoff + m * 2048 + k * 1024); } while (0)
; #define PG8_LDB(dst, b, h) do { _Pragma("unroll") for (int n = 0; n < 2; ++n) _Pragma("unroll") for (int k = 0; k < 2; ++k) dst[n][k] = *(const LAS bf16x8*)(lds + PG8_SB(b, h) + boff + n * 2048 + k * 1024); } while (0)
; #define PG8_MMA(ai, bj, At, Bt) do { __builtin_amdgcn_s_setprio(1); _Pragma("unroll") for (int m = 0; m < 4; ++m) _Pragma("unroll") for (int n = 0; n < 2; ++n) _Pragma("unroll") for (int k = 0; k < 2; ++k) \
;         acc[ai][bj][m][n] = __builtin_amdgcn_mfma_f32_16x16x32_bf16(Bt[n][k], At[m][k], acc[ai][bj][m][n], 0, 0, 0); __builtin_amdgcn_s_setprio(0); } while (0)
; #define PG8_WAIT_V(n) asm volatile("s_waitcnt vmcnt(" #n ")" ::: "memory")
; #define PG8_WAIT_L(n) asm volatile("s_waitcnt lgkmcnt(" #n ")" ::: "memory")
; template <class Epi, class Sched, bool ALIGN_EPI>
; __device__ __forceinline__ void gemm_phase(LAS unsigned char* lds, const Gemm g, const Sched& S, const Epi& E, int wave_id) {
;     ...
;         for (int t = 0; t < nt; t += 2) {
;             const bool last = (t == nt - 2);
;             const GAS char* a1 = cA + (size_t)(t + 1) * kstep;
;             const GAS char* a2 = last ? nA : cA + (size_t)(t + 2) * kstep; const GAS char* b2 = last ? nB : cB + (size_t)(t + 2) * kstep;
;             const GAS char* a3 = a2 + kstep; const GAS char* b3 = b2 + kstep;
;             PG8_LDB(B0, 0, 0); PG8_LDB(B1, 0, 1); PG8_SCHED; PG8_LDA(At, 0, 0); PG8_STAGE(PG8_SA(1, 1), a1 + hsA, voffA);
;             PG8_WAIT_V(8); PG8_WAIT_L(0); PG8_BAR; PG8_MMA(0, 0, At, B0); PG8_MMA(0, 1, At, B1); PG8_BAR; PG8_SCHED;
;             PG8_LDA(At, 0, 1); PG8_STAGE(PG8_SB(0, 0), b2, voffB); PG8_STAGE(PG8_SB(0, 1), b2 + hsB, voffB); PG8_STAGE(PG8_SA(0, 0), a2, voffA);
;             PG8_WAIT_V(8); PG8_WAIT_L(0); PG8_BAR; PG8_MMA(1, 0, At, B0); PG8_MMA(1, 1, At, B1); PG8_BAR; PG8_SCHED;
.LBB0_1645:
	s_add_u32 s20, s18, 0x100
	s_addc_u32 s21, s19, 0
	s_cmp_eq_u32 s55, 2
	s_cselect_b32 s25, s15, s21
	s_cselect_b32 s24, s14, s20
	s_cselect_b32 s23, s17, s54
	s_cselect_b32 s22, s16, s53
	v_lshl_add_u64 v[192:193], s[18:19], 0, v[170:171]
	s_add_i32 m0, s31, 0xc400
	s_nop 0
	global_load_lds_dwordx4 v[192:193], off
	v_lshl_add_u64 v[192:193], s[18:19], 0, v[168:169]
	s_add_i32 m0, s31, 0xe400
	s_nop 0
	global_load_lds_dwordx4 v[192:193], off
	v_add_u32_e32 v134, 0x10400, v195
	v_add_u32_e32 v158, 0x14400, v195
	ds_read_b128 v[114:117], v134
	ds_read_b128 v[118:121], v134 offset:1024
	ds_read_b128 v[130:133], v134 offset:2048
	ds_read_b128 v[134:137], v134 offset:3072
	ds_read_b128 v[146:149], v158
	ds_read_b128 v[150:153], v158 offset:1024
	ds_read_b128 v[154:157], v158 offset:2048
	ds_read_b128 v[158:161], v158 offset:3072
	ds_read_b128 v[172:175], v194 offset:1024
	ds_read_b128 v[176:179], v194 offset:2048
	ds_read_b128 v[180:183], v194 offset:3072
	ds_read_b128 v[184:187], v194 offset:4096
	ds_read_b128 v[188:191], v194 offset:5120
	ds_read_b128 v[196:199], v194 offset:6144
	ds_read_b128 v[200:203], v194 offset:7168
	ds_read_b128 v[204:207], v194 offset:8192
	s_waitcnt vmcnt(8)
	s_waitcnt lgkmcnt(0)
	s_barrier
	s_setprio 1
	s_waitcnt lgkmcnt(0)
	v_mfma_f32_16x16x32_bf16 v[142:145], v[114:117], v[172:175], v[142:145]
	v_mfma_f32_16x16x32_bf16 v[138:141], v[130:133], v[172:175], v[138:141]
	v_mfma_f32_16x16x32_bf16 v[126:129], v[114:117], v[180:183], v[126:129]
	v_mfma_f32_16x16x32_bf16 v[122:125], v[130:133], v[180:183], v[122:125]
	v_mfma_f32_16x16x32_bf16 v[110:113], v[114:117], v[188:191], v[110:113]
	v_mfma_f32_16x16x32_bf16 v[106:109], v[130:133], v[188:191], v[106:109]
	v_mfma_f32_16x16x32_bf16 v[102:105], v[114:117], v[200:203], v[102:105]
	v_mfma_f32_16x16x32_bf16 v[98:101], v[130:133], v[200:203], v[98:101]
	v_mfma_f32_16x16x32_bf16 v[142:145], v[118:121], v[176:179], v[142:145]
	v_mfma_f32_16x16x32_bf16 v[138:141], v[134:137], v[176:179], v[138:141]
	v_mfma_f32_16x16x32_bf16 v[126:129], v[118:121], v[184:187], v[126:129]
	v_mfma_f32_16x16x32_bf16 v[122:125], v[134:137], v[184:187], v[122:125]
	v_mfma_f32_16x16x32_bf16 v[110:113], v[118:121], v[196:199], v[110:113]
	v_mfma_f32_16x16x32_bf16 v[106:109], v[134:137], v[196:199], v[106:109]
	v_mfma_f32_16x16x32_bf16 v[102:105], v[118:121], v[204:207], v[102:105]
	v_mfma_f32_16x16x32_bf16 v[98:101], v[134:137], v[204:207], v[98:101]
	s_setprio 0
	s_setprio 1
	v_mfma_f32_16x16x32_bf16 v[62:65], v[146:149], v[172:175], v[62:65]
	v_mfma_f32_16x16x32_bf16 v[58:61], v[154:157], v[172:175], v[58:61]
	v_mfma_f32_16x16x32_bf16 v[54:57], v[146:149], v[180:183], v[54:57]
	v_mfma_f32_16x16x32_bf16 v[50:53], v[154:157], v[180:183], v[50:53]
	v_mfma_f32_16x16x32_bf16 v[46:49], v[146:149], v[188:191], v[46:49]
	v_mfma_f32_16x16x32_bf16 v[42:45], v[154:157], v[188:191], v[42:45]
	v_mfma_f32_16x16x32_bf16 v[38:41], v[146:149], v[200:203], v[38:41]
	v_mfma_f32_16x16x32_bf16 v[34:37], v[154:157], v[200:203], v[34:37]
	v_mfma_f32_16x16x32_bf16 v[62:65], v[150:153], v[176:179], v[62:65]
	v_mfma_f32_16x16x32_bf16 v[58:61], v[158:161], v[176:179], v[58:61]
	v_mfma_f32_16x16x32_bf16 v[54:57], v[150:153], v[184:187], v[54:57]
	v_mfma_f32_16x16x32_bf16 v[50:53], v[158:161], v[184:187], v[50:53]
	v_mfma_f32_16x16x32_bf16 v[46:49], v[150:153], v[196:199], v[46:49]
	v_mfma_f32_16x16x32_bf16 v[42:45], v[158:161], v[196:199], v[42:45]
	v_mfma_f32_16x16x32_bf16 v[38:41], v[150:153], v[204:207], v[38:41]
	v_mfma_f32_16x16x32_bf16 v[34:37], v[158:161], v[204:207], v[34:37]
	s_setprio 0
	s_barrier
	s_mov_b32 m0, s34
	v_lshl_add_u64 v[192:193], s[22:23], 0, v[0:1]
	s_add_u32 s18, s22, 0x18000
	global_load_lds_dwordx4 v[192:193], off
	v_lshl_add_u64 v[208:209], s[22:23], 0, v[162:163]
	s_mov_b32 m0, s35
	s_addc_u32 s19, s23, 0
	global_load_lds_dwordx4 v162, s[22:23]
	v_lshl_add_u64 v[210:211], s[18:19], 0, v[0:1]
	s_mov_b32 m0, s36
	v_lshl_add_u64 v[212:213], s[24:25], 0, v[164:165]
	global_load_lds_dwordx4 v[210:211], off
	s_mov_b32 m0, s37
	s_nop 0
	global_load_lds_dwordx4 v162, s[18:19]
	v_lshl_add_u64 v[210:211], s[24:25], 0, v[166:167]
	s_mov_b32 m0, s38
	s_nop 0
	global_load_lds_dwordx4 v166, s[24:25]
	s_mov_b32 m0, s39
	s_nop 0
	global_load_lds_dwordx4 v164, s[24:25]
	ds_read_b128 v[172:175], v194 offset:17408
	ds_read_b128 v[176:179], v194 offset:18432
	ds_read_b128 v[180:183], v194 offset:19456
	ds_read_b128 v[184:187], v194 offset:20480
	ds_read_b128 v[188:191], v194 offset:21504
	ds_read_b128 v[196:199], v194 offset:22528
	ds_read_b128 v[200:203], v194 offset:23552
	ds_read_b128 v[204:207], v194 offset:24576
	s_waitcnt vmcnt(8)
	s_waitcnt lgkmcnt(0)
	s_barrier
; #define PG8_STAGE(bufoff, gbase, voff) do { _Pragma("unroll") for (int _i = 0; _i < 2; ++_i) \
;         __builtin_amdgcn_global_load_lds((const GAS unsigned*)((const GAS char*)(gbase) + (voff)[_i]), (LAS unsigned*)(lds + (bufoff) + ldsw + _i * 8192), 16, 0, 0); } while (0)
; #define PG8_LDA(dst, b, h) do { _Pragma("unroll") for (int m = 0; m < 4; ++m) _Pragma("unroll") for (int k = 0; k < 2; ++k) dst[m][k] = *(const LAS bf16x8*)(lds + PG8_SA(b, h) + aoff + m * 2048 + k * 1024); } while (0)
; #define PG8_LDB(dst, b, h) do { _Pragma("unroll") for (int n = 0; n < 2; ++n) _Pragma("unroll") for (int k = 0; k < 2; ++k) dst[n][k] = *(const LAS bf16x8*)(lds + PG8_SB(b, h) + boff + n * 2048 + k * 1024); } while (0)
; #define PG8_MMA(ai, bj, At, Bt) do { __builtin_amdgcn_s_setprio(1); _Pragma("unroll") for (int m = 0; m < 4; ++m) _Pragma("unroll") for (int n = 0; n < 2; ++n) _Pragma("unroll") for (int k = 0; k < 2; ++k) \
;         acc[ai][bj][m][n] = __builtin_amdgcn_mfma_f32_16x16x32_bf16(Bt[n][k], At[m][k], acc[ai][bj][m][n], 0, 0, 0); __builtin_amdgcn_s_setprio(0); } while (0)
; #define PG8_WAIT_V(n) asm volatile("s_waitcnt vmcnt(" #n ")" ::: "memory")
; #define PG8_WAIT_L(n) asm volatile("s_waitcnt lgkmcnt(" #n ")" ::: "memory")
; #define PG8_BAR __builtin_amdgcn_s_barrier()
; #define PG8_SCHED __builtin_amdgcn_sched_barrier(0)
; template <class Epi, class Sched, bool ALIGN_EPI>
; __device__ __forceinline__ void gemm_phase(LAS unsigned char* lds, const Gemm g, const Sched& S, const Epi& E, int wave_id) {
;     ...
;             PG8_WAIT_V(8); PG8_WAIT_L(0); PG8_BAR; PG8_MMA(1, 0, At, B0); PG8_MMA(1, 1, At, B1); PG8_BAR; PG8_SCHED;
;             PG8_LDB(B0, 1, 0); PG8_LDB(B1, 1, 1); PG8_SCHED; PG8_LDA(At, 1, 0); PG8_STAGE(PG8_SA(0, 1), a2 + hsA, voffA);
;             PG8_WAIT_V(8); PG8_WAIT_L(0); PG8_BAR; PG8_MMA(0, 0, At, B0); PG8_MMA(0, 1, At, B1); PG8_BAR; PG8_SCHED;
	s_setprio 1
	s_waitcnt lgkmcnt(0)
	v_mfma_f32_16x16x32_bf16 v[94:97], v[114:117], v[172:175], v[94:97]
	v_mfma_f32_16x16x32_bf16 v[90:93], v[130:133], v[172:175], v[90:93]
	v_mfma_f32_16x16x32_bf16 v[86:89], v[114:117], v[180:183], v[86:89]
	v_mfma_f32_16x16x32_bf16 v[82:85], v[130:133], v[180:183], v[82:85]
	v_mfma_f32_16x16x32_bf16 v[78:81], v[114:117], v[188:191], v[78:81]
	v_mfma_f32_16x16x32_bf16 v[74:77], v[130:133], v[188:191], v[74:77]
	v_mfma_f32_16x16x32_bf16 v[70:73], v[114:117], v[200:203], v[70:73]
	v_mfma_f32_16x16x32_bf16 v[66:69], v[130:133], v[200:203], v[66:69]
	v_mfma_f32_16x16x32_bf16 v[94:97], v[118:121], v[176:179], v[94:97]
	v_mfma_f32_16x16x32_bf16 v[90:93], v[134:137], v[176:179], v[90:93]
	v_mfma_f32_16x16x32_bf16 v[86:89], v[118:121], v[184:187], v[86:89]
	v_mfma_f32_16x16x32_bf16 v[82:85], v[134:137], v[184:187], v[82:85]
	v_mfma_f32_16x16x32_bf16 v[78:81], v[118:121], v[196:199], v[78:81]
	v_mfma_f32_16x16x32_bf16 v[74:77], v[134:137], v[196:199], v[74:77]
	v_mfma_f32_16x16x32_bf16 v[70:73], v[118:121], v[204:207], v[70:73]
	v_mfma_f32_16x16x32_bf16 v[66:69], v[134:137], v[204:207], v[66:69]
	s_setprio 0
	s_setprio 1
	v_mfma_f32_16x16x32_bf16 v[30:33], v[146:149], v[172:175], v[30:33]
	v_mfma_f32_16x16x32_bf16 v[26:29], v[154:157], v[172:175], v[26:29]
	v_mfma_f32_16x16x32_bf16 v[22:25], v[146:149], v[180:183], v[22:25]
	v_mfma_f32_16x16x32_bf16 v[18:21], v[154:157], v[180:183], v[18:21]
	v_mfma_f32_16x16x32_bf16 v[14:17], v[146:149], v[188:191], v[14:17]
	v_mfma_f32_16x16x32_bf16 v[10:13], v[154:157], v[188:191], v[10:13]
	v_mfma_f32_16x16x32_bf16 v[6:9], v[146:149], v[200:203], v[6:9]
	v_mfma_f32_16x16x32_bf16 v[2:5], v[154:157], v[200:203], v[2:5]
	v_mfma_f32_16x16x32_bf16 v[30:33], v[150:153], v[176:179], v[30:33]
	v_mfma_f32_16x16x32_bf16 v[26:29], v[158:161], v[176:179], v[26:29]
	v_mfma_f32_16x16x32_bf16 v[22:25], v[150:153], v[184:187], v[22:25]
	v_mfma_f32_16x16x32_bf16 v[18:21], v[158:161], v[184:187], v[18:21]
	v_mfma_f32_16x16x32_bf16 v[14:17], v[150:153], v[196:199], v[14:17]
	v_mfma_f32_16x16x32_bf16 v[10:13], v[158:161], v[196:199], v[10:13]
	v_mfma_f32_16x16x32_bf16 v[6:9], v[150:153], v[204:207], v[6:9]
	v_mfma_f32_16x16x32_bf16 v[2:5], v[158:161], v[204:207], v[2:5]
	s_setprio 0
	s_barrier
	s_add_u32 s18, s24, 0x18000
	s_addc_u32 s19, s25, 0
	s_mov_b32 m0, s40
	s_nop 0
	global_load_lds_dwordx4 v166, s[18:19]
	s_mov_b32 m0, s41
	s_nop 0
	global_load_lds_dwordx4 v164, s[18:19]
	v_add_u32_e32 v134, 0x18400, v195
	v_add_u32_e32 v158, 0x1c400, v195
	ds_read_b128 v[114:117], v134
	ds_read_b128 v[118:121], v134 offset:1024
	ds_read_b128 v[130:133], v134 offset:2048
	ds_read_b128 v[134:137], v134 offset:3072
	ds_read_b128 v[146:149], v158
	ds_read_b128 v[150:153], v158 offset:1024
	ds_read_b128 v[154:157], v158 offset:2048
	ds_read_b128 v[158:161], v158 offset:3072
	ds_read_b128 v[172:175], v194 offset:33792
	ds_read_b128 v[176:179], v194 offset:34816
	ds_read_b128 v[180:183], v194 offset:35840
	ds_read_b128 v[184:187], v194 offset:36864
	ds_read_b128 v[188:191], v194 offset:37888
	ds_read_b128 v[196:199], v194 offset:38912
	ds_read_b128 v[200:203], v194 offset:39936
	ds_read_b128 v[204:207], v194 offset:40960
	s_waitcnt vmcnt(8)
	s_waitcnt lgkmcnt(0)
	s_barrier
	s_setprio 1
	s_waitcnt lgkmcnt(0)
	v_mfma_f32_16x16x32_bf16 v[142:145], v[114:117], v[172:175], v[142:145]
	v_mfma_f32_16x16x32_bf16 v[138:141], v[130:133], v[172:175], v[138:141]
	v_mfma_f32_16x16x32_bf16 v[126:129], v[114:117], v[180:183], v[126:129]
	v_mfma_f32_16x16x32_bf16 v[122:125], v[130:133], v[180:183], v[122:125]
	v_mfma_f32_16x16x32_bf16 v[110:113], v[114:117], v[188:191], v[110:113]
	v_mfma_f32_16x16x32_bf16 v[106:109], v[130:133], v[188:191], v[106:109]
	v_mfma_f32_16x16x32_bf16 v[102:105], v[114:117], v[200:203], v[102:105]
	v_mfma_f32_16x16x32_bf16 v[98:101], v[130:133], v[200:203], v[98:101]
	v_mfma_f32_16x16x32_bf16 v[142:145], v[118:121], v[176:179], v[142:145]
	v_mfma_f32_16x16x32_bf16 v[138:141], v[134:137], v[176:179], v[138:141]
	v_mfma_f32_16x16x32_bf16 v[126:129], v[118:121], v[184:187], v[126:129]
	v_mfma_f32_16x16x32_bf16 v[122:125], v[134:137], v[184:187], v[122:125]
	v_mfma_f32_16x16x32_bf16 v[110:113], v[118:121], v[196:199], v[110:113]
	v_mfma_f32_16x16x32_bf16 v[106:109], v[134:137], v[196:199], v[106:109]
	v_mfma_f32_16x16x32_bf16 v[102:105], v[118:121], v[204:207], v[102:105]
	v_mfma_f32_16x16x32_bf16 v[98:101], v[134:137], v[204:207], v[98:101]
	s_setprio 0
	s_setprio 1
	v_mfma_f32_16x16x32_bf16 v[62:65], v[146:149], v[172:175], v[62:65]
	v_mfma_f32_16x16x32_bf16 v[58:61], v[154:157], v[172:175], v[58:61]
	v_mfma_f32_16x16x32_bf16 v[54:57], v[146:149], v[180:183], v[54:57]
	v_mfma_f32_16x16x32_bf16 v[50:53], v[154:157], v[180:183], v[50:53]
	v_mfma_f32_16x16x32_bf16 v[46:49], v[146:149], v[188:191], v[46:49]
	v_mfma_f32_16x16x32_bf16 v[42:45], v[154:157], v[188:191], v[42:45]
	v_mfma_f32_16x16x32_bf16 v[38:41], v[146:149], v[200:203], v[38:41]
	v_mfma_f32_16x16x32_bf16 v[34:37], v[154:157], v[200:203], v[34:37]
	v_mfma_f32_16x16x32_bf16 v[62:65], v[150:153], v[176:179], v[62:65]
	v_mfma_f32_16x16x32_bf16 v[58:61], v[158:161], v[176:179], v[58:61]
	v_mfma_f32_16x16x32_bf16 v[54:57], v[150:153], v[184:187], v[54:57]
	v_mfma_f32_16x16x32_bf16 v[50:53], v[158:161], v[184:187], v[50:53]
	v_mfma_f32_16x16x32_bf16 v[46:49], v[150:153], v[196:199], v[46:49]
	v_mfma_f32_16x16x32_bf16 v[42:45], v[158:161], v[196:199], v[42:45]
	v_mfma_f32_16x16x32_bf16 v[38:41], v[150:153], v[204:207], v[38:41]
	v_mfma_f32_16x16x32_bf16 v[34:37], v[158:161], v[204:207], v[34:37]
	s_setprio 0
	s_barrier
; #define PG8_STAGE(bufoff, gbase, voff) do { _Pragma("unroll") for (int _i = 0; _i < 2; ++_i) \
;         __builtin_amdgcn_global_load_lds((const GAS unsigned*)((const GAS char*)(gbase) + (voff)[_i]), (LAS unsigned*)(lds + (bufoff) + ldsw + _i * 8192), 16, 0, 0); } while (0)
; #define PG8_LDA(dst, b, h) do { _Pragma("unroll") for (int m = 0; m < 4; ++m) _Pragma("unroll") for (int k = 0; k < 2; ++k) dst[m][k] = *(const LAS bf16x8*)(lds + PG8_SA(b, h) + aoff + m * 2048 + k * 1024); } while (0)
; #define PG8_MMA(ai, bj, At, Bt) do { __builtin_amdgcn_s_setprio(1); _Pragma("unroll") for (int m = 0; m < 4; ++m) _Pragma("unroll") for (int n = 0; n < 2; ++n) _Pragma("unroll") for (int k = 0; k < 2; ++k) \
;         acc[ai][bj][m][n] = __builtin_amdgcn_mfma_f32_16x16x32_bf16(Bt[n][k], At[m][k], acc[ai][bj][m][n], 0, 0, 0); __builtin_amdgcn_s_setprio(0); } while (0)
; #define PG8_WAIT_V(n) asm volatile("s_waitcnt vmcnt(" #n ")" ::: "memory")
; #define PG8_WAIT_L(n) asm volatile("s_waitcnt lgkmcnt(" #n ")" ::: "memory")
; #define PG8_BAR __builtin_amdgcn_s_barrier()
; #define PG8_SCHED __builtin_amdgcn_sched_barrier(0)
; template <class Epi, class Sched, bool ALIGN_EPI>
; __device__ __forceinline__ void gemm_phase(LAS unsigned char* lds, const Gemm g, const Sched& S, const Epi& E, int wave_id) {
;     ...
;             PG8_LDA(At, 1, 1); PG8_STAGE(PG8_SB(1, 0), b3, voffB); PG8_STAGE(PG8_SB(1, 1), b3 + hsB, voffB); PG8_STAGE(PG8_SA(1, 0), a3, voffA);
;             PG8_WAIT_V(8); PG8_WAIT_L(0); PG8_BAR; PG8_MMA(1, 0, At, B0); PG8_MMA(1, 1, At, B1); PG8_BAR; PG8_SCHED;
;         }
	s_mov_b32 m0, s44
	v_lshl_add_u64 v[192:193], v[192:193], 0, s[92:93]
	s_add_u32 s18, s22, 0x18080
	global_load_lds_dwordx4 v[192:193], off
	v_lshl_add_u64 v[192:193], v[208:209], 0, s[92:93]
	s_mov_b32 m0, s45
	s_addc_u32 s19, s23, 0
	global_load_lds_dwordx4 v[192:193], off
	v_lshl_add_u64 v[192:193], s[18:19], 0, v[0:1]
	s_mov_b32 m0, s48
	s_nop 0
	global_load_lds_dwordx4 v[192:193], off
	s_mov_b32 m0, s49
	s_nop 0
	global_load_lds_dwordx4 v162, s[18:19]
	v_lshl_add_u64 v[192:193], v[210:211], 0, s[92:93]
	s_mov_b32 m0, s46
	s_nop 0
	global_load_lds_dwordx4 v[192:193], off
	v_lshl_add_u64 v[192:193], v[212:213], 0, s[92:93]
	s_mov_b32 m0, s47
	s_nop 0
	global_load_lds_dwordx4 v[192:193], off
	ds_read_b128 v[172:175], v194 offset:50176
	ds_read_b128 v[176:179], v194 offset:51200
	ds_read_b128 v[180:183], v194 offset:52224
	ds_read_b128 v[184:187], v194 offset:53248
	ds_read_b128 v[188:191], v194 offset:54272
	ds_read_b128 v[196:199], v194 offset:55296
	ds_read_b128 v[200:203], v194 offset:56320
	ds_read_b128 v[204:207], v194 offset:57344
	s_waitcnt vmcnt(8)
	s_waitcnt lgkmcnt(0)
	s_barrier
	s_setprio 1
	s_waitcnt lgkmcnt(0)
	v_mfma_f32_16x16x32_bf16 v[94:97], v[114:117], v[172:175], v[94:97]
	v_mfma_f32_16x16x32_bf16 v[90:93], v[130:133], v[172:175], v[90:93]
	v_mfma_f32_16x16x32_bf16 v[86:89], v[114:117], v[180:183], v[86:89]
	v_mfma_f32_16x16x32_bf16 v[82:85], v[130:133], v[180:183], v[82:85]
	v_mfma_f32_16x16x32_bf16 v[78:81], v[114:117], v[188:191], v[78:81]
	v_mfma_f32_16x16x32_bf16 v[74:77], v[130:133], v[188:191], v[74:77]
	v_mfma_f32_16x16x32_bf16 v[70:73], v[114:117], v[200:203], v[70:73]
	v_mfma_f32_16x16x32_bf16 v[66:69], v[130:133], v[200:203], v[66:69]
	v_mfma_f32_16x16x32_bf16 v[94:97], v[118:121], v[176:179], v[94:97]
	v_mfma_f32_16x16x32_bf16 v[90:93], v[134:137], v[176:179], v[90:93]
	v_mfma_f32_16x16x32_bf16 v[86:89], v[118:121], v[184:187], v[86:89]
	v_mfma_f32_16x16x32_bf16 v[82:85], v[134:137], v[184:187], v[82:85]
	v_mfma_f32_16x16x32_bf16 v[78:81], v[118:121], v[196:199], v[78:81]
	v_mfma_f32_16x16x32_bf16 v[74:77], v[134:137], v[196:199], v[74:77]
	v_mfma_f32_16x16x32_bf16 v[70:73], v[118:121], v[204:207], v[70:73]
	v_mfma_f32_16x16x32_bf16 v[66:69], v[134:137], v[204:207], v[66:69]
	s_setprio 0
	s_setprio 1
	v_mfma_f32_16x16x32_bf16 v[30:33], v[146:149], v[172:175], v[30:33]
	v_mfma_f32_16x16x32_bf16 v[26:29], v[154:157], v[172:175], v[26:29]
	v_mfma_f32_16x16x32_bf16 v[22:25], v[146:149], v[180:183], v[22:25]
	v_mfma_f32_16x16x32_bf16 v[18:21], v[154:157], v[180:183], v[18:21]
	v_mfma_f32_16x16x32_bf16 v[14:17], v[146:149], v[188:191], v[14:17]
	v_mfma_f32_16x16x32_bf16 v[10:13], v[154:157], v[188:191], v[10:13]
	v_mfma_f32_16x16x32_bf16 v[6:9], v[146:149], v[200:203], v[6:9]
	v_mfma_f32_16x16x32_bf16 v[2:5], v[154:157], v[200:203], v[2:5]
	v_mfma_f32_16x16x32_bf16 v[30:33], v[150:153], v[176:179], v[30:33]
	v_mfma_f32_16x16x32_bf16 v[26:29], v[158:161], v[176:179], v[26:29]
	v_mfma_f32_16x16x32_bf16 v[22:25], v[150:153], v[184:187], v[22:25]
	v_mfma_f32_16x16x32_bf16 v[18:21], v[158:161], v[184:187], v[18:21]
	v_mfma_f32_16x16x32_bf16 v[14:17], v[150:153], v[196:199], v[14:17]
	v_mfma_f32_16x16x32_bf16 v[10:13], v[158:161], v[196:199], v[10:13]
	v_mfma_f32_16x16x32_bf16 v[6:9], v[150:153], v[204:207], v[6:9]
	v_mfma_f32_16x16x32_bf16 v[2:5], v[158:161], v[204:207], v[2:5]
	s_setprio 0
	s_barrier
	s_add_i32 s55, s55, 2
	s_add_u32 s53, s53, 0x100
	s_addc_u32 s54, s54, 0
	s_cmp_gt_u32 s55, 3
	s_mov_b64 s[18:19], s[20:21]
	s_cbranch_scc0 .LBB0_1645
	s_and_b64 vcc, exec, s[12:13]
	s_cbranch_vccz .LBB0_1648
	s_barrier

; #define GAS __attribute__((address_space(1)))
; #define PG8_STAGE(bufoff, gbase, voff) do { _Pragma("unroll") for (int _i = 0; _i < 2; ++_i) \
;         __builtin_amdgcn_global_load_lds((const GAS unsigned*)((const GAS char*)(gbase) + (voff)[_i]), (LAS unsigned*)(lds + (bufoff) + ldsw + _i * 8192), 16, 0, 0); } while (0)
; #define PG8_LDA(dst, b, h) do { _Pragma("unroll") for (int m = 0; m < 4; ++m) _Pragma("unroll") for (int k = 0; k < 2; ++k) dst[m][k] = *(const LAS bf16x8*)(lds + PG8_SA(b, h) + aoff + m * 2048 + k * 1024); } while (0)
; #define PG8_LDB(dst, b, h) do { _Pragma("unroll") for (int n = 0; n < 2; ++n) _Pragma("unroll") for (int k = 0; k < 2; ++k) dst[n][k] = *(const LAS bf16x8*)(lds + PG8_SB(b, h) + boff + n * 2048 + k * 1024); } while (0)
; #define PG8_MMA(ai, bj, At, Bt) do { __builtin_amdgcn_s_setprio(1); _Pragma("unroll") for (int m = 0; m < 4; ++m) _Pragma("unroll") for (int n = 0; n < 2; ++n) _Pragma("unroll") for (int k = 0; k < 2; ++k) \
;         acc[ai][bj][m][n] = __builtin_amdgcn_mfma_f32_16x16x32_bf16(Bt[n][k], At[m][k], acc[ai][bj][m][n], 0, 0, 0); __builtin_amdgcn_s_setprio(0); } while (0)
; #define PG8_WAIT_V(n) asm volatile("s_waitcnt vmcnt(" #n ")" ::: "memory")
; #define PG8_WAIT_L(n) asm volatile("s_waitcnt lgkmcnt(" #n ")" ::: "memory")
; template <class Epi, class Sched, bool ALIGN_EPI>
; __device__ __forceinline__ void gemm_phase(LAS unsigned char* lds, const Gemm g, const Sched& S, const Epi& E, int wave_id) {
;     ...
;         for (int t = 0; t < nt; t += 2) {
;             const bool last = (t == nt - 2);
;             const GAS char* a1 = cA + (size_t)(t + 1) * kstep;
;             const GAS char* a2 = last ? nA : cA + (size_t)(t + 2) * kstep; const GAS char* b2 = last ? nB : cB + (size_t)(t + 2) * kstep;
;             const GAS char* a3 = a2 + kstep; const GAS char* b3 = b2 + kstep;
;             PG8_LDB(B0, 0, 0); PG8_LDB(B1, 0, 1); PG8_SCHED; PG8_LDA(At, 0, 0); PG8_STAGE(PG8_SA(1, 1), a1 + hsA, voffA);
;             PG8_WAIT_V(8); PG8_WAIT_L(0); PG8_BAR; PG8_MMA(0, 0, At, B0); PG8_MMA(0, 1, At, B1); PG8_BAR; PG8_SCHED;
;             PG8_LDA(At, 0, 1); PG8_STAGE(PG8_SB(0, 0), b2, voffB); PG8_STAGE(PG8_SB(0, 1), b2 + hsB, voffB); PG8_STAGE(PG8_SA(0, 0), a2, voffA);
;             PG8_WAIT_V(8); PG8_WAIT_L(0); PG8_BAR; PG8_MMA(1, 0, At, B0); PG8_MMA(1, 1, At, B1); PG8_BAR; PG8_SCHED;
.LBB0_1837:
	s_add_u32 s42, s40, 0xfffc0080
	s_addc_u32 s43, s41, -1
	s_cmp_eq_u32 s67, 12
	s_cselect_b32 s45, s5, s43
	s_cselect_b32 s44, s25, s42
	s_cselect_b32 s43, s27, s66
	s_cselect_b32 s42, s37, s39
	s_add_i32 m0, s1, 0xc400
	s_nop 0
	global_load_lds_dwordx4 v182, s[40:41]
	s_add_i32 m0, s1, 0xe400
	s_nop 0
	global_load_lds_dwordx4 v180, s[40:41]
	v_add_u32_e32 v142, 0x10400, v199
	v_add_u32_e32 v158, 0x14400, v199
	ds_read_b128 v[130:133], v142
	ds_read_b128 v[134:137], v142 offset:1024
	ds_read_b128 v[138:141], v142 offset:2048
	ds_read_b128 v[142:145], v142 offset:3072
	ds_read_b128 v[146:149], v158
	ds_read_b128 v[150:153], v158 offset:1024
	ds_read_b128 v[154:157], v158 offset:2048
	ds_read_b128 v[158:161], v158 offset:3072
	ds_read_b128 v[162:165], v198 offset:1024
	ds_read_b128 v[166:169], v198 offset:2048
	ds_read_b128 v[170:173], v198 offset:3072
	ds_read_b128 v[184:187], v198 offset:4096
	ds_read_b128 v[188:191], v198 offset:5120
	ds_read_b128 v[192:195], v198 offset:6144
	ds_read_b128 v[200:203], v198 offset:7168
	ds_read_b128 v[204:207], v198 offset:8192
	s_waitcnt vmcnt(8)
	s_waitcnt lgkmcnt(0)
	s_barrier
	s_setprio 1
	s_waitcnt lgkmcnt(0)
	v_mfma_f32_16x16x32_bf16 v[126:129], v[130:133], v[162:165], v[126:129]
	v_mfma_f32_16x16x32_bf16 v[122:125], v[138:141], v[162:165], v[122:125]
	v_mfma_f32_16x16x32_bf16 v[114:117], v[130:133], v[170:173], v[114:117]
	v_mfma_f32_16x16x32_bf16 v[106:109], v[138:141], v[170:173], v[106:109]
	v_mfma_f32_16x16x32_bf16 v[98:101], v[130:133], v[188:191], v[98:101]
	v_mfma_f32_16x16x32_bf16 v[90:93], v[138:141], v[188:191], v[90:93]
	v_mfma_f32_16x16x32_bf16 v[82:85], v[130:133], v[200:203], v[82:85]
	v_mfma_f32_16x16x32_bf16 v[74:77], v[138:141], v[200:203], v[74:77]
	v_mfma_f32_16x16x32_bf16 v[126:129], v[134:137], v[166:169], v[126:129]
	v_mfma_f32_16x16x32_bf16 v[122:125], v[142:145], v[166:169], v[122:125]
	v_mfma_f32_16x16x32_bf16 v[114:117], v[134:137], v[184:187], v[114:117]
	v_mfma_f32_16x16x32_bf16 v[106:109], v[142:145], v[184:187], v[106:109]
	v_mfma_f32_16x16x32_bf16 v[98:101], v[134:137], v[192:195], v[98:101]
	v_mfma_f32_16x16x32_bf16 v[90:93], v[142:145], v[192:195], v[90:93]
	v_mfma_f32_16x16x32_bf16 v[82:85], v[134:137], v[204:207], v[82:85]
	v_mfma_f32_16x16x32_bf16 v[74:77], v[142:145], v[204:207], v[74:77]
	s_setprio 0
	s_setprio 1
	v_mfma_f32_16x16x32_bf16 v[118:121], v[146:149], v[162:165], v[118:121]
	v_mfma_f32_16x16x32_bf16 v[110:113], v[154:157], v[162:165], v[110:113]
	v_mfma_f32_16x16x32_bf16 v[102:105], v[146:149], v[170:173], v[102:105]
	v_mfma_f32_16x16x32_bf16 v[94:97], v[154:157], v[170:173], v[94:97]
	v_mfma_f32_16x16x32_bf16 v[86:89], v[146:149], v[188:191], v[86:89]
	v_mfma_f32_16x16x32_bf16 v[78:81], v[154:157], v[188:191], v[78:81]
	v_mfma_f32_16x16x32_bf16 v[70:73], v[146:149], v[200:203], v[70:73]
	v_mfma_f32_16x16x32_bf16 v[66:69], v[154:157], v[200:203], v[66:69]
	v_mfma_f32_16x16x32_bf16 v[118:121], v[150:153], v[166:169], v[118:121]
	v_mfma_f32_16x16x32_bf16 v[110:113], v[158:161], v[166:169], v[110:113]
	v_mfma_f32_16x16x32_bf16 v[102:105], v[150:153], v[184:187], v[102:105]
	v_mfma_f32_16x16x32_bf16 v[94:97], v[158:161], v[184:187], v[94:97]
	v_mfma_f32_16x16x32_bf16 v[86:89], v[150:153], v[192:195], v[86:89]
	v_mfma_f32_16x16x32_bf16 v[78:81], v[158:161], v[192:195], v[78:81]
	v_mfma_f32_16x16x32_bf16 v[70:73], v[150:153], v[204:207], v[70:73]
	v_mfma_f32_16x16x32_bf16 v[66:69], v[158:161], v[204:207], v[66:69]
	s_setprio 0
	s_barrier
	s_mov_b32 m0, s48
	v_lshl_add_u64 v[196:197], s[42:43], 0, v[0:1]
	s_add_u32 s68, s42, 0x40000
	global_load_lds_dwordx4 v[196:197], off
	v_lshl_add_u64 v[208:209], s[42:43], 0, v[178:179]
	s_mov_b32 m0, s49
	s_addc_u32 s69, s43, 0
	global_load_lds_dwordx4 v178, s[42:43]
	v_lshl_add_u64 v[210:211], s[68:69], 0, v[0:1]
	s_mov_b32 m0, s50
	v_lshl_add_u64 v[212:213], s[44:45], 0, v[176:177]
	global_load_lds_dwordx4 v[210:211], off
	s_mov_b32 m0, s51
	s_nop 0
	global_load_lds_dwordx4 v178, s[68:69]
	v_lshl_add_u64 v[210:211], s[44:45], 0, v[174:175]
	s_mov_b32 m0, s52
	s_nop 0
	global_load_lds_dwordx4 v174, s[44:45]
	s_mov_b32 m0, s53
	s_nop 0
	global_load_lds_dwordx4 v176, s[44:45]
	ds_read_b128 v[162:165], v198 offset:17408
	ds_read_b128 v[166:169], v198 offset:18432
	ds_read_b128 v[170:173], v198 offset:19456
	ds_read_b128 v[184:187], v198 offset:20480
	ds_read_b128 v[188:191], v198 offset:21504
	ds_read_b128 v[192:195], v198 offset:22528
	ds_read_b128 v[200:203], v198 offset:23552
	ds_read_b128 v[204:207], v198 offset:24576
	s_waitcnt vmcnt(8)
	s_waitcnt lgkmcnt(0)
	s_barrier
; #define PG8_STAGE(bufoff, gbase, voff) do { _Pragma("unroll") for (int _i = 0; _i < 2; ++_i) \
;         __builtin_amdgcn_global_load_lds((const GAS unsigned*)((const GAS char*)(gbase) + (voff)[_i]), (LAS unsigned*)(lds + (bufoff) + ldsw + _i * 8192), 16, 0, 0); } while (0)
; #define PG8_LDA(dst, b, h) do { _Pragma("unroll") for (int m = 0; m < 4; ++m) _Pragma("unroll") for (int k = 0; k < 2; ++k) dst[m][k] = *(const LAS bf16x8*)(lds + PG8_SA(b, h) + aoff + m * 2048 + k * 1024); } while (0)
; #define PG8_LDB(dst, b, h) do { _Pragma("unroll") for (int n = 0; n < 2; ++n) _Pragma("unroll") for (int k = 0; k < 2; ++k) dst[n][k] = *(const LAS bf16x8*)(lds + PG8_SB(b, h) + boff + n * 2048 + k * 1024); } while (0)
; #define PG8_MMA(ai, bj, At, Bt) do { __builtin_amdgcn_s_setprio(1); _Pragma("unroll") for (int m = 0; m < 4; ++m) _Pragma("unroll") for (int n = 0; n < 2; ++n) _Pragma("unroll") for (int k = 0; k < 2; ++k) \
;         acc[ai][bj][m][n] = __builtin_amdgcn_mfma_f32_16x16x32_bf16(Bt[n][k], At[m][k], acc[ai][bj][m][n], 0, 0, 0); __builtin_amdgcn_s_setprio(0); } while (0)
; #define PG8_WAIT_V(n) asm volatile("s_waitcnt vmcnt(" #n ")" ::: "memory")
; #define PG8_WAIT_L(n) asm volatile("s_waitcnt lgkmcnt(" #n ")" ::: "memory")
; #define PG8_BAR __builtin_amdgcn_s_barrier()
; #define PG8_SCHED __builtin_amdgcn_sched_barrier(0)
; template <class Epi, class Sched, bool ALIGN_EPI>
; __device__ __forceinline__ void gemm_phase(LAS unsigned char* lds, const Gemm g, const Sched& S, const Epi& E, int wave_id) {
;     ...
;             PG8_WAIT_V(8); PG8_WAIT_L(0); PG8_BAR; PG8_MMA(1, 0, At, B0); PG8_MMA(1, 1, At, B1); PG8_BAR; PG8_SCHED;
;             PG8_LDB(B0, 1, 0); PG8_LDB(B1, 1, 1); PG8_SCHED; PG8_LDA(At, 1, 0); PG8_STAGE(PG8_SA(0, 1), a2 + hsA, voffA);
;             PG8_WAIT_V(8); PG8_WAIT_L(0); PG8_BAR; PG8_MMA(0, 0, At, B0); PG8_MMA(0, 1, At, B1); PG8_BAR; PG8_SCHED;
	s_setprio 1
	s_waitcnt lgkmcnt(0)
	v_mfma_f32_16x16x32_bf16 v[62:65], v[130:133], v[162:165], v[62:65]
	v_mfma_f32_16x16x32_bf16 v[58:61], v[138:141], v[162:165], v[58:61]
	v_mfma_f32_16x16x32_bf16 v[50:53], v[130:133], v[170:173], v[50:53]
	v_mfma_f32_16x16x32_bf16 v[42:45], v[138:141], v[170:173], v[42:45]
	v_mfma_f32_16x16x32_bf16 v[34:37], v[130:133], v[188:191], v[34:37]
	v_mfma_f32_16x16x32_bf16 v[26:29], v[138:141], v[188:191], v[26:29]
	v_mfma_f32_16x16x32_bf16 v[18:21], v[130:133], v[200:203], v[18:21]
	v_mfma_f32_16x16x32_bf16 v[10:13], v[138:141], v[200:203], v[10:13]
	v_mfma_f32_16x16x32_bf16 v[62:65], v[134:137], v[166:169], v[62:65]
	v_mfma_f32_16x16x32_bf16 v[58:61], v[142:145], v[166:169], v[58:61]
	v_mfma_f32_16x16x32_bf16 v[50:53], v[134:137], v[184:187], v[50:53]
	v_mfma_f32_16x16x32_bf16 v[42:45], v[142:145], v[184:187], v[42:45]
	v_mfma_f32_16x16x32_bf16 v[34:37], v[134:137], v[192:195], v[34:37]
	v_mfma_f32_16x16x32_bf16 v[26:29], v[142:145], v[192:195], v[26:29]
	v_mfma_f32_16x16x32_bf16 v[18:21], v[134:137], v[204:207], v[18:21]
	v_mfma_f32_16x16x32_bf16 v[10:13], v[142:145], v[204:207], v[10:13]
	s_setprio 0
	s_setprio 1
	v_mfma_f32_16x16x32_bf16 v[54:57], v[146:149], v[162:165], v[54:57]
	v_mfma_f32_16x16x32_bf16 v[46:49], v[154:157], v[162:165], v[46:49]
	v_mfma_f32_16x16x32_bf16 v[38:41], v[146:149], v[170:173], v[38:41]
	v_mfma_f32_16x16x32_bf16 v[30:33], v[154:157], v[170:173], v[30:33]
	v_mfma_f32_16x16x32_bf16 v[22:25], v[146:149], v[188:191], v[22:25]
	v_mfma_f32_16x16x32_bf16 v[14:17], v[154:157], v[188:191], v[14:17]
	v_mfma_f32_16x16x32_bf16 v[6:9], v[146:149], v[200:203], v[6:9]
	v_mfma_f32_16x16x32_bf16 v[2:5], v[154:157], v[200:203], v[2:5]
	v_mfma_f32_16x16x32_bf16 v[54:57], v[150:153], v[166:169], v[54:57]
	v_mfma_f32_16x16x32_bf16 v[46:49], v[158:161], v[166:169], v[46:49]
	v_mfma_f32_16x16x32_bf16 v[38:41], v[150:153], v[184:187], v[38:41]
	v_mfma_f32_16x16x32_bf16 v[30:33], v[158:161], v[184:187], v[30:33]
	v_mfma_f32_16x16x32_bf16 v[22:25], v[150:153], v[192:195], v[22:25]
	v_mfma_f32_16x16x32_bf16 v[14:17], v[158:161], v[192:195], v[14:17]
	v_mfma_f32_16x16x32_bf16 v[6:9], v[150:153], v[204:207], v[6:9]
	v_mfma_f32_16x16x32_bf16 v[2:5], v[158:161], v[204:207], v[2:5]
	s_setprio 0
	s_barrier
	s_add_u32 s44, s44, 0x40000
	s_addc_u32 s45, s45, 0
	s_mov_b32 m0, s54
	s_nop 0
	global_load_lds_dwordx4 v174, s[44:45]
	s_mov_b32 m0, s55
	s_nop 0
	global_load_lds_dwordx4 v176, s[44:45]
	v_add_u32_e32 v142, 0x18400, v199
	v_add_u32_e32 v158, 0x1c400, v199
	ds_read_b128 v[130:133], v142
	ds_read_b128 v[134:137], v142 offset:1024
	ds_read_b128 v[138:141], v142 offset:2048
	ds_read_b128 v[142:145], v142 offset:3072
	ds_read_b128 v[146:149], v158
	ds_read_b128 v[150:153], v158 offset:1024
	ds_read_b128 v[154:157], v158 offset:2048
	ds_read_b128 v[158:161], v158 offset:3072
	ds_read_b128 v[162:165], v198 offset:33792
	ds_read_b128 v[166:169], v198 offset:34816
	ds_read_b128 v[170:173], v198 offset:35840
	ds_read_b128 v[184:187], v198 offset:36864
	ds_read_b128 v[188:191], v198 offset:37888
	ds_read_b128 v[192:195], v198 offset:38912
	ds_read_b128 v[200:203], v198 offset:39936
	ds_read_b128 v[204:207], v198 offset:40960
	s_waitcnt vmcnt(8)
	s_waitcnt lgkmcnt(0)
	s_barrier
	s_setprio 1
	s_waitcnt lgkmcnt(0)
	v_mfma_f32_16x16x32_bf16 v[126:129], v[130:133], v[162:165], v[126:129]
	v_mfma_f32_16x16x32_bf16 v[122:125], v[138:141], v[162:165], v[122:125]
	v_mfma_f32_16x16x32_bf16 v[114:117], v[130:133], v[170:173], v[114:117]
	v_mfma_f32_16x16x32_bf16 v[106:109], v[138:141], v[170:173], v[106:109]
	v_mfma_f32_16x16x32_bf16 v[98:101], v[130:133], v[188:191], v[98:101]
	v_mfma_f32_16x16x32_bf16 v[90:93], v[138:141], v[188:191], v[90:93]
	v_mfma_f32_16x16x32_bf16 v[82:85], v[130:133], v[200:203], v[82:85]
	v_mfma_f32_16x16x32_bf16 v[74:77], v[138:141], v[200:203], v[74:77]
	v_mfma_f32_16x16x32_bf16 v[126:129], v[134:137], v[166:169], v[126:129]
	v_mfma_f32_16x16x32_bf16 v[122:125], v[142:145], v[166:169], v[122:125]
	v_mfma_f32_16x16x32_bf16 v[114:117], v[134:137], v[184:187], v[114:117]
	v_mfma_f32_16x16x32_bf16 v[106:109], v[142:145], v[184:187], v[106:109]
	v_mfma_f32_16x16x32_bf16 v[98:101], v[134:137], v[192:195], v[98:101]
	v_mfma_f32_16x16x32_bf16 v[90:93], v[142:145], v[192:195], v[90:93]
	v_mfma_f32_16x16x32_bf16 v[82:85], v[134:137], v[204:207], v[82:85]
	v_mfma_f32_16x16x32_bf16 v[74:77], v[142:145], v[204:207], v[74:77]
	s_setprio 0
	s_setprio 1
	v_mfma_f32_16x16x32_bf16 v[118:121], v[146:149], v[162:165], v[118:121]
	v_mfma_f32_16x16x32_bf16 v[110:113], v[154:157], v[162:165], v[110:113]
	v_mfma_f32_16x16x32_bf16 v[102:105], v[146:149], v[170:173], v[102:105]
	v_mfma_f32_16x16x32_bf16 v[94:97], v[154:157], v[170:173], v[94:97]
	v_mfma_f32_16x16x32_bf16 v[86:89], v[146:149], v[188:191], v[86:89]
	v_mfma_f32_16x16x32_bf16 v[78:81], v[154:157], v[188:191], v[78:81]
	v_mfma_f32_16x16x32_bf16 v[70:73], v[146:149], v[200:203], v[70:73]
	v_mfma_f32_16x16x32_bf16 v[66:69], v[154:157], v[200:203], v[66:69]
	v_mfma_f32_16x16x32_bf16 v[118:121], v[150:153], v[166:169], v[118:121]
	v_mfma_f32_16x16x32_bf16 v[110:113], v[158:161], v[166:169], v[110:113]
	v_mfma_f32_16x16x32_bf16 v[102:105], v[150:153], v[184:187], v[102:105]
	v_mfma_f32_16x16x32_bf16 v[94:97], v[158:161], v[184:187], v[94:97]
	v_mfma_f32_16x16x32_bf16 v[86:89], v[150:153], v[192:195], v[86:89]
	v_mfma_f32_16x16x32_bf16 v[78:81], v[158:161], v[192:195], v[78:81]
	v_mfma_f32_16x16x32_bf16 v[70:73], v[150:153], v[204:207], v[70:73]
	v_mfma_f32_16x16x32_bf16 v[66:69], v[158:161], v[204:207], v[66:69]
	s_setprio 0
	s_barrier
; #define PG8_STAGE(bufoff, gbase, voff) do { _Pragma("unroll") for (int _i = 0; _i < 2; ++_i) \
;         __builtin_amdgcn_global_load_lds((const GAS unsigned*)((const GAS char*)(gbase) + (voff)[_i]), (LAS unsigned*)(lds + (bufoff) + ldsw + _i * 8192), 16, 0, 0); } while (0)
; #define PG8_LDA(dst, b, h) do { _Pragma("unroll") for (int m = 0; m < 4; ++m) _Pragma("unroll") for (int k = 0; k < 2; ++k) dst[m][k] = *(const LAS bf16x8*)(lds + PG8_SA(b, h) + aoff + m * 2048 + k * 1024); } while (0)
; #define PG8_MMA(ai, bj, At, Bt) do { __builtin_amdgcn_s_setprio(1); _Pragma("unroll") for (int m = 0; m < 4; ++m) _Pragma("unroll") for (int n = 0; n < 2; ++n) _Pragma("unroll") for (int k = 0; k < 2; ++k) \
;         acc[ai][bj][m][n] = __builtin_amdgcn_mfma_f32_16x16x32_bf16(Bt[n][k], At[m][k], acc[ai][bj][m][n], 0, 0, 0); __builtin_amdgcn_s_setprio(0); } while (0)
; #define PG8_WAIT_V(n) asm volatile("s_waitcnt vmcnt(" #n ")" ::: "memory")
; #define PG8_WAIT_L(n) asm volatile("s_waitcnt lgkmcnt(" #n ")" ::: "memory")
; #define PG8_BAR __builtin_amdgcn_s_barrier()
; #define PG8_SCHED __builtin_amdgcn_sched_barrier(0)
; template <class Epi, class Sched, bool ALIGN_EPI>
; __device__ __forceinline__ void gemm_phase(LAS unsigned char* lds, const Gemm g, const Sched& S, const Epi& E, int wave_id) {
;     ...
;             PG8_LDA(At, 1, 1); PG8_STAGE(PG8_SB(1, 0), b3, voffB); PG8_STAGE(PG8_SB(1, 1), b3 + hsB, voffB); PG8_STAGE(PG8_SA(1, 0), a3, voffA);
;             PG8_WAIT_V(8); PG8_WAIT_L(0); PG8_BAR; PG8_MMA(1, 0, At, B0); PG8_MMA(1, 1, At, B1); PG8_BAR; PG8_SCHED;
;         }
	s_mov_b32 m0, s58
	v_lshl_add_u64 v[196:197], v[196:197], 0, s[92:93]
	s_add_u32 s42, s42, 0x40080
	global_load_lds_dwordx4 v[196:197], off
	v_lshl_add_u64 v[196:197], v[208:209], 0, s[92:93]
	s_mov_b32 m0, s59
	s_addc_u32 s43, s43, 0
	global_load_lds_dwordx4 v[196:197], off
	v_lshl_add_u64 v[196:197], s[42:43], 0, v[0:1]
	s_mov_b32 m0, s62
	s_nop 0
	global_load_lds_dwordx4 v[196:197], off
	s_mov_b32 m0, s63
	s_nop 0
	global_load_lds_dwordx4 v178, s[42:43]
	v_lshl_add_u64 v[196:197], v[210:211], 0, s[92:93]
	s_mov_b32 m0, s60
	s_nop 0
	global_load_lds_dwordx4 v[196:197], off
	v_lshl_add_u64 v[196:197], v[212:213], 0, s[92:93]
	s_mov_b32 m0, s61
	s_nop 0
	global_load_lds_dwordx4 v[196:197], off
	ds_read_b128 v[162:165], v198 offset:50176
	ds_read_b128 v[166:169], v198 offset:51200
	ds_read_b128 v[170:173], v198 offset:52224
	ds_read_b128 v[184:187], v198 offset:53248
	ds_read_b128 v[188:191], v198 offset:54272
	ds_read_b128 v[192:195], v198 offset:55296
	ds_read_b128 v[200:203], v198 offset:56320
	ds_read_b128 v[204:207], v198 offset:57344
	s_waitcnt vmcnt(8)
	s_waitcnt lgkmcnt(0)
	s_barrier
	s_setprio 1
	s_waitcnt lgkmcnt(0)
	v_mfma_f32_16x16x32_bf16 v[62:65], v[130:133], v[162:165], v[62:65]
	v_mfma_f32_16x16x32_bf16 v[58:61], v[138:141], v[162:165], v[58:61]
	v_mfma_f32_16x16x32_bf16 v[50:53], v[130:133], v[170:173], v[50:53]
	v_mfma_f32_16x16x32_bf16 v[42:45], v[138:141], v[170:173], v[42:45]
	v_mfma_f32_16x16x32_bf16 v[34:37], v[130:133], v[188:191], v[34:37]
	v_mfma_f32_16x16x32_bf16 v[26:29], v[138:141], v[188:191], v[26:29]
	v_mfma_f32_16x16x32_bf16 v[18:21], v[130:133], v[200:203], v[18:21]
	v_mfma_f32_16x16x32_bf16 v[10:13], v[138:141], v[200:203], v[10:13]
	v_mfma_f32_16x16x32_bf16 v[62:65], v[134:137], v[166:169], v[62:65]
	v_mfma_f32_16x16x32_bf16 v[58:61], v[142:145], v[166:169], v[58:61]
	v_mfma_f32_16x16x32_bf16 v[50:53], v[134:137], v[184:187], v[50:53]
	v_mfma_f32_16x16x32_bf16 v[42:45], v[142:145], v[184:187], v[42:45]
	v_mfma_f32_16x16x32_bf16 v[34:37], v[134:137], v[192:195], v[34:37]
	v_mfma_f32_16x16x32_bf16 v[26:29], v[142:145], v[192:195], v[26:29]
	v_mfma_f32_16x16x32_bf16 v[18:21], v[134:137], v[204:207], v[18:21]
	v_mfma_f32_16x16x32_bf16 v[10:13], v[142:145], v[204:207], v[10:13]
	s_setprio 0
	s_setprio 1
	v_mfma_f32_16x16x32_bf16 v[54:57], v[146:149], v[162:165], v[54:57]
	v_mfma_f32_16x16x32_bf16 v[46:49], v[154:157], v[162:165], v[46:49]
	v_mfma_f32_16x16x32_bf16 v[38:41], v[146:149], v[170:173], v[38:41]
	v_mfma_f32_16x16x32_bf16 v[30:33], v[154:157], v[170:173], v[30:33]
	v_mfma_f32_16x16x32_bf16 v[22:25], v[146:149], v[188:191], v[22:25]
	v_mfma_f32_16x16x32_bf16 v[14:17], v[154:157], v[188:191], v[14:17]
	v_mfma_f32_16x16x32_bf16 v[6:9], v[146:149], v[200:203], v[6:9]
	v_mfma_f32_16x16x32_bf16 v[2:5], v[154:157], v[200:203], v[2:5]
	v_mfma_f32_16x16x32_bf16 v[54:57], v[150:153], v[166:169], v[54:57]
	v_mfma_f32_16x16x32_bf16 v[46:49], v[158:161], v[166:169], v[46:49]
	v_mfma_f32_16x16x32_bf16 v[38:41], v[150:153], v[184:187], v[38:41]
	v_mfma_f32_16x16x32_bf16 v[30:33], v[158:161], v[184:187], v[30:33]
	v_mfma_f32_16x16x32_bf16 v[22:25], v[150:153], v[192:195], v[22:25]
	v_mfma_f32_16x16x32_bf16 v[14:17], v[158:161], v[192:195], v[14:17]
	v_mfma_f32_16x16x32_bf16 v[6:9], v[150:153], v[204:207], v[6:9]
	v_mfma_f32_16x16x32_bf16 v[2:5], v[158:161], v[204:207], v[2:5]
	s_setprio 0
	s_barrier
	s_add_i32 s67, s67, 2
	s_add_u32 s39, s39, 0x100
	s_addc_u32 s66, s66, 0
	s_add_u32 s40, s40, 0x100
	s_addc_u32 s41, s41, 0
	s_cmp_gt_u32 s67, 13
	s_cbranch_scc0 .LBB0_1837
	s_and_b64 vcc, exec, s[22:23]
	s_cbranch_vccz .LBB0_1840
	s_barrier

; #define GAS __attribute__((address_space(1)))
; #define PG8_STAGE(bufoff, gbase, voff) do { _Pragma("unroll") for (int _i = 0; _i < 2; ++_i) \
;         __builtin_amdgcn_global_load_lds((const GAS unsigned*)((const GAS char*)(gbase) + (voff)[_i]), (LAS unsigned*)(lds + (bufoff) + ldsw + _i * 8192), 16, 0, 0); } while (0)
; #define PG8_LDA(dst, b, h) do { _Pragma("unroll") for (int m = 0; m < 4; ++m) _Pragma("unroll") for (int k = 0; k < 2; ++k) dst[m][k] = *(const LAS bf16x8*)(lds + PG8_SA(b, h) + aoff + m * 2048 + k * 1024); } while (0)
; #define PG8_LDB(dst, b, h) do { _Pragma("unroll") for (int n = 0; n < 2; ++n) _Pragma("unroll") for (int k = 0; k < 2; ++k) dst[n][k] = *(const LAS bf16x8*)(lds + PG8_SB(b, h) + boff + n * 2048 + k * 1024); } while (0)
; #define PG8_MMA(ai, bj, At, Bt) do { __builtin_amdgcn_s_setprio(1); _Pragma("unroll") for (int m = 0; m < 4; ++m) _Pragma("unroll") for (int n = 0; n < 2; ++n) _Pragma("unroll") for (int k = 0; k < 2; ++k) \
;         acc[ai][bj][m][n] = __builtin_amdgcn_mfma_f32_16x16x32_bf16(Bt[n][k], At[m][k], acc[ai][bj][m][n], 0, 0, 0); __builtin_amdgcn_s_setprio(0); } while (0)
; #define PG8_WAIT_V(n) asm volatile("s_waitcnt vmcnt(" #n ")" ::: "memory")
; #define PG8_WAIT_L(n) asm volatile("s_waitcnt lgkmcnt(" #n ")" ::: "memory")
; template <class Epi, class Sched, bool ALIGN_EPI>
; __device__ __forceinline__ void gemm_phase(LAS unsigned char* lds, const Gemm g, const Sched& S, const Epi& E, int wave_id) {
;     ...
;         for (int t = 0; t < nt; t += 2) {
;             const bool last = (t == nt - 2);
;             const GAS char* a1 = cA + (size_t)(t + 1) * kstep;
;             const GAS char* a2 = last ? nA : cA + (size_t)(t + 2) * kstep; const GAS char* b2 = last ? nB : cB + (size_t)(t + 2) * kstep;
;             const GAS char* a3 = a2 + kstep; const GAS char* b3 = b2 + kstep;
;             PG8_LDB(B0, 0, 0); PG8_LDB(B1, 0, 1); PG8_SCHED; PG8_LDA(At, 0, 0); PG8_STAGE(PG8_SA(1, 1), a1 + hsA, voffA);
;             PG8_WAIT_V(8); PG8_WAIT_L(0); PG8_BAR; PG8_MMA(0, 0, At, B0); PG8_MMA(0, 1, At, B1); PG8_BAR; PG8_SCHED;
;             PG8_LDA(At, 0, 1); PG8_STAGE(PG8_SB(0, 0), b2, voffB); PG8_STAGE(PG8_SB(0, 1), b2 + hsB, voffB); PG8_STAGE(PG8_SA(0, 0), a2, voffA);
;             PG8_WAIT_V(8); PG8_WAIT_L(0); PG8_BAR; PG8_MMA(1, 0, At, B0); PG8_MMA(1, 1, At, B1); PG8_BAR; PG8_SCHED;
.LBB0_2565:
	s_add_u32 s28, s26, 0xfffc0080
	s_addc_u32 s29, s27, -1
	s_cmp_eq_u32 s60, 12
	s_cselect_b32 s31, s19, s29
	s_cselect_b32 s30, s33, s28
	s_cselect_b32 s29, s17, s59
	s_cselect_b32 s28, s57, s58
	s_add_i32 m0, s40, 0xc400
	s_nop 0
	global_load_lds_dwordx4 v138, s[26:27]
	s_add_i32 m0, s40, 0xe400
	s_nop 0
	global_load_lds_dwordx4 v136, s[26:27]
	v_add_u32_e32 v154, 0x10400, v153
	v_add_u32_e32 v170, 0x14400, v153
	ds_read_b128 v[140:143], v154
	ds_read_b128 v[144:147], v154 offset:1024
	ds_read_b128 v[148:151], v154 offset:2048
	ds_read_b128 v[154:157], v154 offset:3072
	ds_read_b128 v[158:161], v170
	ds_read_b128 v[162:165], v170 offset:1024
	ds_read_b128 v[166:169], v170 offset:2048
	ds_read_b128 v[170:173], v170 offset:3072
	ds_read_b128 v[174:177], v152 offset:1024
	ds_read_b128 v[178:181], v152 offset:2048
	ds_read_b128 v[182:185], v152 offset:3072
	ds_read_b128 v[186:189], v152 offset:4096
	ds_read_b128 v[190:193], v152 offset:5120
	ds_read_b128 v[194:197], v152 offset:6144
	ds_read_b128 v[198:201], v152 offset:7168
	ds_read_b128 v[202:205], v152 offset:8192
	s_waitcnt vmcnt(8)
	s_waitcnt lgkmcnt(0)
	s_barrier
	s_setprio 1
	s_waitcnt lgkmcnt(0)
	v_mfma_f32_16x16x32_bf16 v[126:129], v[140:143], v[174:177], v[126:129]
	v_mfma_f32_16x16x32_bf16 v[122:125], v[148:151], v[174:177], v[122:125]
	v_mfma_f32_16x16x32_bf16 v[110:113], v[140:143], v[182:185], v[110:113]
	v_mfma_f32_16x16x32_bf16 v[106:109], v[148:151], v[182:185], v[106:109]
	v_mfma_f32_16x16x32_bf16 v[94:97], v[140:143], v[190:193], v[94:97]
	v_mfma_f32_16x16x32_bf16 v[90:93], v[148:151], v[190:193], v[90:93]
	v_mfma_f32_16x16x32_bf16 v[78:81], v[140:143], v[198:201], v[78:81]
	v_mfma_f32_16x16x32_bf16 v[74:77], v[148:151], v[198:201], v[74:77]
	v_mfma_f32_16x16x32_bf16 v[126:129], v[144:147], v[178:181], v[126:129]
	v_mfma_f32_16x16x32_bf16 v[122:125], v[154:157], v[178:181], v[122:125]
	v_mfma_f32_16x16x32_bf16 v[110:113], v[144:147], v[186:189], v[110:113]
	v_mfma_f32_16x16x32_bf16 v[106:109], v[154:157], v[186:189], v[106:109]
	v_mfma_f32_16x16x32_bf16 v[94:97], v[144:147], v[194:197], v[94:97]
	v_mfma_f32_16x16x32_bf16 v[90:93], v[154:157], v[194:197], v[90:93]
	v_mfma_f32_16x16x32_bf16 v[78:81], v[144:147], v[202:205], v[78:81]
	v_mfma_f32_16x16x32_bf16 v[74:77], v[154:157], v[202:205], v[74:77]
	s_setprio 0
	s_setprio 1
	v_mfma_f32_16x16x32_bf16 v[118:121], v[158:161], v[174:177], v[118:121]
	v_mfma_f32_16x16x32_bf16 v[114:117], v[166:169], v[174:177], v[114:117]
	v_mfma_f32_16x16x32_bf16 v[102:105], v[158:161], v[182:185], v[102:105]
	v_mfma_f32_16x16x32_bf16 v[98:101], v[166:169], v[182:185], v[98:101]
	v_mfma_f32_16x16x32_bf16 v[86:89], v[158:161], v[190:193], v[86:89]
	v_mfma_f32_16x16x32_bf16 v[82:85], v[166:169], v[190:193], v[82:85]
	v_mfma_f32_16x16x32_bf16 v[70:73], v[158:161], v[198:201], v[70:73]
	v_mfma_f32_16x16x32_bf16 v[66:69], v[166:169], v[198:201], v[66:69]
	v_mfma_f32_16x16x32_bf16 v[118:121], v[162:165], v[178:181], v[118:121]
	v_mfma_f32_16x16x32_bf16 v[114:117], v[170:173], v[178:181], v[114:117]
	v_mfma_f32_16x16x32_bf16 v[102:105], v[162:165], v[186:189], v[102:105]
	v_mfma_f32_16x16x32_bf16 v[98:101], v[170:173], v[186:189], v[98:101]
	v_mfma_f32_16x16x32_bf16 v[86:89], v[162:165], v[194:197], v[86:89]
	v_mfma_f32_16x16x32_bf16 v[82:85], v[170:173], v[194:197], v[82:85]
	v_mfma_f32_16x16x32_bf16 v[70:73], v[162:165], v[202:205], v[70:73]
	v_mfma_f32_16x16x32_bf16 v[66:69], v[170:173], v[202:205], v[66:69]
	s_setprio 0
	s_barrier
	s_mov_b32 m0, s25
	v_lshl_add_u64 v[206:207], s[28:29], 0, v[0:1]
	s_add_u32 s62, s28, 0x40000
	global_load_lds_dwordx4 v[206:207], off
	v_lshl_add_u64 v[208:209], s[28:29], 0, v[130:131]
	s_mov_b32 m0, s41
	s_addc_u32 s63, s29, 0
	global_load_lds_dwordx4 v130, s[28:29]
	v_lshl_add_u64 v[210:211], s[62:63], 0, v[0:1]
	s_mov_b32 m0, s42
	v_lshl_add_u64 v[212:213], s[30:31], 0, v[132:133]
	global_load_lds_dwordx4 v[210:211], off
	s_mov_b32 m0, s43
	s_nop 0
	global_load_lds_dwordx4 v130, s[62:63]
	v_lshl_add_u64 v[210:211], s[30:31], 0, v[134:135]
	s_mov_b32 m0, s44
	s_nop 0
	global_load_lds_dwordx4 v134, s[30:31]
	s_mov_b32 m0, s45
	s_nop 0
	global_load_lds_dwordx4 v132, s[30:31]
	ds_read_b128 v[174:177], v152 offset:17408
	ds_read_b128 v[178:181], v152 offset:18432
	ds_read_b128 v[182:185], v152 offset:19456
	ds_read_b128 v[186:189], v152 offset:20480
	ds_read_b128 v[190:193], v152 offset:21504
	ds_read_b128 v[194:197], v152 offset:22528
	ds_read_b128 v[198:201], v152 offset:23552
	ds_read_b128 v[202:205], v152 offset:24576
	s_waitcnt vmcnt(8)
	s_waitcnt lgkmcnt(0)
	s_barrier
; #define PG8_STAGE(bufoff, gbase, voff) do { _Pragma("unroll") for (int _i = 0; _i < 2; ++_i) \
;         __builtin_amdgcn_global_load_lds((const GAS unsigned*)((const GAS char*)(gbase) + (voff)[_i]), (LAS unsigned*)(lds + (bufoff) + ldsw + _i * 8192), 16, 0, 0); } while (0)
; #define PG8_LDA(dst, b, h) do { _Pragma("unroll") for (int m = 0; m < 4; ++m) _Pragma("unroll") for (int k = 0; k < 2; ++k) dst[m][k] = *(const LAS bf16x8*)(lds + PG8_SA(b, h) + aoff + m * 2048 + k * 1024); } while (0)
; #define PG8_LDB(dst, b, h) do { _Pragma("unroll") for (int n = 0; n < 2; ++n) _Pragma("unroll") for (int k = 0; k < 2; ++k) dst[n][k] = *(const LAS bf16x8*)(lds + PG8_SB(b, h) + boff + n * 2048 + k * 1024); } while (0)
; #define PG8_MMA(ai, bj, At, Bt) do { __builtin_amdgcn_s_setprio(1); _Pragma("unroll") for (int m = 0; m < 4; ++m) _Pragma("unroll") for (int n = 0; n < 2; ++n) _Pragma("unroll") for (int k = 0; k < 2; ++k) \
;         acc[ai][bj][m][n] = __builtin_amdgcn_mfma_f32_16x16x32_bf16(Bt[n][k], At[m][k], acc[ai][bj][m][n], 0, 0, 0); __builtin_amdgcn_s_setprio(0); } while (0)
; #define PG8_WAIT_V(n) asm volatile("s_waitcnt vmcnt(" #n ")" ::: "memory")
; #define PG8_WAIT_L(n) asm volatile("s_waitcnt lgkmcnt(" #n ")" ::: "memory")
; #define PG8_BAR __builtin_amdgcn_s_barrier()
; #define PG8_SCHED __builtin_amdgcn_sched_barrier(0)
; template <class Epi, class Sched, bool ALIGN_EPI>
; __device__ __forceinline__ void gemm_phase(LAS unsigned char* lds, const Gemm g, const Sched& S, const Epi& E, int wave_id) {
;     ...
;             PG8_WAIT_V(8); PG8_WAIT_L(0); PG8_BAR; PG8_MMA(1, 0, At, B0); PG8_MMA(1, 1, At, B1); PG8_BAR; PG8_SCHED;
;             PG8_LDB(B0, 1, 0); PG8_LDB(B1, 1, 1); PG8_SCHED; PG8_LDA(At, 1, 0); PG8_STAGE(PG8_SA(0, 1), a2 + hsA, voffA);
;             PG8_WAIT_V(8); PG8_WAIT_L(0); PG8_BAR; PG8_MMA(0, 0, At, B0); PG8_MMA(0, 1, At, B1); PG8_BAR; PG8_SCHED;
	s_setprio 1
	s_waitcnt lgkmcnt(0)
	v_mfma_f32_16x16x32_bf16 v[62:65], v[140:143], v[174:177], v[62:65]
	v_mfma_f32_16x16x32_bf16 v[58:61], v[148:151], v[174:177], v[58:61]
	v_mfma_f32_16x16x32_bf16 v[46:49], v[140:143], v[182:185], v[46:49]
	v_mfma_f32_16x16x32_bf16 v[42:45], v[148:151], v[182:185], v[42:45]
	v_mfma_f32_16x16x32_bf16 v[30:33], v[140:143], v[190:193], v[30:33]
	v_mfma_f32_16x16x32_bf16 v[26:29], v[148:151], v[190:193], v[26:29]
	v_mfma_f32_16x16x32_bf16 v[14:17], v[140:143], v[198:201], v[14:17]
	v_mfma_f32_16x16x32_bf16 v[10:13], v[148:151], v[198:201], v[10:13]
	v_mfma_f32_16x16x32_bf16 v[62:65], v[144:147], v[178:181], v[62:65]
	v_mfma_f32_16x16x32_bf16 v[58:61], v[154:157], v[178:181], v[58:61]
	v_mfma_f32_16x16x32_bf16 v[46:49], v[144:147], v[186:189], v[46:49]
	v_mfma_f32_16x16x32_bf16 v[42:45], v[154:157], v[186:189], v[42:45]
	v_mfma_f32_16x16x32_bf16 v[30:33], v[144:147], v[194:197], v[30:33]
	v_mfma_f32_16x16x32_bf16 v[26:29], v[154:157], v[194:197], v[26:29]
	v_mfma_f32_16x16x32_bf16 v[14:17], v[144:147], v[202:205], v[14:17]
	v_mfma_f32_16x16x32_bf16 v[10:13], v[154:157], v[202:205], v[10:13]
	s_setprio 0
	s_setprio 1
	v_mfma_f32_16x16x32_bf16 v[54:57], v[158:161], v[174:177], v[54:57]
	v_mfma_f32_16x16x32_bf16 v[50:53], v[166:169], v[174:177], v[50:53]
	v_mfma_f32_16x16x32_bf16 v[38:41], v[158:161], v[182:185], v[38:41]
	v_mfma_f32_16x16x32_bf16 v[34:37], v[166:169], v[182:185], v[34:37]
	v_mfma_f32_16x16x32_bf16 v[22:25], v[158:161], v[190:193], v[22:25]
	v_mfma_f32_16x16x32_bf16 v[18:21], v[166:169], v[190:193], v[18:21]
	v_mfma_f32_16x16x32_bf16 v[6:9], v[158:161], v[198:201], v[6:9]
	v_mfma_f32_16x16x32_bf16 v[2:5], v[166:169], v[198:201], v[2:5]
	v_mfma_f32_16x16x32_bf16 v[54:57], v[162:165], v[178:181], v[54:57]
	v_mfma_f32_16x16x32_bf16 v[50:53], v[170:173], v[178:181], v[50:53]
	v_mfma_f32_16x16x32_bf16 v[38:41], v[162:165], v[186:189], v[38:41]
	v_mfma_f32_16x16x32_bf16 v[34:37], v[170:173], v[186:189], v[34:37]
	v_mfma_f32_16x16x32_bf16 v[22:25], v[162:165], v[194:197], v[22:25]
	v_mfma_f32_16x16x32_bf16 v[18:21], v[170:173], v[194:197], v[18:21]
	v_mfma_f32_16x16x32_bf16 v[6:9], v[162:165], v[202:205], v[6:9]
	v_mfma_f32_16x16x32_bf16 v[2:5], v[170:173], v[202:205], v[2:5]
	s_setprio 0
	s_barrier
	s_add_u32 s30, s30, 0x40000
	s_addc_u32 s31, s31, 0
	s_mov_b32 m0, s46
	s_nop 0
	global_load_lds_dwordx4 v134, s[30:31]
	s_mov_b32 m0, s47
	s_nop 0
	global_load_lds_dwordx4 v132, s[30:31]
	v_add_u32_e32 v154, 0x18400, v153
	v_add_u32_e32 v170, 0x1c400, v153
	ds_read_b128 v[140:143], v154
	ds_read_b128 v[144:147], v154 offset:1024
	ds_read_b128 v[148:151], v154 offset:2048
	ds_read_b128 v[154:157], v154 offset:3072
	ds_read_b128 v[158:161], v170
	ds_read_b128 v[162:165], v170 offset:1024
	ds_read_b128 v[166:169], v170 offset:2048
	ds_read_b128 v[170:173], v170 offset:3072
	ds_read_b128 v[174:177], v152 offset:33792
	ds_read_b128 v[178:181], v152 offset:34816
	ds_read_b128 v[182:185], v152 offset:35840
	ds_read_b128 v[186:189], v152 offset:36864
	ds_read_b128 v[190:193], v152 offset:37888
	ds_read_b128 v[194:197], v152 offset:38912
	ds_read_b128 v[198:201], v152 offset:39936
	ds_read_b128 v[202:205], v152 offset:40960
	s_waitcnt vmcnt(8)
	s_waitcnt lgkmcnt(0)
	s_barrier
	s_setprio 1
	s_waitcnt lgkmcnt(0)
	v_mfma_f32_16x16x32_bf16 v[126:129], v[140:143], v[174:177], v[126:129]
	v_mfma_f32_16x16x32_bf16 v[122:125], v[148:151], v[174:177], v[122:125]
	v_mfma_f32_16x16x32_bf16 v[110:113], v[140:143], v[182:185], v[110:113]
	v_mfma_f32_16x16x32_bf16 v[106:109], v[148:151], v[182:185], v[106:109]
	v_mfma_f32_16x16x32_bf16 v[94:97], v[140:143], v[190:193], v[94:97]
	v_mfma_f32_16x16x32_bf16 v[90:93], v[148:151], v[190:193], v[90:93]
	v_mfma_f32_16x16x32_bf16 v[78:81], v[140:143], v[198:201], v[78:81]
	v_mfma_f32_16x16x32_bf16 v[74:77], v[148:151], v[198:201], v[74:77]
	v_mfma_f32_16x16x32_bf16 v[126:129], v[144:147], v[178:181], v[126:129]
	v_mfma_f32_16x16x32_bf16 v[122:125], v[154:157], v[178:181], v[122:125]
	v_mfma_f32_16x16x32_bf16 v[110:113], v[144:147], v[186:189], v[110:113]
	v_mfma_f32_16x16x32_bf16 v[106:109], v[154:157], v[186:189], v[106:109]
	v_mfma_f32_16x16x32_bf16 v[94:97], v[144:147], v[194:197], v[94:97]
	v_mfma_f32_16x16x32_bf16 v[90:93], v[154:157], v[194:197], v[90:93]
	v_mfma_f32_16x16x32_bf16 v[78:81], v[144:147], v[202:205], v[78:81]
	v_mfma_f32_16x16x32_bf16 v[74:77], v[154:157], v[202:205], v[74:77]
	s_setprio 0
	s_setprio 1
	v_mfma_f32_16x16x32_bf16 v[118:121], v[158:161], v[174:177], v[118:121]
	v_mfma_f32_16x16x32_bf16 v[114:117], v[166:169], v[174:177], v[114:117]
	v_mfma_f32_16x16x32_bf16 v[102:105], v[158:161], v[182:185], v[102:105]
	v_mfma_f32_16x16x32_bf16 v[98:101], v[166:169], v[182:185], v[98:101]
	v_mfma_f32_16x16x32_bf16 v[86:89], v[158:161], v[190:193], v[86:89]
	v_mfma_f32_16x16x32_bf16 v[82:85], v[166:169], v[190:193], v[82:85]
	v_mfma_f32_16x16x32_bf16 v[70:73], v[158:161], v[198:201], v[70:73]
	v_mfma_f32_16x16x32_bf16 v[66:69], v[166:169], v[198:201], v[66:69]
	v_mfma_f32_16x16x32_bf16 v[118:121], v[162:165], v[178:181], v[118:121]
	v_mfma_f32_16x16x32_bf16 v[114:117], v[170:173], v[178:181], v[114:117]
	v_mfma_f32_16x16x32_bf16 v[102:105], v[162:165], v[186:189], v[102:105]
	v_mfma_f32_16x16x32_bf16 v[98:101], v[170:173], v[186:189], v[98:101]
	v_mfma_f32_16x16x32_bf16 v[86:89], v[162:165], v[194:197], v[86:89]
	v_mfma_f32_16x16x32_bf16 v[82:85], v[170:173], v[194:197], v[82:85]
	v_mfma_f32_16x16x32_bf16 v[70:73], v[162:165], v[202:205], v[70:73]
	v_mfma_f32_16x16x32_bf16 v[66:69], v[170:173], v[202:205], v[66:69]
	s_setprio 0
	s_barrier
; #define PG8_STAGE(bufoff, gbase, voff) do { _Pragma("unroll") for (int _i = 0; _i < 2; ++_i) \
;         __builtin_amdgcn_global_load_lds((const GAS unsigned*)((const GAS char*)(gbase) + (voff)[_i]), (LAS unsigned*)(lds + (bufoff) + ldsw + _i * 8192), 16, 0, 0); } while (0)
; #define PG8_LDA(dst, b, h) do { _Pragma("unroll") for (int m = 0; m < 4; ++m) _Pragma("unroll") for (int k = 0; k < 2; ++k) dst[m][k] = *(const LAS bf16x8*)(lds + PG8_SA(b, h) + aoff + m * 2048 + k * 1024); } while (0)
; #define PG8_MMA(ai, bj, At, Bt) do { __builtin_amdgcn_s_setprio(1); _Pragma("unroll") for (int m = 0; m < 4; ++m) _Pragma("unroll") for (int n = 0; n < 2; ++n) _Pragma("unroll") for (int k = 0; k < 2; ++k) \
;         acc[ai][bj][m][n] = __builtin_amdgcn_mfma_f32_16x16x32_bf16(Bt[n][k], At[m][k], acc[ai][bj][m][n], 0, 0, 0); __builtin_amdgcn_s_setprio(0); } while (0)
; #define PG8_WAIT_V(n) asm volatile("s_waitcnt vmcnt(" #n ")" ::: "memory")
; #define PG8_WAIT_L(n) asm volatile("s_waitcnt lgkmcnt(" #n ")" ::: "memory")
; #define PG8_BAR __builtin_amdgcn_s_barrier()
; #define PG8_SCHED __builtin_amdgcn_sched_barrier(0)
; template <class Epi, class Sched, bool ALIGN_EPI>
; __device__ __forceinline__ void gemm_phase(LAS unsigned char* lds, const Gemm g, const Sched& S, const Epi& E, int wave_id) {
;     ...
;             PG8_LDA(At, 1, 1); PG8_STAGE(PG8_SB(1, 0), b3, voffB); PG8_STAGE(PG8_SB(1, 1), b3 + hsB, voffB); PG8_STAGE(PG8_SA(1, 0), a3, voffA);
;             PG8_WAIT_V(8); PG8_WAIT_L(0); PG8_BAR; PG8_MMA(1, 0, At, B0); PG8_MMA(1, 1, At, B1); PG8_BAR; PG8_SCHED;
;         }
	s_mov_b32 m0, s50
	v_lshl_add_u64 v[206:207], v[206:207], 0, s[92:93]
	s_add_u32 s28, s28, 0x40080
	global_load_lds_dwordx4 v[206:207], off
	v_lshl_add_u64 v[206:207], v[208:209], 0, s[92:93]
	s_mov_b32 m0, s51
	s_addc_u32 s29, s29, 0
	global_load_lds_dwordx4 v[206:207], off
	v_lshl_add_u64 v[206:207], s[28:29], 0, v[0:1]
	s_mov_b32 m0, s54
	s_nop 0
	global_load_lds_dwordx4 v[206:207], off
	s_mov_b32 m0, s55
	s_nop 0
	global_load_lds_dwordx4 v130, s[28:29]
	v_lshl_add_u64 v[206:207], v[210:211], 0, s[92:93]
	s_mov_b32 m0, s52
	s_nop 0
	global_load_lds_dwordx4 v[206:207], off
	v_lshl_add_u64 v[206:207], v[212:213], 0, s[92:93]
	s_mov_b32 m0, s53
	s_nop 0
	global_load_lds_dwordx4 v[206:207], off
	ds_read_b128 v[174:177], v152 offset:50176
	ds_read_b128 v[178:181], v152 offset:51200
	ds_read_b128 v[182:185], v152 offset:52224
	ds_read_b128 v[186:189], v152 offset:53248
	ds_read_b128 v[190:193], v152 offset:54272
	ds_read_b128 v[194:197], v152 offset:55296
	ds_read_b128 v[198:201], v152 offset:56320
	ds_read_b128 v[202:205], v152 offset:57344
	s_waitcnt vmcnt(8)
	s_waitcnt lgkmcnt(0)
	s_barrier
	s_setprio 1
	s_waitcnt lgkmcnt(0)
	v_mfma_f32_16x16x32_bf16 v[62:65], v[140:143], v[174:177], v[62:65]
	v_mfma_f32_16x16x32_bf16 v[58:61], v[148:151], v[174:177], v[58:61]
	v_mfma_f32_16x16x32_bf16 v[46:49], v[140:143], v[182:185], v[46:49]
	v_mfma_f32_16x16x32_bf16 v[42:45], v[148:151], v[182:185], v[42:45]
	v_mfma_f32_16x16x32_bf16 v[30:33], v[140:143], v[190:193], v[30:33]
	v_mfma_f32_16x16x32_bf16 v[26:29], v[148:151], v[190:193], v[26:29]
	v_mfma_f32_16x16x32_bf16 v[14:17], v[140:143], v[198:201], v[14:17]
	v_mfma_f32_16x16x32_bf16 v[10:13], v[148:151], v[198:201], v[10:13]
	v_mfma_f32_16x16x32_bf16 v[62:65], v[144:147], v[178:181], v[62:65]
	v_mfma_f32_16x16x32_bf16 v[58:61], v[154:157], v[178:181], v[58:61]
	v_mfma_f32_16x16x32_bf16 v[46:49], v[144:147], v[186:189], v[46:49]
	v_mfma_f32_16x16x32_bf16 v[42:45], v[154:157], v[186:189], v[42:45]
	v_mfma_f32_16x16x32_bf16 v[30:33], v[144:147], v[194:197], v[30:33]
	v_mfma_f32_16x16x32_bf16 v[26:29], v[154:157], v[194:197], v[26:29]
	v_mfma_f32_16x16x32_bf16 v[14:17], v[144:147], v[202:205], v[14:17]
	v_mfma_f32_16x16x32_bf16 v[10:13], v[154:157], v[202:205], v[10:13]
	s_setprio 0
	s_setprio 1
	v_mfma_f32_16x16x32_bf16 v[54:57], v[158:161], v[174:177], v[54:57]
	v_mfma_f32_16x16x32_bf16 v[50:53], v[166:169], v[174:177], v[50:53]
	v_mfma_f32_16x16x32_bf16 v[38:41], v[158:161], v[182:185], v[38:41]
	v_mfma_f32_16x16x32_bf16 v[34:37], v[166:169], v[182:185], v[34:37]
	v_mfma_f32_16x16x32_bf16 v[22:25], v[158:161], v[190:193], v[22:25]
	v_mfma_f32_16x16x32_bf16 v[18:21], v[166:169], v[190:193], v[18:21]
	v_mfma_f32_16x16x32_bf16 v[6:9], v[158:161], v[198:201], v[6:9]
	v_mfma_f32_16x16x32_bf16 v[2:5], v[166:169], v[198:201], v[2:5]
	v_mfma_f32_16x16x32_bf16 v[54:57], v[162:165], v[178:181], v[54:57]
	v_mfma_f32_16x16x32_bf16 v[50:53], v[170:173], v[178:181], v[50:53]
	v_mfma_f32_16x16x32_bf16 v[38:41], v[162:165], v[186:189], v[38:41]
	v_mfma_f32_16x16x32_bf16 v[34:37], v[170:173], v[186:189], v[34:37]
	v_mfma_f32_16x16x32_bf16 v[22:25], v[162:165], v[194:197], v[22:25]
	v_mfma_f32_16x16x32_bf16 v[18:21], v[170:173], v[194:197], v[18:21]
	v_mfma_f32_16x16x32_bf16 v[6:9], v[162:165], v[202:205], v[6:9]
	v_mfma_f32_16x16x32_bf16 v[2:5], v[170:173], v[202:205], v[2:5]
	s_setprio 0
	s_barrier
	s_add_i32 s60, s60, 2
	s_add_u32 s58, s58, 0x100
	s_addc_u32 s59, s59, 0
	s_add_u32 s26, s26, 0x100
	s_addc_u32 s27, s27, 0
	s_cmp_gt_u32 s60, 13
	s_cbranch_scc0 .LBB0_2565
	s_and_b64 vcc, exec, s[14:15]
	s_cbranch_vccz .LBB0_2568
	s_barrier

; #define GAS __attribute__((address_space(1)))
; #define PG8_STAGE(bufoff, gbase, voff) do { _Pragma("unroll") for (int _i = 0; _i < 2; ++_i) \
;         __builtin_amdgcn_global_load_lds((const GAS unsigned*)((const GAS char*)(gbase) + (voff)[_i]), (LAS unsigned*)(lds + (bufoff) + ldsw + _i * 8192), 16, 0, 0); } while (0)
; #define PG8_LDA(dst, b, h) do { _Pragma("unroll") for (int m = 0; m < 4; ++m) _Pragma("unroll") for (int k = 0; k < 2; ++k) dst[m][k] = *(const LAS bf16x8*)(lds + PG8_SA(b, h) + aoff + m * 2048 + k * 1024); } while (0)
; #define PG8_LDB(dst, b, h) do { _Pragma("unroll") for (int n = 0; n < 2; ++n) _Pragma("unroll") for (int k = 0; k < 2; ++k) dst[n][k] = *(const LAS bf16x8*)(lds + PG8_SB(b, h) + boff + n * 2048 + k * 1024); } while (0)
; #define PG8_MMA(ai, bj, At, Bt) do { __builtin_amdgcn_s_setprio(1); _Pragma("unroll") for (int m = 0; m < 4; ++m) _Pragma("unroll") for (int n = 0; n < 2; ++n) _Pragma("unroll") for (int k = 0; k < 2; ++k) \
;         acc[ai][bj][m][n] = __builtin_amdgcn_mfma_f32_16x16x32_bf16(Bt[n][k], At[m][k], acc[ai][bj][m][n], 0, 0, 0); __builtin_amdgcn_s_setprio(0); } while (0)
; #define PG8_WAIT_V(n) asm volatile("s_waitcnt vmcnt(" #n ")" ::: "memory")
; #define PG8_WAIT_L(n) asm volatile("s_waitcnt lgkmcnt(" #n ")" ::: "memory")
; template <class Epi, class Sched, bool ALIGN_EPI>
; __device__ __forceinline__ void gemm_phase(LAS unsigned char* lds, const Gemm g, const Sched& S, const Epi& E, int wave_id) {
;     ...
;         for (int t = 0; t < nt; t += 2) {
;             const bool last = (t == nt - 2);
;             const GAS char* a1 = cA + (size_t)(t + 1) * kstep;
;             const GAS char* a2 = last ? nA : cA + (size_t)(t + 2) * kstep; const GAS char* b2 = last ? nB : cB + (size_t)(t + 2) * kstep;
;             const GAS char* a3 = a2 + kstep; const GAS char* b3 = b2 + kstep;
;             PG8_LDB(B0, 0, 0); PG8_LDB(B1, 0, 1); PG8_SCHED; PG8_LDA(At, 0, 0); PG8_STAGE(PG8_SA(1, 1), a1 + hsA, voffA);
;             PG8_WAIT_V(8); PG8_WAIT_L(0); PG8_BAR; PG8_MMA(0, 0, At, B0); PG8_MMA(0, 1, At, B1); PG8_BAR; PG8_SCHED;
;             PG8_LDA(At, 0, 1); PG8_STAGE(PG8_SB(0, 0), b2, voffB); PG8_STAGE(PG8_SB(0, 1), b2 + hsB, voffB); PG8_STAGE(PG8_SA(0, 0), a2, voffA);
;             PG8_WAIT_V(8); PG8_WAIT_L(0); PG8_BAR; PG8_MMA(1, 0, At, B0); PG8_MMA(1, 1, At, B1); PG8_BAR; PG8_SCHED;
.LBB0_2620:
	s_add_u32 s38, s36, 0xfff80080
	s_addc_u32 s39, s37, -1
	s_cmp_eq_u32 s65, 28
	s_cselect_b32 s41, s1, s39
	s_cselect_b32 s40, s5, s38
	s_cselect_b32 s39, s7, s33
	s_cselect_b32 s38, s27, s29
	s_add_i32 m0, s43, 0xc400
	s_nop 0
	global_load_lds_dwordx4 v218, s[36:37]
	s_add_i32 m0, s43, 0xe400
	s_nop 0
	global_load_lds_dwordx4 v216, s[36:37]
	v_add_u32_e32 v46, 0x10400, v235
	v_add_u32_e32 v62, 0x14400, v235
	ds_read_b128 v[34:37], v46
	ds_read_b128 v[38:41], v46 offset:1024
	ds_read_b128 v[42:45], v46 offset:2048
	ds_read_b128 v[46:49], v46 offset:3072
	ds_read_b128 v[50:53], v62
	ds_read_b128 v[54:57], v62 offset:1024
	ds_read_b128 v[58:61], v62 offset:2048
	ds_read_b128 v[62:65], v62 offset:3072
	ds_read_b128 v[82:85], v234 offset:1024
	ds_read_b128 v[94:97], v234 offset:2048
	ds_read_b128 v[170:173], v234 offset:3072
	ds_read_b128 v[174:177], v234 offset:4096
	ds_read_b128 v[178:181], v234 offset:5120
	ds_read_b128 v[182:185], v234 offset:6144
	ds_read_b128 v[186:189], v234 offset:7168
	ds_read_b128 v[190:193], v234 offset:8192
	s_waitcnt vmcnt(8)
	s_waitcnt lgkmcnt(0)
	s_barrier
	s_setprio 1
	s_waitcnt lgkmcnt(0)
	v_mfma_f32_16x16x32_bf16 v[166:169], v[34:37], v[82:85], v[166:169]
	v_mfma_f32_16x16x32_bf16 v[162:165], v[42:45], v[82:85], v[162:165]
	v_mfma_f32_16x16x32_bf16 v[150:153], v[34:37], v[170:173], v[150:153]
	v_mfma_f32_16x16x32_bf16 v[146:149], v[42:45], v[170:173], v[146:149]
	v_mfma_f32_16x16x32_bf16 v[134:137], v[34:37], v[178:181], v[134:137]
	v_mfma_f32_16x16x32_bf16 v[130:133], v[42:45], v[178:181], v[130:133]
	v_mfma_f32_16x16x32_bf16 v[118:121], v[34:37], v[186:189], v[118:121]
	v_mfma_f32_16x16x32_bf16 v[114:117], v[42:45], v[186:189], v[114:117]
	v_mfma_f32_16x16x32_bf16 v[166:169], v[38:41], v[94:97], v[166:169]
	v_mfma_f32_16x16x32_bf16 v[162:165], v[46:49], v[94:97], v[162:165]
	v_mfma_f32_16x16x32_bf16 v[150:153], v[38:41], v[174:177], v[150:153]
	v_mfma_f32_16x16x32_bf16 v[146:149], v[46:49], v[174:177], v[146:149]
	v_mfma_f32_16x16x32_bf16 v[134:137], v[38:41], v[182:185], v[134:137]
	v_mfma_f32_16x16x32_bf16 v[130:133], v[46:49], v[182:185], v[130:133]
	v_mfma_f32_16x16x32_bf16 v[118:121], v[38:41], v[190:193], v[118:121]
	v_mfma_f32_16x16x32_bf16 v[114:117], v[46:49], v[190:193], v[114:117]
	s_setprio 0
	s_setprio 1
	v_mfma_f32_16x16x32_bf16 v[158:161], v[50:53], v[82:85], v[158:161]
	v_mfma_f32_16x16x32_bf16 v[82:85], v[58:61], v[82:85], v[154:157]
	v_mfma_f32_16x16x32_bf16 v[138:141], v[58:61], v[170:173], v[138:141]
	v_mfma_f32_16x16x32_bf16 v[126:129], v[50:53], v[178:181], v[126:129]
	v_mfma_f32_16x16x32_bf16 v[122:125], v[58:61], v[178:181], v[122:125]
	v_mfma_f32_16x16x32_bf16 v[110:113], v[50:53], v[186:189], v[110:113]
	v_mfma_f32_16x16x32_bf16 v[106:109], v[58:61], v[186:189], v[106:109]
	v_mfma_f32_16x16x32_bf16 v[158:161], v[54:57], v[94:97], v[158:161]
	v_mfma_f32_16x16x32_bf16 v[82:85], v[62:65], v[94:97], v[82:85]
	v_mfma_f32_16x16x32_bf16 v[94:97], v[50:53], v[170:173], v[142:145]
	v_mfma_f32_16x16x32_bf16 v[138:141], v[62:65], v[174:177], v[138:141]
	v_mfma_f32_16x16x32_bf16 v[126:129], v[54:57], v[182:185], v[126:129]
	v_mfma_f32_16x16x32_bf16 v[122:125], v[62:65], v[182:185], v[122:125]
	v_mfma_f32_16x16x32_bf16 v[110:113], v[54:57], v[190:193], v[110:113]
	v_mfma_f32_16x16x32_bf16 v[106:109], v[62:65], v[190:193], v[106:109]
	v_mfma_f32_16x16x32_bf16 v[94:97], v[54:57], v[174:177], v[94:97]
	s_setprio 0
	s_barrier
	s_mov_b32 m0, s48
	v_lshl_add_u64 v[202:203], s[38:39], 0, v[0:1]
	s_add_u32 s66, s38, 0x80000
	global_load_lds_dwordx4 v[202:203], off
	v_lshl_add_u64 v[204:205], s[38:39], 0, v[210:211]
	s_mov_b32 m0, s49
	s_addc_u32 s67, s39, 0
	global_load_lds_dwordx4 v210, s[38:39]
	v_lshl_add_u64 v[194:195], s[66:67], 0, v[0:1]
	s_mov_b32 m0, s50
	v_lshl_add_u64 v[220:221], s[40:41], 0, v[206:207]
	global_load_lds_dwordx4 v[194:195], off
	v_lshl_add_u64 v[194:195], s[66:67], 0, v[210:211]
	s_mov_b32 m0, s51
	v_lshl_add_u64 v[224:225], s[40:41], 0, v[208:209]
	global_load_lds_dwordx4 v210, s[66:67]
	s_mov_b32 m0, s52
	s_nop 0
	global_load_lds_dwordx4 v206, s[40:41]
	s_mov_b32 m0, s53
	s_nop 0
	global_load_lds_dwordx4 v208, s[40:41]
	ds_read_b128 v[142:145], v234 offset:17408
	ds_read_b128 v[154:157], v234 offset:18432
	ds_read_b128 v[170:173], v234 offset:19456
	ds_read_b128 v[174:177], v234 offset:20480
	ds_read_b128 v[178:181], v234 offset:21504
	ds_read_b128 v[182:185], v234 offset:22528
	ds_read_b128 v[186:189], v234 offset:23552
	ds_read_b128 v[190:193], v234 offset:24576
	s_waitcnt vmcnt(8)
	s_waitcnt lgkmcnt(0)
	s_barrier
; #define PG8_STAGE(bufoff, gbase, voff) do { _Pragma("unroll") for (int _i = 0; _i < 2; ++_i) \
;         __builtin_amdgcn_global_load_lds((const GAS unsigned*)((const GAS char*)(gbase) + (voff)[_i]), (LAS unsigned*)(lds + (bufoff) + ldsw + _i * 8192), 16, 0, 0); } while (0)
; #define PG8_LDA(dst, b, h) do { _Pragma("unroll") for (int m = 0; m < 4; ++m) _Pragma("unroll") for (int k = 0; k < 2; ++k) dst[m][k] = *(const LAS bf16x8*)(lds + PG8_SA(b, h) + aoff + m * 2048 + k * 1024); } while (0)
; #define PG8_LDB(dst, b, h) do { _Pragma("unroll") for (int n = 0; n < 2; ++n) _Pragma("unroll") for (int k = 0; k < 2; ++k) dst[n][k] = *(const LAS bf16x8*)(lds + PG8_SB(b, h) + boff + n * 2048 + k * 1024); } while (0)
; #define PG8_MMA(ai, bj, At, Bt) do { __builtin_amdgcn_s_setprio(1); _Pragma("unroll") for (int m = 0; m < 4; ++m) _Pragma("unroll") for (int n = 0; n < 2; ++n) _Pragma("unroll") for (int k = 0; k < 2; ++k) \
;         acc[ai][bj][m][n] = __builtin_amdgcn_mfma_f32_16x16x32_bf16(Bt[n][k], At[m][k], acc[ai][bj][m][n], 0, 0, 0); __builtin_amdgcn_s_setprio(0); } while (0)
; #define PG8_WAIT_V(n) asm volatile("s_waitcnt vmcnt(" #n ")" ::: "memory")
; #define PG8_WAIT_L(n) asm volatile("s_waitcnt lgkmcnt(" #n ")" ::: "memory")
; #define PG8_BAR __builtin_amdgcn_s_barrier()
; #define PG8_SCHED __builtin_amdgcn_sched_barrier(0)
; template <class Epi, class Sched, bool ALIGN_EPI>
; __device__ __forceinline__ void gemm_phase(LAS unsigned char* lds, const Gemm g, const Sched& S, const Epi& E, int wave_id) {
;     ...
;             PG8_WAIT_V(8); PG8_WAIT_L(0); PG8_BAR; PG8_MMA(1, 0, At, B0); PG8_MMA(1, 1, At, B1); PG8_BAR; PG8_SCHED;
;             PG8_LDB(B0, 1, 0); PG8_LDB(B1, 1, 1); PG8_SCHED; PG8_LDA(At, 1, 0); PG8_STAGE(PG8_SA(0, 1), a2 + hsA, voffA);
;             PG8_WAIT_V(8); PG8_WAIT_L(0); PG8_BAR; PG8_MMA(0, 0, At, B0); PG8_MMA(0, 1, At, B1); PG8_BAR; PG8_SCHED;
	s_setprio 1
	s_waitcnt lgkmcnt(0)
	v_mfma_f32_16x16x32_bf16 v[102:105], v[34:37], v[142:145], v[102:105]
	v_mfma_f32_16x16x32_bf16 v[98:101], v[42:45], v[142:145], v[98:101]
	v_mfma_f32_16x16x32_bf16 v[78:81], v[34:37], v[170:173], v[78:81]
	v_mfma_f32_16x16x32_bf16 v[74:77], v[42:45], v[170:173], v[74:77]
	v_mfma_f32_16x16x32_bf16 v[30:33], v[34:37], v[178:181], v[30:33]
	v_mfma_f32_16x16x32_bf16 v[26:29], v[42:45], v[178:181], v[26:29]
	v_mfma_f32_16x16x32_bf16 v[14:17], v[34:37], v[186:189], v[14:17]
	v_mfma_f32_16x16x32_bf16 v[10:13], v[42:45], v[186:189], v[10:13]
	v_mfma_f32_16x16x32_bf16 v[102:105], v[38:41], v[154:157], v[102:105]
	v_mfma_f32_16x16x32_bf16 v[98:101], v[46:49], v[154:157], v[98:101]
	v_mfma_f32_16x16x32_bf16 v[78:81], v[38:41], v[174:177], v[78:81]
	v_mfma_f32_16x16x32_bf16 v[74:77], v[46:49], v[174:177], v[74:77]
	v_mfma_f32_16x16x32_bf16 v[30:33], v[38:41], v[182:185], v[30:33]
	v_mfma_f32_16x16x32_bf16 v[26:29], v[46:49], v[182:185], v[26:29]
	v_mfma_f32_16x16x32_bf16 v[14:17], v[38:41], v[190:193], v[14:17]
	v_mfma_f32_16x16x32_bf16 v[10:13], v[46:49], v[190:193], v[10:13]
	s_setprio 0
	s_setprio 1
	v_mfma_f32_16x16x32_bf16 v[22:25], v[50:53], v[178:181], v[22:25]
	v_mfma_f32_16x16x32_bf16 v[18:21], v[58:61], v[178:181], v[18:21]
	v_mfma_f32_16x16x32_bf16 v[6:9], v[50:53], v[186:189], v[6:9]
	v_mfma_f32_16x16x32_bf16 v[2:5], v[58:61], v[186:189], v[2:5]
	v_mfma_f32_16x16x32_bf16 v[34:37], v[50:53], v[142:145], v[90:93]
	v_mfma_f32_16x16x32_bf16 v[38:41], v[58:61], v[142:145], v[86:89]
	v_mfma_f32_16x16x32_bf16 v[42:45], v[50:53], v[170:173], v[70:73]
	v_mfma_f32_16x16x32_bf16 v[46:49], v[58:61], v[170:173], v[66:69]
	v_mfma_f32_16x16x32_bf16 v[22:25], v[54:57], v[182:185], v[22:25]
	v_mfma_f32_16x16x32_bf16 v[18:21], v[62:65], v[182:185], v[18:21]
	v_mfma_f32_16x16x32_bf16 v[6:9], v[54:57], v[190:193], v[6:9]
	v_mfma_f32_16x16x32_bf16 v[2:5], v[62:65], v[190:193], v[2:5]
	v_mfma_f32_16x16x32_bf16 v[34:37], v[54:57], v[154:157], v[34:37]
	v_mfma_f32_16x16x32_bf16 v[38:41], v[62:65], v[154:157], v[38:41]
	v_mfma_f32_16x16x32_bf16 v[42:45], v[54:57], v[174:177], v[42:45]
	v_mfma_f32_16x16x32_bf16 v[46:49], v[62:65], v[174:177], v[46:49]
	s_setprio 0
	s_barrier
	s_add_u32 s40, s40, 0x80000
	s_addc_u32 s41, s41, 0
	s_mov_b32 m0, s54
	s_nop 0
	global_load_lds_dwordx4 v206, s[40:41]
	v_lshl_add_u64 v[142:143], s[40:41], 0, v[208:209]
	s_mov_b32 m0, s55
	s_nop 0
	global_load_lds_dwordx4 v208, s[40:41]
	v_add_u32_e32 v62, 0x18400, v235
	v_add_u32_e32 v66, 0x1c400, v235
	ds_read_b128 v[50:53], v62
	ds_read_b128 v[54:57], v62 offset:1024
	ds_read_b128 v[58:61], v62 offset:2048
	ds_read_b128 v[62:65], v62 offset:3072
	ds_read_b128 v[170:173], v66
	ds_read_b128 v[174:177], v66 offset:1024
	ds_read_b128 v[178:181], v66 offset:2048
	ds_read_b128 v[182:185], v66 offset:3072
	ds_read_b128 v[66:69], v234 offset:33792
	ds_read_b128 v[70:73], v234 offset:34816
	ds_read_b128 v[86:89], v234 offset:35840
	ds_read_b128 v[90:93], v234 offset:36864
	ds_read_b128 v[186:189], v234 offset:37888
	ds_read_b128 v[190:193], v234 offset:38912
	ds_read_b128 v[194:197], v234 offset:39936
	ds_read_b128 v[198:201], v234 offset:40960
	s_waitcnt vmcnt(8)
	s_waitcnt lgkmcnt(0)
	s_barrier
	s_setprio 1
	s_waitcnt lgkmcnt(0)
	v_mfma_f32_16x16x32_bf16 v[142:145], v[50:53], v[66:69], v[166:169]
	v_mfma_f32_16x16x32_bf16 v[166:169], v[54:57], v[70:73], v[142:145]
	v_mfma_f32_16x16x32_bf16 v[142:145], v[58:61], v[66:69], v[162:165]
	v_mfma_f32_16x16x32_bf16 v[162:165], v[62:65], v[70:73], v[142:145]
	v_mfma_f32_16x16x32_bf16 v[142:145], v[50:53], v[86:89], v[150:153]
	v_mfma_f32_16x16x32_bf16 v[150:153], v[54:57], v[90:93], v[142:145]
	v_mfma_f32_16x16x32_bf16 v[142:145], v[58:61], v[86:89], v[146:149]
	v_mfma_f32_16x16x32_bf16 v[134:137], v[50:53], v[186:189], v[134:137]
	v_mfma_f32_16x16x32_bf16 v[130:133], v[58:61], v[186:189], v[130:133]
	v_mfma_f32_16x16x32_bf16 v[118:121], v[50:53], v[194:197], v[118:121]
	v_mfma_f32_16x16x32_bf16 v[114:117], v[58:61], v[194:197], v[114:117]
	v_mfma_f32_16x16x32_bf16 v[146:149], v[62:65], v[90:93], v[142:145]
	v_mfma_f32_16x16x32_bf16 v[134:137], v[54:57], v[190:193], v[134:137]
	v_mfma_f32_16x16x32_bf16 v[130:133], v[62:65], v[190:193], v[130:133]
	v_mfma_f32_16x16x32_bf16 v[118:121], v[54:57], v[198:201], v[118:121]
	v_mfma_f32_16x16x32_bf16 v[114:117], v[62:65], v[198:201], v[114:117]
	s_setprio 0
	s_setprio 1
	v_mfma_f32_16x16x32_bf16 v[142:145], v[170:173], v[66:69], v[158:161]
	v_mfma_f32_16x16x32_bf16 v[66:69], v[178:181], v[66:69], v[82:85]
	v_mfma_f32_16x16x32_bf16 v[154:157], v[182:185], v[70:73], v[66:69]
	v_mfma_f32_16x16x32_bf16 v[66:69], v[170:173], v[86:89], v[94:97]
	v_mfma_f32_16x16x32_bf16 v[158:161], v[174:177], v[70:73], v[142:145]
	v_mfma_f32_16x16x32_bf16 v[142:145], v[174:177], v[90:93], v[66:69]
	v_mfma_f32_16x16x32_bf16 v[66:69], v[178:181], v[86:89], v[138:141]
	v_mfma_f32_16x16x32_bf16 v[138:141], v[182:185], v[90:93], v[66:69]
	v_mfma_f32_16x16x32_bf16 v[66:69], v[170:173], v[186:189], v[126:129]
	v_mfma_f32_16x16x32_bf16 v[126:129], v[174:177], v[190:193], v[66:69]
	v_mfma_f32_16x16x32_bf16 v[66:69], v[178:181], v[186:189], v[122:125]
	v_mfma_f32_16x16x32_bf16 v[122:125], v[182:185], v[190:193], v[66:69]
	v_mfma_f32_16x16x32_bf16 v[66:69], v[170:173], v[194:197], v[110:113]
	v_mfma_f32_16x16x32_bf16 v[110:113], v[174:177], v[198:201], v[66:69]
	v_mfma_f32_16x16x32_bf16 v[66:69], v[178:181], v[194:197], v[106:109]
	v_mfma_f32_16x16x32_bf16 v[106:109], v[182:185], v[198:201], v[66:69]
	s_setprio 0
	s_barrier
; #define PG8_STAGE(bufoff, gbase, voff) do { _Pragma("unroll") for (int _i = 0; _i < 2; ++_i) \
;         __builtin_amdgcn_global_load_lds((const GAS unsigned*)((const GAS char*)(gbase) + (voff)[_i]), (LAS unsigned*)(lds + (bufoff) + ldsw + _i * 8192), 16, 0, 0); } while (0)
; #define PG8_LDA(dst, b, h) do { _Pragma("unroll") for (int m = 0; m < 4; ++m) _Pragma("unroll") for (int k = 0; k < 2; ++k) dst[m][k] = *(const LAS bf16x8*)(lds + PG8_SA(b, h) + aoff + m * 2048 + k * 1024); } while (0)
; #define PG8_MMA(ai, bj, At, Bt) do { __builtin_amdgcn_s_setprio(1); _Pragma("unroll") for (int m = 0; m < 4; ++m) _Pragma("unroll") for (int n = 0; n < 2; ++n) _Pragma("unroll") for (int k = 0; k < 2; ++k) \
;         acc[ai][bj][m][n] = __builtin_amdgcn_mfma_f32_16x16x32_bf16(Bt[n][k], At[m][k], acc[ai][bj][m][n], 0, 0, 0); __builtin_amdgcn_s_setprio(0); } while (0)
; #define PG8_WAIT_V(n) asm volatile("s_waitcnt vmcnt(" #n ")" ::: "memory")
; #define PG8_WAIT_L(n) asm volatile("s_waitcnt lgkmcnt(" #n ")" ::: "memory")
; #define PG8_BAR __builtin_amdgcn_s_barrier()
; #define PG8_SCHED __builtin_amdgcn_sched_barrier(0)
; template <class Epi, class Sched, bool ALIGN_EPI>
; __device__ __forceinline__ void gemm_phase(LAS unsigned char* lds, const Gemm g, const Sched& S, const Epi& E, int wave_id) {
;     ...
;             PG8_LDA(At, 1, 1); PG8_STAGE(PG8_SB(1, 0), b3, voffB); PG8_STAGE(PG8_SB(1, 1), b3 + hsB, voffB); PG8_STAGE(PG8_SA(1, 0), a3, voffA);
;             PG8_WAIT_V(8); PG8_WAIT_L(0); PG8_BAR; PG8_MMA(1, 0, At, B0); PG8_MMA(1, 1, At, B1); PG8_BAR; PG8_SCHED;
;         }
	s_mov_b32 m0, s58
	v_lshl_add_u64 v[86:87], v[202:203], 0, s[92:93]
	s_add_u32 s38, s38, 0x80080
	s_nop 1
	global_load_lds_dwordx4 v[86:87], off
	v_lshl_add_u64 v[86:87], v[204:205], 0, s[92:93]
	s_mov_b32 m0, s59
	s_addc_u32 s39, s39, 0
	global_load_lds_dwordx4 v[86:87], off
	v_lshl_add_u64 v[86:87], s[38:39], 0, v[0:1]
	s_mov_b32 m0, s62
	s_nop 0
	global_load_lds_dwordx4 v[86:87], off
	s_mov_b32 m0, s63
	s_nop 0
	global_load_lds_dwordx4 v210, s[38:39]
	v_lshl_add_u64 v[86:87], v[220:221], 0, s[92:93]
	s_mov_b32 m0, s60
	s_nop 0
	global_load_lds_dwordx4 v[86:87], off
	v_lshl_add_u64 v[86:87], v[224:225], 0, s[92:93]
	s_mov_b32 m0, s61
	s_nop 0
	global_load_lds_dwordx4 v[86:87], off
	ds_read_b128 v[66:69], v234 offset:50176
	ds_read_b128 v[70:73], v234 offset:51200
	ds_read_b128 v[82:85], v234 offset:52224
	ds_read_b128 v[94:97], v234 offset:53248
	ds_read_b128 v[186:189], v234 offset:54272
	ds_read_b128 v[190:193], v234 offset:55296
	ds_read_b128 v[194:197], v234 offset:56320
	ds_read_b128 v[198:201], v234 offset:57344
	s_waitcnt vmcnt(8)
	s_waitcnt lgkmcnt(0)
	s_barrier
	s_setprio 1
	s_waitcnt lgkmcnt(0)
	v_mfma_f32_16x16x32_bf16 v[86:89], v[50:53], v[66:69], v[102:105]
	v_mfma_f32_16x16x32_bf16 v[102:105], v[54:57], v[70:73], v[86:89]
	v_mfma_f32_16x16x32_bf16 v[86:89], v[58:61], v[66:69], v[98:101]
	v_mfma_f32_16x16x32_bf16 v[78:81], v[50:53], v[82:85], v[78:81]
	v_mfma_f32_16x16x32_bf16 v[74:77], v[58:61], v[82:85], v[74:77]
	v_mfma_f32_16x16x32_bf16 v[30:33], v[50:53], v[186:189], v[30:33]
	v_mfma_f32_16x16x32_bf16 v[26:29], v[58:61], v[186:189], v[26:29]
	v_mfma_f32_16x16x32_bf16 v[14:17], v[50:53], v[194:197], v[14:17]
	v_mfma_f32_16x16x32_bf16 v[10:13], v[58:61], v[194:197], v[10:13]
	v_mfma_f32_16x16x32_bf16 v[98:101], v[62:65], v[70:73], v[86:89]
	v_mfma_f32_16x16x32_bf16 v[78:81], v[54:57], v[94:97], v[78:81]
	v_mfma_f32_16x16x32_bf16 v[74:77], v[62:65], v[94:97], v[74:77]
	v_mfma_f32_16x16x32_bf16 v[30:33], v[54:57], v[190:193], v[30:33]
	v_mfma_f32_16x16x32_bf16 v[26:29], v[62:65], v[190:193], v[26:29]
	v_mfma_f32_16x16x32_bf16 v[14:17], v[54:57], v[198:201], v[14:17]
	v_mfma_f32_16x16x32_bf16 v[10:13], v[62:65], v[198:201], v[10:13]
	s_setprio 0
	s_setprio 1
	v_mfma_f32_16x16x32_bf16 v[34:37], v[170:173], v[66:69], v[34:37]
	v_mfma_f32_16x16x32_bf16 v[90:93], v[174:177], v[70:73], v[34:37]
	v_mfma_f32_16x16x32_bf16 v[34:37], v[178:181], v[66:69], v[38:41]
	v_mfma_f32_16x16x32_bf16 v[86:89], v[182:185], v[70:73], v[34:37]
	v_mfma_f32_16x16x32_bf16 v[34:37], v[170:173], v[82:85], v[42:45]
	v_mfma_f32_16x16x32_bf16 v[70:73], v[174:177], v[94:97], v[34:37]
	v_mfma_f32_16x16x32_bf16 v[34:37], v[178:181], v[82:85], v[46:49]
	v_mfma_f32_16x16x32_bf16 v[22:25], v[170:173], v[186:189], v[22:25]
	v_mfma_f32_16x16x32_bf16 v[18:21], v[178:181], v[186:189], v[18:21]
	v_mfma_f32_16x16x32_bf16 v[6:9], v[170:173], v[194:197], v[6:9]
	v_mfma_f32_16x16x32_bf16 v[2:5], v[178:181], v[194:197], v[2:5]
	v_mfma_f32_16x16x32_bf16 v[66:69], v[182:185], v[94:97], v[34:37]
	v_mfma_f32_16x16x32_bf16 v[22:25], v[174:177], v[190:193], v[22:25]
	v_mfma_f32_16x16x32_bf16 v[18:21], v[182:185], v[190:193], v[18:21]
	v_mfma_f32_16x16x32_bf16 v[6:9], v[174:177], v[198:201], v[6:9]
	v_mfma_f32_16x16x32_bf16 v[2:5], v[182:185], v[198:201], v[2:5]
	s_setprio 0
	s_barrier
	s_add_i32 s65, s65, 2
	s_add_u32 s29, s29, 0x100
	s_addc_u32 s33, s33, 0
	s_add_u32 s36, s36, 0x100
	s_addc_u32 s37, s37, 0
	s_cmp_gt_u32 s65, 29
	s_cbranch_scc0 .LBB0_2620
	s_and_b64 vcc, exec, s[22:23]
	s_cbranch_vccz .LBB0_2623
	s_barrier

; #define GAS __attribute__((address_space(1)))
; #define PG8_STAGE(bufoff, gbase, voff) do { _Pragma("unroll") for (int _i = 0; _i < 2; ++_i) \
;         __builtin_amdgcn_global_load_lds((const GAS unsigned*)((const GAS char*)(gbase) + (voff)[_i]), (LAS unsigned*)(lds + (bufoff) + ldsw + _i * 8192), 16, 0, 0); } while (0)
; #define PG8_LDA(dst, b, h) do { _Pragma("unroll") for (int m = 0; m < 4; ++m) _Pragma("unroll") for (int k = 0; k < 2; ++k) dst[m][k] = *(const LAS bf16x8*)(lds + PG8_SA(b, h) + aoff + m * 2048 + k * 1024); } while (0)
; #define PG8_LDB(dst, b, h) do { _Pragma("unroll") for (int n = 0; n < 2; ++n) _Pragma("unroll") for (int k = 0; k < 2; ++k) dst[n][k] = *(const LAS bf16x8*)(lds + PG8_SB(b, h) + boff + n * 2048 + k * 1024); } while (0)
; #define PG8_MMA(ai, bj, At, Bt) do { __builtin_amdgcn_s_setprio(1); _Pragma("unroll") for (int m = 0; m < 4; ++m) _Pragma("unroll") for (int n = 0; n < 2; ++n) _Pragma("unroll") for (int k = 0; k < 2; ++k) \
;         acc[ai][bj][m][n] = __builtin_amdgcn_mfma_f32_16x16x32_bf16(Bt[n][k], At[m][k], acc[ai][bj][m][n], 0, 0, 0); __builtin_amdgcn_s_setprio(0); } while (0)
; #define PG8_WAIT_V(n) asm volatile("s_waitcnt vmcnt(" #n ")" ::: "memory")
; #define PG8_WAIT_L(n) asm volatile("s_waitcnt lgkmcnt(" #n ")" ::: "memory")
; template <class Epi, class Sched, bool ALIGN_EPI>
; __device__ __forceinline__ void gemm_phase(LAS unsigned char* lds, const Gemm g, const Sched& S, const Epi& E, int wave_id) {
;     ...
;         for (int t = 0; t < nt; t += 2) {
;             const bool last = (t == nt - 2);
;             const GAS char* a1 = cA + (size_t)(t + 1) * kstep;
;             const GAS char* a2 = last ? nA : cA + (size_t)(t + 2) * kstep; const GAS char* b2 = last ? nB : cB + (size_t)(t + 2) * kstep;
;             const GAS char* a3 = a2 + kstep; const GAS char* b3 = b2 + kstep;
;             PG8_LDB(B0, 0, 0); PG8_LDB(B1, 0, 1); PG8_SCHED; PG8_LDA(At, 0, 0); PG8_STAGE(PG8_SA(1, 1), a1 + hsA, voffA);
;             PG8_WAIT_V(8); PG8_WAIT_L(0); PG8_BAR; PG8_MMA(0, 0, At, B0); PG8_MMA(0, 1, At, B1); PG8_BAR; PG8_SCHED;
;             PG8_LDA(At, 0, 1); PG8_STAGE(PG8_SB(0, 0), b2, voffB); PG8_STAGE(PG8_SB(0, 1), b2 + hsB, voffB); PG8_STAGE(PG8_SA(0, 0), a2, voffA);
;             PG8_WAIT_V(8); PG8_WAIT_L(0); PG8_BAR; PG8_MMA(1, 0, At, B0); PG8_MMA(1, 1, At, B1); PG8_BAR; PG8_SCHED;
.LBB0_2874:
	s_add_u32 s28, s2, 0xfff80080
	s_addc_u32 s29, s3, -1
	s_cmp_eq_u32 s67, 28
	s_cselect_b32 s31, s23, s29
	s_cselect_b32 s30, s22, s28
	s_cselect_b32 s29, s21, s66
	s_cselect_b32 s28, s27, s33
	s_add_i32 m0, s40, 0xc400
	s_nop 0
	global_load_lds_dwordx4 v232, s[2:3]
	s_add_i32 m0, s40, 0xe400
	s_nop 0
	global_load_lds_dwordx4 v230, s[2:3]
	v_add_u32_e32 v82, 0x10400, v240
	ds_read_b128 v[18:21], v82
	ds_read_b128 v[88:91], v82 offset:1024
	ds_read_b128 v[108:111], v82 offset:2048
	ds_read_b128 v[112:115], v82 offset:3072
	v_add_u32_e32 v82, 0x14400, v240
	ds_read_b128 v[116:119], v82
	ds_read_b128 v[120:123], v82 offset:1024
	ds_read_b128 v[128:131], v82 offset:2048
	ds_read_b128 v[132:135], v82 offset:3072
	ds_read_b128 v[136:139], v239 offset:1024
	ds_read_b128 v[140:143], v239 offset:2048
	ds_read_b128 v[144:147], v239 offset:3072
	ds_read_b128 v[164:167], v239 offset:4096
	ds_read_b128 v[180:183], v239 offset:5120
	ds_read_b128 v[184:187], v239 offset:6144
	ds_read_b128 v[188:191], v239 offset:7168
	ds_read_b128 v[192:195], v239 offset:8192
	s_waitcnt vmcnt(8)
	s_waitcnt lgkmcnt(0)
	s_barrier
	s_setprio 1
	s_waitcnt lgkmcnt(0)
	v_mfma_f32_16x16x32_bf16 v[176:179], v[18:21], v[136:139], v[176:179]
	v_mfma_f32_16x16x32_bf16 v[30:33], v[108:111], v[136:139], v[30:33]
	v_mfma_f32_16x16x32_bf16 v[172:175], v[18:21], v[144:147], v[172:175]
	v_mfma_f32_16x16x32_bf16 v[50:53], v[108:111], v[144:147], v[50:53]
	v_mfma_f32_16x16x32_bf16 v[156:159], v[18:21], v[180:183], v[156:159]
	v_mfma_f32_16x16x32_bf16 v[78:81], v[108:111], v[180:183], v[78:81]
	v_mfma_f32_16x16x32_bf16 v[124:127], v[18:21], v[188:191], v[124:127]
	v_mfma_f32_16x16x32_bf16 v[104:107], v[108:111], v[188:191], v[104:107]
	v_mfma_f32_16x16x32_bf16 v[176:179], v[88:91], v[140:143], v[176:179]
	v_mfma_f32_16x16x32_bf16 v[30:33], v[112:115], v[140:143], v[30:33]
	v_mfma_f32_16x16x32_bf16 v[172:175], v[88:91], v[164:167], v[172:175]
	v_mfma_f32_16x16x32_bf16 v[50:53], v[112:115], v[164:167], v[50:53]
	v_mfma_f32_16x16x32_bf16 v[156:159], v[88:91], v[184:187], v[156:159]
	v_mfma_f32_16x16x32_bf16 v[78:81], v[112:115], v[184:187], v[78:81]
	v_mfma_f32_16x16x32_bf16 v[124:127], v[88:91], v[192:195], v[124:127]
	v_mfma_f32_16x16x32_bf16 v[104:107], v[112:115], v[192:195], v[104:107]
	s_setprio 0
	s_setprio 1
	v_mfma_f32_16x16x32_bf16 v[160:163], v[116:119], v[136:139], v[160:163]
	v_mfma_f32_16x16x32_bf16 v[62:65], v[128:131], v[136:139], v[62:65]
	v_mfma_f32_16x16x32_bf16 v[92:95], v[128:131], v[144:147], v[92:95]
	v_mfma_f32_16x16x32_bf16 v[100:103], v[116:119], v[188:191], v[100:103]
	v_mfma_f32_16x16x32_bf16 v[96:99], v[128:131], v[188:191], v[96:99]
	v_mfma_f32_16x16x32_bf16 v[160:163], v[120:123], v[140:143], v[160:163]
	v_mfma_f32_16x16x32_bf16 v[62:65], v[132:135], v[140:143], v[62:65]
	v_mfma_f32_16x16x32_bf16 v[136:139], v[116:119], v[144:147], v[168:171]
	v_mfma_f32_16x16x32_bf16 v[92:95], v[132:135], v[164:167], v[92:95]
	v_mfma_f32_16x16x32_bf16 v[140:143], v[116:119], v[180:183], v[152:155]
	v_mfma_f32_16x16x32_bf16 v[144:147], v[128:131], v[180:183], v[148:151]
	v_mfma_f32_16x16x32_bf16 v[100:103], v[120:123], v[192:195], v[100:103]
	v_mfma_f32_16x16x32_bf16 v[96:99], v[132:135], v[192:195], v[96:99]
	v_mfma_f32_16x16x32_bf16 v[136:139], v[120:123], v[164:167], v[136:139]
	v_mfma_f32_16x16x32_bf16 v[140:143], v[120:123], v[184:187], v[140:143]
	v_mfma_f32_16x16x32_bf16 v[144:147], v[132:135], v[184:187], v[144:147]
	s_setprio 0
	s_barrier
	s_mov_b32 m0, s41
	v_lshl_add_u64 v[200:201], s[28:29], 0, v[0:1]
	s_add_u32 s68, s28, 0x80000
	global_load_lds_dwordx4 v[200:201], off
	v_lshl_add_u64 v[202:203], s[28:29], 0, v[228:229]
	s_mov_b32 m0, s42
	s_addc_u32 s69, s29, 0
	global_load_lds_dwordx4 v228, s[28:29]
	v_lshl_add_u64 v[82:83], s[68:69], 0, v[0:1]
	s_mov_b32 m0, s43
	v_lshl_add_u64 v[204:205], s[30:31], 0, v[224:225]
	global_load_lds_dwordx4 v[82:83], off
	v_lshl_add_u64 v[82:83], s[68:69], 0, v[228:229]
	s_mov_b32 m0, s44
	v_lshl_add_u64 v[206:207], s[30:31], 0, v[226:227]
	global_load_lds_dwordx4 v228, s[68:69]
	s_mov_b32 m0, s45
	s_nop 0
	global_load_lds_dwordx4 v224, s[30:31]
	s_mov_b32 m0, s46
	s_nop 0
	global_load_lds_dwordx4 v226, s[30:31]
	ds_read_b128 v[148:151], v239 offset:17408
	ds_read_b128 v[152:155], v239 offset:18432
	ds_read_b128 v[164:167], v239 offset:19456
	ds_read_b128 v[168:171], v239 offset:20480
	ds_read_b128 v[180:183], v239 offset:21504
	ds_read_b128 v[184:187], v239 offset:22528
	ds_read_b128 v[188:191], v239 offset:23552
	ds_read_b128 v[192:195], v239 offset:24576
	s_waitcnt vmcnt(8)
	s_waitcnt lgkmcnt(0)
	s_barrier
; #define PG8_STAGE(bufoff, gbase, voff) do { _Pragma("unroll") for (int _i = 0; _i < 2; ++_i) \
;         __builtin_amdgcn_global_load_lds((const GAS unsigned*)((const GAS char*)(gbase) + (voff)[_i]), (LAS unsigned*)(lds + (bufoff) + ldsw + _i * 8192), 16, 0, 0); } while (0)
; #define PG8_LDA(dst, b, h) do { _Pragma("unroll") for (int m = 0; m < 4; ++m) _Pragma("unroll") for (int k = 0; k < 2; ++k) dst[m][k] = *(const LAS bf16x8*)(lds + PG8_SA(b, h) + aoff + m * 2048 + k * 1024); } while (0)
; #define PG8_LDB(dst, b, h) do { _Pragma("unroll") for (int n = 0; n < 2; ++n) _Pragma("unroll") for (int k = 0; k < 2; ++k) dst[n][k] = *(const LAS bf16x8*)(lds + PG8_SB(b, h) + boff + n * 2048 + k * 1024); } while (0)
; #define PG8_MMA(ai, bj, At, Bt) do { __builtin_amdgcn_s_setprio(1); _Pragma("unroll") for (int m = 0; m < 4; ++m) _Pragma("unroll") for (int n = 0; n < 2; ++n) _Pragma("unroll") for (int k = 0; k < 2; ++k) \
;         acc[ai][bj][m][n] = __builtin_amdgcn_mfma_f32_16x16x32_bf16(Bt[n][k], At[m][k], acc[ai][bj][m][n], 0, 0, 0); __builtin_amdgcn_s_setprio(0); } while (0)
; #define PG8_WAIT_V(n) asm volatile("s_waitcnt vmcnt(" #n ")" ::: "memory")
; #define PG8_WAIT_L(n) asm volatile("s_waitcnt lgkmcnt(" #n ")" ::: "memory")
; #define PG8_BAR __builtin_amdgcn_s_barrier()
; #define PG8_SCHED __builtin_amdgcn_sched_barrier(0)
; template <class Epi, class Sched, bool ALIGN_EPI>
; __device__ __forceinline__ void gemm_phase(LAS unsigned char* lds, const Gemm g, const Sched& S, const Epi& E, int wave_id) {
;     ...
;             PG8_WAIT_V(8); PG8_WAIT_L(0); PG8_BAR; PG8_MMA(1, 0, At, B0); PG8_MMA(1, 1, At, B1); PG8_BAR; PG8_SCHED;
;             PG8_LDB(B0, 1, 0); PG8_LDB(B1, 1, 1); PG8_SCHED; PG8_LDA(At, 1, 0); PG8_STAGE(PG8_SA(0, 1), a2 + hsA, voffA);
;             PG8_WAIT_V(8); PG8_WAIT_L(0); PG8_BAR; PG8_MMA(0, 0, At, B0); PG8_MMA(0, 1, At, B1); PG8_BAR; PG8_SCHED;
	s_setprio 1
	s_waitcnt lgkmcnt(0)
	v_mfma_f32_16x16x32_bf16 v[82:85], v[18:21], v[148:151], v[84:87]
	v_mfma_f32_16x16x32_bf16 v[70:73], v[108:111], v[148:151], v[70:73]
	v_mfma_f32_16x16x32_bf16 v[58:61], v[18:21], v[164:167], v[58:61]
	v_mfma_f32_16x16x32_bf16 v[54:57], v[108:111], v[164:167], v[54:57]
	v_mfma_f32_16x16x32_bf16 v[38:41], v[18:21], v[180:183], v[38:41]
	v_mfma_f32_16x16x32_bf16 v[34:37], v[108:111], v[180:183], v[34:37]
	v_mfma_f32_16x16x32_bf16 v[14:17], v[18:21], v[188:191], v[14:17]
	v_mfma_f32_16x16x32_bf16 v[10:13], v[108:111], v[188:191], v[10:13]
	v_mfma_f32_16x16x32_bf16 v[82:85], v[88:91], v[152:155], v[82:85]
	v_mfma_f32_16x16x32_bf16 v[70:73], v[112:115], v[152:155], v[70:73]
	v_mfma_f32_16x16x32_bf16 v[58:61], v[88:91], v[168:171], v[58:61]
	v_mfma_f32_16x16x32_bf16 v[54:57], v[112:115], v[168:171], v[54:57]
	v_mfma_f32_16x16x32_bf16 v[38:41], v[88:91], v[184:187], v[38:41]
	v_mfma_f32_16x16x32_bf16 v[34:37], v[112:115], v[184:187], v[34:37]
	v_mfma_f32_16x16x32_bf16 v[14:17], v[88:91], v[192:195], v[14:17]
	v_mfma_f32_16x16x32_bf16 v[10:13], v[112:115], v[192:195], v[10:13]
	s_setprio 0
	s_setprio 1
	v_mfma_f32_16x16x32_bf16 v[66:69], v[128:131], v[148:151], v[66:69]
	v_mfma_f32_16x16x32_bf16 v[46:49], v[116:119], v[164:167], v[46:49]
	v_mfma_f32_16x16x32_bf16 v[42:45], v[128:131], v[164:167], v[42:45]
	v_mfma_f32_16x16x32_bf16 v[26:29], v[116:119], v[180:183], v[26:29]
	v_mfma_f32_16x16x32_bf16 v[22:25], v[128:131], v[180:183], v[22:25]
	v_mfma_f32_16x16x32_bf16 v[6:9], v[116:119], v[188:191], v[6:9]
	v_mfma_f32_16x16x32_bf16 v[2:5], v[128:131], v[188:191], v[2:5]
	v_mfma_f32_16x16x32_bf16 v[18:21], v[116:119], v[148:151], v[74:77]
	v_mfma_f32_16x16x32_bf16 v[66:69], v[132:135], v[152:155], v[66:69]
	v_mfma_f32_16x16x32_bf16 v[46:49], v[120:123], v[168:171], v[46:49]
	v_mfma_f32_16x16x32_bf16 v[42:45], v[132:135], v[168:171], v[42:45]
	v_mfma_f32_16x16x32_bf16 v[26:29], v[120:123], v[184:187], v[26:29]
	v_mfma_f32_16x16x32_bf16 v[22:25], v[132:135], v[184:187], v[22:25]
	v_mfma_f32_16x16x32_bf16 v[6:9], v[120:123], v[192:195], v[6:9]
	v_mfma_f32_16x16x32_bf16 v[2:5], v[132:135], v[192:195], v[2:5]
	v_mfma_f32_16x16x32_bf16 v[18:21], v[120:123], v[152:155], v[18:21]
	s_setprio 0
	s_barrier
	s_add_u32 s30, s30, 0x80000
	s_addc_u32 s31, s31, 0
	s_mov_b32 m0, s47
	s_nop 0
	global_load_lds_dwordx4 v224, s[30:31]
	s_mov_b32 m0, s48
	s_nop 0
	global_load_lds_dwordx4 v226, s[30:31]
	v_add_u32_e32 v86, 0x18400, v240
	ds_read_b128 v[74:77], v86
	ds_read_b128 v[88:91], v86 offset:1024
	ds_read_b128 v[108:111], v86 offset:2048
	ds_read_b128 v[112:115], v86 offset:3072
	v_add_u32_e32 v86, 0x1c400, v240
	ds_read_b128 v[116:119], v86
	ds_read_b128 v[120:123], v86 offset:1024
	ds_read_b128 v[128:131], v86 offset:2048
	ds_read_b128 v[132:135], v86 offset:3072
	ds_read_b128 v[148:151], v239 offset:33792
	ds_read_b128 v[152:155], v239 offset:34816
	ds_read_b128 v[164:167], v239 offset:35840
	ds_read_b128 v[180:183], v239 offset:36864
	ds_read_b128 v[184:187], v239 offset:37888
	ds_read_b128 v[188:191], v239 offset:38912
	ds_read_b128 v[192:195], v239 offset:39936
	ds_read_b128 v[196:199], v239 offset:40960
	s_waitcnt vmcnt(8)
	s_waitcnt lgkmcnt(0)
	s_barrier
	s_setprio 1
	s_waitcnt lgkmcnt(0)
	v_mfma_f32_16x16x32_bf16 v[168:171], v[74:77], v[148:151], v[176:179]
	v_mfma_f32_16x16x32_bf16 v[176:179], v[88:91], v[152:155], v[168:171]
	v_mfma_f32_16x16x32_bf16 v[30:33], v[108:111], v[148:151], v[30:33]
	v_mfma_f32_16x16x32_bf16 v[168:171], v[74:77], v[164:167], v[172:175]
	v_mfma_f32_16x16x32_bf16 v[50:53], v[108:111], v[164:167], v[50:53]
	v_mfma_f32_16x16x32_bf16 v[156:159], v[74:77], v[184:187], v[156:159]
	v_mfma_f32_16x16x32_bf16 v[78:81], v[108:111], v[184:187], v[78:81]
	v_mfma_f32_16x16x32_bf16 v[124:127], v[74:77], v[192:195], v[124:127]
	v_mfma_f32_16x16x32_bf16 v[104:107], v[108:111], v[192:195], v[104:107]
	v_mfma_f32_16x16x32_bf16 v[30:33], v[112:115], v[152:155], v[30:33]
	v_mfma_f32_16x16x32_bf16 v[172:175], v[88:91], v[180:183], v[168:171]
	v_mfma_f32_16x16x32_bf16 v[50:53], v[112:115], v[180:183], v[50:53]
	v_mfma_f32_16x16x32_bf16 v[156:159], v[88:91], v[188:191], v[156:159]
	v_mfma_f32_16x16x32_bf16 v[78:81], v[112:115], v[188:191], v[78:81]
	v_mfma_f32_16x16x32_bf16 v[124:127], v[88:91], v[196:199], v[124:127]
	v_mfma_f32_16x16x32_bf16 v[104:107], v[112:115], v[196:199], v[104:107]
	s_setprio 0
	s_setprio 1
	v_mfma_f32_16x16x32_bf16 v[136:139], v[116:119], v[164:167], v[136:139]
	v_mfma_f32_16x16x32_bf16 v[160:163], v[116:119], v[148:151], v[160:163]
	v_mfma_f32_16x16x32_bf16 v[62:65], v[128:131], v[148:151], v[62:65]
	v_mfma_f32_16x16x32_bf16 v[168:171], v[120:123], v[180:183], v[136:139]
	v_mfma_f32_16x16x32_bf16 v[136:139], v[116:119], v[184:187], v[140:143]
	v_mfma_f32_16x16x32_bf16 v[160:163], v[120:123], v[152:155], v[160:163]
	v_mfma_f32_16x16x32_bf16 v[62:65], v[132:135], v[152:155], v[62:65]
	v_mfma_f32_16x16x32_bf16 v[92:95], v[128:131], v[164:167], v[92:95]
	v_mfma_f32_16x16x32_bf16 v[152:155], v[120:123], v[188:191], v[136:139]
	v_mfma_f32_16x16x32_bf16 v[136:139], v[128:131], v[184:187], v[144:147]
	v_mfma_f32_16x16x32_bf16 v[100:103], v[116:119], v[192:195], v[100:103]
	v_mfma_f32_16x16x32_bf16 v[96:99], v[128:131], v[192:195], v[96:99]
	v_mfma_f32_16x16x32_bf16 v[92:95], v[132:135], v[180:183], v[92:95]
	v_mfma_f32_16x16x32_bf16 v[148:151], v[132:135], v[188:191], v[136:139]
	v_mfma_f32_16x16x32_bf16 v[100:103], v[120:123], v[196:199], v[100:103]
	v_mfma_f32_16x16x32_bf16 v[96:99], v[132:135], v[196:199], v[96:99]
	s_setprio 0
	s_barrier
; #define PG8_STAGE(bufoff, gbase, voff) do { _Pragma("unroll") for (int _i = 0; _i < 2; ++_i) \
;         __builtin_amdgcn_global_load_lds((const GAS unsigned*)((const GAS char*)(gbase) + (voff)[_i]), (LAS unsigned*)(lds + (bufoff) + ldsw + _i * 8192), 16, 0, 0); } while (0)
; #define PG8_LDA(dst, b, h) do { _Pragma("unroll") for (int m = 0; m < 4; ++m) _Pragma("unroll") for (int k = 0; k < 2; ++k) dst[m][k] = *(const LAS bf16x8*)(lds + PG8_SA(b, h) + aoff + m * 2048 + k * 1024); } while (0)
; #define PG8_MMA(ai, bj, At, Bt) do { __builtin_amdgcn_s_setprio(1); _Pragma("unroll") for (int m = 0; m < 4; ++m) _Pragma("unroll") for (int n = 0; n < 2; ++n) _Pragma("unroll") for (int k = 0; k < 2; ++k) \
;         acc[ai][bj][m][n] = __builtin_amdgcn_mfma_f32_16x16x32_bf16(Bt[n][k], At[m][k], acc[ai][bj][m][n], 0, 0, 0); __builtin_amdgcn_s_setprio(0); } while (0)
; #define PG8_WAIT_V(n) asm volatile("s_waitcnt vmcnt(" #n ")" ::: "memory")
; #define PG8_WAIT_L(n) asm volatile("s_waitcnt lgkmcnt(" #n ")" ::: "memory")
; #define PG8_BAR __builtin_amdgcn_s_barrier()
; #define PG8_SCHED __builtin_amdgcn_sched_barrier(0)
; template <class Epi, class Sched, bool ALIGN_EPI>
; __device__ __forceinline__ void gemm_phase(LAS unsigned char* lds, const Gemm g, const Sched& S, const Epi& E, int wave_id) {
;     ...
;             PG8_LDA(At, 1, 1); PG8_STAGE(PG8_SB(1, 0), b3, voffB); PG8_STAGE(PG8_SB(1, 1), b3 + hsB, voffB); PG8_STAGE(PG8_SA(1, 0), a3, voffA);
;             PG8_WAIT_V(8); PG8_WAIT_L(0); PG8_BAR; PG8_MMA(1, 0, At, B0); PG8_MMA(1, 1, At, B1); PG8_BAR; PG8_SCHED;
;         }
	s_mov_b32 m0, s52
	v_lshl_add_u64 v[86:87], v[200:201], 0, s[92:93]
	s_add_u32 s28, s28, 0x80080
	global_load_lds_dwordx4 v[86:87], off
	v_lshl_add_u64 v[86:87], v[202:203], 0, s[92:93]
	s_mov_b32 m0, s53
	s_addc_u32 s29, s29, 0
	global_load_lds_dwordx4 v[86:87], off
	v_lshl_add_u64 v[86:87], s[28:29], 0, v[0:1]
	s_mov_b32 m0, s56
	s_nop 0
	global_load_lds_dwordx4 v[86:87], off
	s_mov_b32 m0, s57
	s_nop 0
	global_load_lds_dwordx4 v228, s[28:29]
	v_lshl_add_u64 v[86:87], v[204:205], 0, s[92:93]
	s_mov_b32 m0, s54
	s_nop 0
	global_load_lds_dwordx4 v[86:87], off
	v_lshl_add_u64 v[86:87], v[206:207], 0, s[92:93]
	s_mov_b32 m0, s55
	s_nop 0
	global_load_lds_dwordx4 v[86:87], off
	ds_read_b128 v[136:139], v239 offset:50176
	ds_read_b128 v[140:143], v239 offset:51200
	ds_read_b128 v[144:147], v239 offset:52224
	ds_read_b128 v[164:167], v239 offset:53248
	ds_read_b128 v[180:183], v239 offset:54272
	ds_read_b128 v[184:187], v239 offset:55296
	ds_read_b128 v[188:191], v239 offset:56320
	ds_read_b128 v[192:195], v239 offset:57344
	s_waitcnt vmcnt(8)
	s_waitcnt lgkmcnt(0)
	s_barrier
	s_setprio 1
	s_waitcnt lgkmcnt(0)
	v_mfma_f32_16x16x32_bf16 v[82:85], v[74:77], v[136:139], v[82:85]
	v_mfma_f32_16x16x32_bf16 v[70:73], v[108:111], v[136:139], v[70:73]
	v_mfma_f32_16x16x32_bf16 v[58:61], v[74:77], v[144:147], v[58:61]
	v_mfma_f32_16x16x32_bf16 v[54:57], v[108:111], v[144:147], v[54:57]
	v_mfma_f32_16x16x32_bf16 v[38:41], v[74:77], v[180:183], v[38:41]
	v_mfma_f32_16x16x32_bf16 v[34:37], v[108:111], v[180:183], v[34:37]
	v_mfma_f32_16x16x32_bf16 v[14:17], v[74:77], v[188:191], v[14:17]
	v_mfma_f32_16x16x32_bf16 v[10:13], v[108:111], v[188:191], v[10:13]
	v_mfma_f32_16x16x32_bf16 v[84:87], v[88:91], v[140:143], v[82:85]
	v_mfma_f32_16x16x32_bf16 v[70:73], v[112:115], v[140:143], v[70:73]
	v_mfma_f32_16x16x32_bf16 v[58:61], v[88:91], v[164:167], v[58:61]
	v_mfma_f32_16x16x32_bf16 v[54:57], v[112:115], v[164:167], v[54:57]
	v_mfma_f32_16x16x32_bf16 v[38:41], v[88:91], v[184:187], v[38:41]
	v_mfma_f32_16x16x32_bf16 v[34:37], v[112:115], v[184:187], v[34:37]
	v_mfma_f32_16x16x32_bf16 v[14:17], v[88:91], v[192:195], v[14:17]
	v_mfma_f32_16x16x32_bf16 v[10:13], v[112:115], v[192:195], v[10:13]
	s_setprio 0
	s_setprio 1
	v_mfma_f32_16x16x32_bf16 v[18:21], v[116:119], v[136:139], v[18:21]
	v_mfma_f32_16x16x32_bf16 v[74:77], v[120:123], v[140:143], v[18:21]
	v_mfma_f32_16x16x32_bf16 v[18:21], v[128:131], v[136:139], v[66:69]
	v_mfma_f32_16x16x32_bf16 v[66:69], v[132:135], v[140:143], v[18:21]
	v_mfma_f32_16x16x32_bf16 v[18:21], v[116:119], v[144:147], v[46:49]
	v_mfma_f32_16x16x32_bf16 v[46:49], v[120:123], v[164:167], v[18:21]
	v_mfma_f32_16x16x32_bf16 v[18:21], v[128:131], v[144:147], v[42:45]
	v_mfma_f32_16x16x32_bf16 v[42:45], v[132:135], v[164:167], v[18:21]
	v_mfma_f32_16x16x32_bf16 v[18:21], v[116:119], v[180:183], v[26:29]
	v_mfma_f32_16x16x32_bf16 v[26:29], v[120:123], v[184:187], v[18:21]
	v_mfma_f32_16x16x32_bf16 v[18:21], v[128:131], v[180:183], v[22:25]
	v_mfma_f32_16x16x32_bf16 v[6:9], v[116:119], v[188:191], v[6:9]
	v_mfma_f32_16x16x32_bf16 v[2:5], v[128:131], v[188:191], v[2:5]
	v_mfma_f32_16x16x32_bf16 v[22:25], v[132:135], v[184:187], v[18:21]
	v_mfma_f32_16x16x32_bf16 v[6:9], v[120:123], v[192:195], v[6:9]
	v_mfma_f32_16x16x32_bf16 v[2:5], v[132:135], v[192:195], v[2:5]
	s_setprio 0
	s_barrier
	s_add_i32 s67, s67, 2
	s_add_u32 s33, s33, 0x100
	s_addc_u32 s66, s66, 0
	s_add_u32 s2, s2, 0x100
	s_addc_u32 s3, s3, 0
	s_cmp_gt_u32 s67, 29
	s_cbranch_scc0 .LBB0_2874
	s_and_b64 vcc, exec, s[16:17]
	s_cbranch_vccz .LBB0_2877
	s_barrier

; #define GAS __attribute__((address_space(1)))
; #define PG8_STAGE(bufoff, gbase, voff) do { _Pragma("unroll") for (int _i = 0; _i < 2; ++_i) \
;         __builtin_amdgcn_global_load_lds((const GAS unsigned*)((const GAS char*)(gbase) + (voff)[_i]), (LAS unsigned*)(lds + (bufoff) + ldsw + _i * 8192), 16, 0, 0); } while (0)
; #define PG8_LDA(dst, b, h) do { _Pragma("unroll") for (int m = 0; m < 4; ++m) _Pragma("unroll") for (int k = 0; k < 2; ++k) dst[m][k] = *(const LAS bf16x8*)(lds + PG8_SA(b, h) + aoff + m * 2048 + k * 1024); } while (0)
; #define PG8_LDB(dst, b, h) do { _Pragma("unroll") for (int n = 0; n < 2; ++n) _Pragma("unroll") for (int k = 0; k < 2; ++k) dst[n][k] = *(const LAS bf16x8*)(lds + PG8_SB(b, h) + boff + n * 2048 + k * 1024); } while (0)
; #define PG8_MMA(ai, bj, At, Bt) do { __builtin_amdgcn_s_setprio(1); _Pragma("unroll") for (int m = 0; m < 4; ++m) _Pragma("unroll") for (int n = 0; n < 2; ++n) _Pragma("unroll") for (int k = 0; k < 2; ++k) \
;         acc[ai][bj][m][n] = __builtin_amdgcn_mfma_f32_16x16x32_bf16(Bt[n][k], At[m][k], acc[ai][bj][m][n], 0, 0, 0); __builtin_amdgcn_s_setprio(0); } while (0)
; #define PG8_WAIT_V(n) asm volatile("s_waitcnt vmcnt(" #n ")" ::: "memory")
; #define PG8_WAIT_L(n) asm volatile("s_waitcnt lgkmcnt(" #n ")" ::: "memory")
; template <class Epi, class Sched, bool ALIGN_EPI>
; __device__ __forceinline__ void gemm_phase(LAS unsigned char* lds, const Gemm g, const Sched& S, const Epi& E, int wave_id) {
;     ...
;         for (int t = 0; t < nt; t += 2) {
;             const bool last = (t == nt - 2);
;             const GAS char* a1 = cA + (size_t)(t + 1) * kstep;
;             const GAS char* a2 = last ? nA : cA + (size_t)(t + 2) * kstep; const GAS char* b2 = last ? nB : cB + (size_t)(t + 2) * kstep;
;             const GAS char* a3 = a2 + kstep; const GAS char* b3 = b2 + kstep;
;             PG8_LDB(B0, 0, 0); PG8_LDB(B1, 0, 1); PG8_SCHED; PG8_LDA(At, 0, 0); PG8_STAGE(PG8_SA(1, 1), a1 + hsA, voffA);
;             PG8_WAIT_V(8); PG8_WAIT_L(0); PG8_BAR; PG8_MMA(0, 0, At, B0); PG8_MMA(0, 1, At, B1); PG8_BAR; PG8_SCHED;
;             PG8_LDA(At, 0, 1); PG8_STAGE(PG8_SB(0, 0), b2, voffB); PG8_STAGE(PG8_SB(0, 1), b2 + hsB, voffB); PG8_STAGE(PG8_SA(0, 0), a2, voffA);
;             PG8_WAIT_V(8); PG8_WAIT_L(0); PG8_BAR; PG8_MMA(1, 0, At, B0); PG8_MMA(1, 1, At, B1); PG8_BAR; PG8_SCHED;
.LBB0_3681:
	s_add_u32 s0, s28, 0x100
	s_addc_u32 s1, s29, 0
	s_cmpk_eq_i32 s63, 0x54
	s_cselect_b32 s35, s25, s1
	s_cselect_b32 s34, s24, s0
	s_cselect_b32 s31, s27, s62
	s_cselect_b32 s30, s26, s61
	v_lshl_add_u64 v[204:205], s[28:29], 0, v[190:191]
	s_add_i32 m0, s41, 0xc400
	s_nop 0
	global_load_lds_dwordx4 v[204:205], off
	v_lshl_add_u64 v[204:205], s[28:29], 0, v[188:189]
	s_add_i32 m0, s41, 0xe400
	s_nop 0
	global_load_lds_dwordx4 v[204:205], off
	v_add_u32_e32 v46, 0x10400, v208
	v_add_u32_e32 v62, 0x14400, v208
	ds_read_b128 v[34:37], v46
	ds_read_b128 v[38:41], v46 offset:1024
	ds_read_b128 v[42:45], v46 offset:2048
	ds_read_b128 v[46:49], v46 offset:3072
	ds_read_b128 v[50:53], v62
	ds_read_b128 v[54:57], v62 offset:1024
	ds_read_b128 v[58:61], v62 offset:2048
	ds_read_b128 v[62:65], v62 offset:3072
	ds_read_b128 v[162:165], v207 offset:1024
	ds_read_b128 v[166:169], v207 offset:2048
	ds_read_b128 v[170:173], v207 offset:3072
	ds_read_b128 v[174:177], v207 offset:4096
	ds_read_b128 v[178:181], v207 offset:5120
	ds_read_b128 v[192:195], v207 offset:6144
	ds_read_b128 v[196:199], v207 offset:7168
	ds_read_b128 v[200:203], v207 offset:8192
	s_waitcnt vmcnt(8)
	s_waitcnt lgkmcnt(0)
	s_barrier
	s_setprio 1
	s_waitcnt lgkmcnt(0)
	v_mfma_f32_16x16x32_bf16 v[158:161], v[34:37], v[162:165], v[158:161]
	v_mfma_f32_16x16x32_bf16 v[154:157], v[42:45], v[162:165], v[154:157]
	v_mfma_f32_16x16x32_bf16 v[142:145], v[34:37], v[170:173], v[142:145]
	v_mfma_f32_16x16x32_bf16 v[138:141], v[42:45], v[170:173], v[138:141]
	v_mfma_f32_16x16x32_bf16 v[126:129], v[34:37], v[178:181], v[126:129]
	v_mfma_f32_16x16x32_bf16 v[122:125], v[42:45], v[178:181], v[122:125]
	v_mfma_f32_16x16x32_bf16 v[110:113], v[34:37], v[196:199], v[110:113]
	v_mfma_f32_16x16x32_bf16 v[106:109], v[42:45], v[196:199], v[106:109]
	v_mfma_f32_16x16x32_bf16 v[158:161], v[38:41], v[166:169], v[158:161]
	v_mfma_f32_16x16x32_bf16 v[154:157], v[46:49], v[166:169], v[154:157]
	v_mfma_f32_16x16x32_bf16 v[142:145], v[38:41], v[174:177], v[142:145]
	v_mfma_f32_16x16x32_bf16 v[138:141], v[46:49], v[174:177], v[138:141]
	v_mfma_f32_16x16x32_bf16 v[126:129], v[38:41], v[192:195], v[126:129]
	v_mfma_f32_16x16x32_bf16 v[122:125], v[46:49], v[192:195], v[122:125]
	v_mfma_f32_16x16x32_bf16 v[110:113], v[38:41], v[200:203], v[110:113]
	v_mfma_f32_16x16x32_bf16 v[106:109], v[46:49], v[200:203], v[106:109]
	s_setprio 0
	s_setprio 1
	v_mfma_f32_16x16x32_bf16 v[150:153], v[50:53], v[162:165], v[150:153]
	v_mfma_f32_16x16x32_bf16 v[146:149], v[58:61], v[162:165], v[146:149]
	v_mfma_f32_16x16x32_bf16 v[134:137], v[50:53], v[170:173], v[134:137]
	v_mfma_f32_16x16x32_bf16 v[130:133], v[58:61], v[170:173], v[130:133]
	v_mfma_f32_16x16x32_bf16 v[118:121], v[50:53], v[178:181], v[118:121]
	v_mfma_f32_16x16x32_bf16 v[114:117], v[58:61], v[178:181], v[114:117]
	v_mfma_f32_16x16x32_bf16 v[102:105], v[50:53], v[196:199], v[102:105]
	v_mfma_f32_16x16x32_bf16 v[98:101], v[58:61], v[196:199], v[98:101]
	v_mfma_f32_16x16x32_bf16 v[150:153], v[54:57], v[166:169], v[150:153]
	v_mfma_f32_16x16x32_bf16 v[146:149], v[62:65], v[166:169], v[146:149]
	v_mfma_f32_16x16x32_bf16 v[134:137], v[54:57], v[174:177], v[134:137]
	v_mfma_f32_16x16x32_bf16 v[130:133], v[62:65], v[174:177], v[130:133]
	v_mfma_f32_16x16x32_bf16 v[118:121], v[54:57], v[192:195], v[118:121]
	v_mfma_f32_16x16x32_bf16 v[114:117], v[62:65], v[192:195], v[114:117]
	v_mfma_f32_16x16x32_bf16 v[102:105], v[54:57], v[200:203], v[102:105]
	v_mfma_f32_16x16x32_bf16 v[98:101], v[62:65], v[200:203], v[98:101]
	s_setprio 0
	s_barrier
	s_mov_b32 m0, s42
	v_lshl_add_u64 v[204:205], s[30:31], 0, v[0:1]
	s_add_u32 s28, s30, 0x160000
	global_load_lds_dwordx4 v[204:205], off
	v_lshl_add_u64 v[218:219], s[30:31], 0, v[186:187]
	s_mov_b32 m0, s43
	s_addc_u32 s29, s31, 0
	global_load_lds_dwordx4 v186, s[30:31]
	v_lshl_add_u64 v[210:211], s[28:29], 0, v[0:1]
	s_mov_b32 m0, s44
	v_lshl_add_u64 v[220:221], s[34:35], 0, v[182:183]
	global_load_lds_dwordx4 v[210:211], off
	s_mov_b32 m0, s45
	v_lshl_add_u64 v[224:225], s[34:35], 0, v[184:185]
	global_load_lds_dwordx4 v186, s[28:29]
	s_mov_b32 m0, s46
	s_nop 0
	global_load_lds_dwordx4 v182, s[34:35]
	s_mov_b32 m0, s47
	s_nop 0
	global_load_lds_dwordx4 v184, s[34:35]
	ds_read_b128 v[162:165], v207 offset:17408
	ds_read_b128 v[166:169], v207 offset:18432
	ds_read_b128 v[170:173], v207 offset:19456
	ds_read_b128 v[174:177], v207 offset:20480
	ds_read_b128 v[178:181], v207 offset:21504
	ds_read_b128 v[192:195], v207 offset:22528
	ds_read_b128 v[196:199], v207 offset:23552
	ds_read_b128 v[200:203], v207 offset:24576
	s_waitcnt vmcnt(8)
	s_waitcnt lgkmcnt(0)
	s_barrier
; #define PG8_STAGE(bufoff, gbase, voff) do { _Pragma("unroll") for (int _i = 0; _i < 2; ++_i) \
;         __builtin_amdgcn_global_load_lds((const GAS unsigned*)((const GAS char*)(gbase) + (voff)[_i]), (LAS unsigned*)(lds + (bufoff) + ldsw + _i * 8192), 16, 0, 0); } while (0)
; #define PG8_LDA(dst, b, h) do { _Pragma("unroll") for (int m = 0; m < 4; ++m) _Pragma("unroll") for (int k = 0; k < 2; ++k) dst[m][k] = *(const LAS bf16x8*)(lds + PG8_SA(b, h) + aoff + m * 2048 + k * 1024); } while (0)
; #define PG8_LDB(dst, b, h) do { _Pragma("unroll") for (int n = 0; n < 2; ++n) _Pragma("unroll") for (int k = 0; k < 2; ++k) dst[n][k] = *(const LAS bf16x8*)(lds + PG8_SB(b, h) + boff + n * 2048 + k * 1024); } while (0)
; #define PG8_MMA(ai, bj, At, Bt) do { __builtin_amdgcn_s_setprio(1); _Pragma("unroll") for (int m = 0; m < 4; ++m) _Pragma("unroll") for (int n = 0; n < 2; ++n) _Pragma("unroll") for (int k = 0; k < 2; ++k) \
;         acc[ai][bj][m][n] = __builtin_amdgcn_mfma_f32_16x16x32_bf16(Bt[n][k], At[m][k], acc[ai][bj][m][n], 0, 0, 0); __builtin_amdgcn_s_setprio(0); } while (0)
; #define PG8_WAIT_V(n) asm volatile("s_waitcnt vmcnt(" #n ")" ::: "memory")
; #define PG8_WAIT_L(n) asm volatile("s_waitcnt lgkmcnt(" #n ")" ::: "memory")
; #define PG8_BAR __builtin_amdgcn_s_barrier()
; #define PG8_SCHED __builtin_amdgcn_sched_barrier(0)
; template <class Epi, class Sched, bool ALIGN_EPI>
; __device__ __forceinline__ void gemm_phase(LAS unsigned char* lds, const Gemm g, const Sched& S, const Epi& E, int wave_id) {
;     ...
;             PG8_WAIT_V(8); PG8_WAIT_L(0); PG8_BAR; PG8_MMA(1, 0, At, B0); PG8_MMA(1, 1, At, B1); PG8_BAR; PG8_SCHED;
;             PG8_LDB(B0, 1, 0); PG8_LDB(B1, 1, 1); PG8_SCHED; PG8_LDA(At, 1, 0); PG8_STAGE(PG8_SA(0, 1), a2 + hsA, voffA);
;             PG8_WAIT_V(8); PG8_WAIT_L(0); PG8_BAR; PG8_MMA(0, 0, At, B0); PG8_MMA(0, 1, At, B1); PG8_BAR; PG8_SCHED;
	s_setprio 1
	s_waitcnt lgkmcnt(0)
	v_mfma_f32_16x16x32_bf16 v[94:97], v[34:37], v[162:165], v[94:97]
	v_mfma_f32_16x16x32_bf16 v[90:93], v[42:45], v[162:165], v[90:93]
	v_mfma_f32_16x16x32_bf16 v[78:81], v[34:37], v[170:173], v[78:81]
	v_mfma_f32_16x16x32_bf16 v[74:77], v[42:45], v[170:173], v[74:77]
	v_mfma_f32_16x16x32_bf16 v[30:33], v[34:37], v[178:181], v[30:33]
	v_mfma_f32_16x16x32_bf16 v[26:29], v[42:45], v[178:181], v[26:29]
	v_mfma_f32_16x16x32_bf16 v[14:17], v[34:37], v[196:199], v[14:17]
	v_mfma_f32_16x16x32_bf16 v[10:13], v[42:45], v[196:199], v[10:13]
	v_mfma_f32_16x16x32_bf16 v[94:97], v[38:41], v[166:169], v[94:97]
	v_mfma_f32_16x16x32_bf16 v[90:93], v[46:49], v[166:169], v[90:93]
	v_mfma_f32_16x16x32_bf16 v[78:81], v[38:41], v[174:177], v[78:81]
	v_mfma_f32_16x16x32_bf16 v[74:77], v[46:49], v[174:177], v[74:77]
	v_mfma_f32_16x16x32_bf16 v[30:33], v[38:41], v[192:195], v[30:33]
	v_mfma_f32_16x16x32_bf16 v[26:29], v[46:49], v[192:195], v[26:29]
	v_mfma_f32_16x16x32_bf16 v[14:17], v[38:41], v[200:203], v[14:17]
	v_mfma_f32_16x16x32_bf16 v[10:13], v[46:49], v[200:203], v[10:13]
	s_setprio 0
	s_setprio 1
	v_mfma_f32_16x16x32_bf16 v[22:25], v[50:53], v[178:181], v[22:25]
	v_mfma_f32_16x16x32_bf16 v[18:21], v[58:61], v[178:181], v[18:21]
	v_mfma_f32_16x16x32_bf16 v[6:9], v[50:53], v[196:199], v[6:9]
	v_mfma_f32_16x16x32_bf16 v[2:5], v[58:61], v[196:199], v[2:5]
	v_mfma_f32_16x16x32_bf16 v[34:37], v[50:53], v[162:165], v[86:89]
	v_mfma_f32_16x16x32_bf16 v[38:41], v[58:61], v[162:165], v[82:85]
	v_mfma_f32_16x16x32_bf16 v[42:45], v[50:53], v[170:173], v[70:73]
	v_mfma_f32_16x16x32_bf16 v[46:49], v[58:61], v[170:173], v[66:69]
	v_mfma_f32_16x16x32_bf16 v[22:25], v[54:57], v[192:195], v[22:25]
	v_mfma_f32_16x16x32_bf16 v[18:21], v[62:65], v[192:195], v[18:21]
	v_mfma_f32_16x16x32_bf16 v[6:9], v[54:57], v[200:203], v[6:9]
	v_mfma_f32_16x16x32_bf16 v[2:5], v[62:65], v[200:203], v[2:5]
	v_mfma_f32_16x16x32_bf16 v[34:37], v[54:57], v[166:169], v[34:37]
	v_mfma_f32_16x16x32_bf16 v[38:41], v[62:65], v[166:169], v[38:41]
	v_mfma_f32_16x16x32_bf16 v[42:45], v[54:57], v[174:177], v[42:45]
	v_mfma_f32_16x16x32_bf16 v[46:49], v[62:65], v[174:177], v[46:49]
	s_setprio 0
	s_barrier
	s_add_u32 s28, s34, 0x160000
	s_addc_u32 s29, s35, 0
	s_mov_b32 m0, s48
	s_nop 0
	global_load_lds_dwordx4 v182, s[28:29]
	v_lshl_add_u64 v[210:211], s[28:29], 0, v[184:185]
	s_mov_b32 m0, s49
	s_nop 0
	global_load_lds_dwordx4 v184, s[28:29]
	v_add_u32_e32 v62, 0x18400, v208
	v_add_u32_e32 v66, 0x1c400, v208
	ds_read_b128 v[50:53], v62
	ds_read_b128 v[54:57], v62 offset:1024
	ds_read_b128 v[58:61], v62 offset:2048
	ds_read_b128 v[62:65], v62 offset:3072
	ds_read_b128 v[162:165], v66
	ds_read_b128 v[166:169], v66 offset:1024
	ds_read_b128 v[170:173], v66 offset:2048
	ds_read_b128 v[174:177], v66 offset:3072
	ds_read_b128 v[66:69], v207 offset:33792
	ds_read_b128 v[70:73], v207 offset:34816
	ds_read_b128 v[82:85], v207 offset:35840
	ds_read_b128 v[86:89], v207 offset:36864
	ds_read_b128 v[178:181], v207 offset:37888
	ds_read_b128 v[192:195], v207 offset:38912
	ds_read_b128 v[196:199], v207 offset:39936
	ds_read_b128 v[200:203], v207 offset:40960
	s_waitcnt vmcnt(8)
	s_waitcnt lgkmcnt(0)
	s_barrier
	s_setprio 1
	s_waitcnt lgkmcnt(0)
	v_mfma_f32_16x16x32_bf16 v[158:161], v[50:53], v[66:69], v[158:161]
	v_mfma_f32_16x16x32_bf16 v[154:157], v[58:61], v[66:69], v[154:157]
	v_mfma_f32_16x16x32_bf16 v[142:145], v[50:53], v[82:85], v[142:145]
	v_mfma_f32_16x16x32_bf16 v[138:141], v[58:61], v[82:85], v[138:141]
	v_mfma_f32_16x16x32_bf16 v[126:129], v[50:53], v[178:181], v[126:129]
	v_mfma_f32_16x16x32_bf16 v[122:125], v[58:61], v[178:181], v[122:125]
	v_mfma_f32_16x16x32_bf16 v[110:113], v[50:53], v[196:199], v[110:113]
	v_mfma_f32_16x16x32_bf16 v[106:109], v[58:61], v[196:199], v[106:109]
	v_mfma_f32_16x16x32_bf16 v[158:161], v[54:57], v[70:73], v[158:161]
	v_mfma_f32_16x16x32_bf16 v[154:157], v[62:65], v[70:73], v[154:157]
	v_mfma_f32_16x16x32_bf16 v[142:145], v[54:57], v[86:89], v[142:145]
	v_mfma_f32_16x16x32_bf16 v[138:141], v[62:65], v[86:89], v[138:141]
	v_mfma_f32_16x16x32_bf16 v[126:129], v[54:57], v[192:195], v[126:129]
	v_mfma_f32_16x16x32_bf16 v[122:125], v[62:65], v[192:195], v[122:125]
	v_mfma_f32_16x16x32_bf16 v[110:113], v[54:57], v[200:203], v[110:113]
	v_mfma_f32_16x16x32_bf16 v[106:109], v[62:65], v[200:203], v[106:109]
	s_setprio 0
	s_setprio 1
	v_mfma_f32_16x16x32_bf16 v[150:153], v[162:165], v[66:69], v[150:153]
	v_mfma_f32_16x16x32_bf16 v[66:69], v[170:173], v[66:69], v[146:149]
	v_mfma_f32_16x16x32_bf16 v[146:149], v[174:177], v[70:73], v[66:69]
	v_mfma_f32_16x16x32_bf16 v[66:69], v[162:165], v[82:85], v[134:137]
	v_mfma_f32_16x16x32_bf16 v[134:137], v[166:169], v[86:89], v[66:69]
	v_mfma_f32_16x16x32_bf16 v[66:69], v[170:173], v[82:85], v[130:133]
	v_mfma_f32_16x16x32_bf16 v[130:133], v[174:177], v[86:89], v[66:69]
	v_mfma_f32_16x16x32_bf16 v[66:69], v[162:165], v[178:181], v[118:121]
	v_mfma_f32_16x16x32_bf16 v[118:121], v[166:169], v[192:195], v[66:69]
	v_mfma_f32_16x16x32_bf16 v[66:69], v[170:173], v[178:181], v[114:117]
	v_mfma_f32_16x16x32_bf16 v[114:117], v[174:177], v[192:195], v[66:69]
	v_mfma_f32_16x16x32_bf16 v[66:69], v[162:165], v[196:199], v[102:105]
	v_mfma_f32_16x16x32_bf16 v[102:105], v[166:169], v[200:203], v[66:69]
	v_mfma_f32_16x16x32_bf16 v[66:69], v[170:173], v[196:199], v[98:101]
	v_mfma_f32_16x16x32_bf16 v[150:153], v[166:169], v[70:73], v[150:153]
	v_mfma_f32_16x16x32_bf16 v[98:101], v[174:177], v[200:203], v[66:69]
	s_setprio 0
	s_barrier
; #define PG8_STAGE(bufoff, gbase, voff) do { _Pragma("unroll") for (int _i = 0; _i < 2; ++_i) \
;         __builtin_amdgcn_global_load_lds((const GAS unsigned*)((const GAS char*)(gbase) + (voff)[_i]), (LAS unsigned*)(lds + (bufoff) + ldsw + _i * 8192), 16, 0, 0); } while (0)
; #define PG8_LDA(dst, b, h) do { _Pragma("unroll") for (int m = 0; m < 4; ++m) _Pragma("unroll") for (int k = 0; k < 2; ++k) dst[m][k] = *(const LAS bf16x8*)(lds + PG8_SA(b, h) + aoff + m * 2048 + k * 1024); } while (0)
; #define PG8_MMA(ai, bj, At, Bt) do { __builtin_amdgcn_s_setprio(1); _Pragma("unroll") for (int m = 0; m < 4; ++m) _Pragma("unroll") for (int n = 0; n < 2; ++n) _Pragma("unroll") for (int k = 0; k < 2; ++k) \
;         acc[ai][bj][m][n] = __builtin_amdgcn_mfma_f32_16x16x32_bf16(Bt[n][k], At[m][k], acc[ai][bj][m][n], 0, 0, 0); __builtin_amdgcn_s_setprio(0); } while (0)
; #define PG8_WAIT_V(n) asm volatile("s_waitcnt vmcnt(" #n ")" ::: "memory")
; #define PG8_WAIT_L(n) asm volatile("s_waitcnt lgkmcnt(" #n ")" ::: "memory")
; #define PG8_BAR __builtin_amdgcn_s_barrier()
; #define PG8_SCHED __builtin_amdgcn_sched_barrier(0)
; template <class Epi, class Sched, bool ALIGN_EPI>
; __device__ __forceinline__ void gemm_phase(LAS unsigned char* lds, const Gemm g, const Sched& S, const Epi& E, int wave_id) {
;     ...
;             PG8_LDA(At, 1, 1); PG8_STAGE(PG8_SB(1, 0), b3, voffB); PG8_STAGE(PG8_SB(1, 1), b3 + hsB, voffB); PG8_STAGE(PG8_SA(1, 0), a3, voffA);
;             PG8_WAIT_V(8); PG8_WAIT_L(0); PG8_BAR; PG8_MMA(1, 0, At, B0); PG8_MMA(1, 1, At, B1); PG8_BAR; PG8_SCHED;
;         }
	s_mov_b32 m0, s52
	v_lshl_add_u64 v[82:83], v[204:205], 0, s[92:93]
	s_add_u32 s28, s30, 0x160080
	s_nop 0
	global_load_lds_dwordx4 v[82:83], off
	v_lshl_add_u64 v[82:83], v[218:219], 0, s[92:93]
	s_mov_b32 m0, s53
	s_addc_u32 s29, s31, 0
	global_load_lds_dwordx4 v[82:83], off
	v_lshl_add_u64 v[82:83], s[28:29], 0, v[0:1]
	s_mov_b32 m0, s56
	s_nop 0
	global_load_lds_dwordx4 v[82:83], off
	s_mov_b32 m0, s57
	s_nop 0
	global_load_lds_dwordx4 v186, s[28:29]
	v_lshl_add_u64 v[82:83], v[220:221], 0, s[92:93]
	s_mov_b32 m0, s54
	s_nop 0
	global_load_lds_dwordx4 v[82:83], off
	v_lshl_add_u64 v[82:83], v[224:225], 0, s[92:93]
	s_mov_b32 m0, s55
	s_nop 0
	global_load_lds_dwordx4 v[82:83], off
	ds_read_b128 v[66:69], v207 offset:50176
	ds_read_b128 v[70:73], v207 offset:51200
	ds_read_b128 v[178:181], v207 offset:52224
	ds_read_b128 v[192:195], v207 offset:53248
	ds_read_b128 v[196:199], v207 offset:54272
	ds_read_b128 v[200:203], v207 offset:55296
	ds_read_b128 v[210:213], v207 offset:56320
	ds_read_b128 v[214:217], v207 offset:57344
	s_waitcnt vmcnt(8)
	s_waitcnt lgkmcnt(0)
	s_barrier
	s_setprio 1
	s_waitcnt lgkmcnt(0)
	v_mfma_f32_16x16x32_bf16 v[82:85], v[50:53], v[66:69], v[94:97]
	v_mfma_f32_16x16x32_bf16 v[94:97], v[54:57], v[70:73], v[82:85]
	v_mfma_f32_16x16x32_bf16 v[82:85], v[58:61], v[66:69], v[90:93]
	v_mfma_f32_16x16x32_bf16 v[78:81], v[50:53], v[178:181], v[78:81]
	v_mfma_f32_16x16x32_bf16 v[74:77], v[58:61], v[178:181], v[74:77]
	v_mfma_f32_16x16x32_bf16 v[30:33], v[50:53], v[196:199], v[30:33]
	v_mfma_f32_16x16x32_bf16 v[26:29], v[58:61], v[196:199], v[26:29]
	v_mfma_f32_16x16x32_bf16 v[14:17], v[50:53], v[210:213], v[14:17]
	v_mfma_f32_16x16x32_bf16 v[10:13], v[58:61], v[210:213], v[10:13]
	v_mfma_f32_16x16x32_bf16 v[90:93], v[62:65], v[70:73], v[82:85]
	v_mfma_f32_16x16x32_bf16 v[78:81], v[54:57], v[192:195], v[78:81]
	v_mfma_f32_16x16x32_bf16 v[74:77], v[62:65], v[192:195], v[74:77]
	v_mfma_f32_16x16x32_bf16 v[30:33], v[54:57], v[200:203], v[30:33]
	v_mfma_f32_16x16x32_bf16 v[26:29], v[62:65], v[200:203], v[26:29]
	v_mfma_f32_16x16x32_bf16 v[14:17], v[54:57], v[214:217], v[14:17]
	v_mfma_f32_16x16x32_bf16 v[10:13], v[62:65], v[214:217], v[10:13]
	s_setprio 0
	s_setprio 1
	v_mfma_f32_16x16x32_bf16 v[34:37], v[162:165], v[66:69], v[34:37]
	v_mfma_f32_16x16x32_bf16 v[86:89], v[166:169], v[70:73], v[34:37]
	v_mfma_f32_16x16x32_bf16 v[34:37], v[170:173], v[66:69], v[38:41]
	v_mfma_f32_16x16x32_bf16 v[82:85], v[174:177], v[70:73], v[34:37]
	v_mfma_f32_16x16x32_bf16 v[34:37], v[162:165], v[178:181], v[42:45]
	v_mfma_f32_16x16x32_bf16 v[70:73], v[166:169], v[192:195], v[34:37]
	v_mfma_f32_16x16x32_bf16 v[34:37], v[170:173], v[178:181], v[46:49]
	v_mfma_f32_16x16x32_bf16 v[22:25], v[162:165], v[196:199], v[22:25]
	v_mfma_f32_16x16x32_bf16 v[18:21], v[170:173], v[196:199], v[18:21]
	v_mfma_f32_16x16x32_bf16 v[6:9], v[162:165], v[210:213], v[6:9]
	v_mfma_f32_16x16x32_bf16 v[2:5], v[170:173], v[210:213], v[2:5]
	v_mfma_f32_16x16x32_bf16 v[66:69], v[174:177], v[192:195], v[34:37]
	v_mfma_f32_16x16x32_bf16 v[22:25], v[166:169], v[200:203], v[22:25]
	v_mfma_f32_16x16x32_bf16 v[18:21], v[174:177], v[200:203], v[18:21]
	v_mfma_f32_16x16x32_bf16 v[6:9], v[166:169], v[214:217], v[6:9]
	v_mfma_f32_16x16x32_bf16 v[2:5], v[174:177], v[214:217], v[2:5]
	s_setprio 0
	s_barrier
	s_add_i32 s63, s63, 2
	s_add_u32 s61, s61, 0x100
	s_addc_u32 s62, s62, 0
	s_cmpk_gt_u32 s63, 0x55
	s_mov_b64 s[28:29], s[0:1]
	s_cbranch_scc0 .LBB0_3681
	s_and_b64 vcc, exec, s[22:23]
	s_cbranch_vccz .LBB0_3684
	s_barrier
